# S5 scan task hand-scheduled (software-pipelined, 16x16x16 bf16 MFMA for B*u), weight conversion re-homed from scan passes and out-proj into gate/up idle workgroups
# speedup vs baseline: 1.0148x; 1.0148x over previous
.LBB0_98:
	s_waitcnt vmcnt(0)
	v_readlane_b32 s72, v247, 5
	v_readlane_b32 s68, v247, 7
	v_readlane_b32 s79, v247, 4
	v_readlane_b32 s73, v247, 6
	v_readlane_b32 s69, v247, 8
	s_mov_b64 s[70:71], 0x20000000
	s_mov_b32 s74, s87
	s_barrier
	s_cmpk_lt_i32 s2, 0x40
	s_cbranch_scc1 .LBB0_99
	s_sub_i32 s4, s2, 0x40
	s_lshl_b32 s4, s4, 3
	s_add_i32 s4, s4, s43
	s_movk_i32 s1, 0x600
	s_and_b64 s[10:11], s[62:63], exec
	s_mov_b32 s25, 17920
	s_mov_b32 s39, 32208
	s_cbranch_scc0 .Lconv_entry
	s_mov_b32 s25, 41472
	s_mov_b32 s39, 47104
	s_branch .Lconv_entry

.LBB0_196:
	s_cmpk_lt_i32 s2, 0x80
	s_cbranch_scc1 .LBB0_219
	s_sub_i32 s4, s2, 0x80
	s_lshl_b32 s4, s4, 3
	s_add_i32 s4, s4, s43
	s_movk_i32 s1, 0x400
	s_and_b64 s[6:7], s[62:63], exec
	s_mov_b32 s25, 10656
	s_mov_b32 s39, 17920
	s_cbranch_scc0 .Lconv_entry
	s_mov_b32 s25, 32208
	s_mov_b32 s39, 41472
.Lconv_entry:
	s_add_i32 s25, s25, s4
	s_cmp_ge_i32 s25, s39
	s_cbranch_scc1 .LBB0_219
	s_lshl_b32 s3, s43, 14
	s_add_i32 s5, s3, 0
	s_add_u32 s3, s56, 0x9c00000
	s_addc_u32 s8, s57, 0
	s_add_u32 s9, s56, 0x4400000
	s_waitcnt lgkmcnt(0)
	s_addc_u32 s10, s57, 0
	v_lshrrev_b32_e32 v1, 5, v168
	v_and_b32_e32 v0, 31, v241
	s_add_u32 s11, s56, 0x3400000
	v_lshlrev_b32_e32 v2, 2, v0
	v_mul_u32_u24_e32 v3, 0x84, v1
	s_addc_u32 s12, s57, 0
	v_add3_u32 v3, s5, v2, v3
	v_lshlrev_b32_e32 v2, 3, v168
	s_add_u32 s13, s56, 0x3000000
	v_lshrrev_b32_e32 v5, 3, v168
	v_and_b32_e32 v2, 56, v2
	s_addc_u32 s15, s57, 0
	v_mul_u32_u24_e32 v6, 0x84, v2
	v_lshlrev_b32_e32 v7, 2, v5
	s_add_u32 s18, s56, 0x1000000
	v_add3_u32 v10, s5, v6, v7
	s_addc_u32 s19, s57, 0
	v_or_b32_e32 v11, 8, v5
	v_or_b32_e32 v12, 16, v5
	v_or_b32_e32 v13, 24, v5
	s_lshl_b32 s36, s25, 1
	s_lshl_b32 s38, s25, 5
	s_branch .LBB0_203
.LBB0_202:
	s_add_i32 s25, s25, s1
	s_lshl_b32 s36, s25, 1
	s_lshl_b32 s38, s25, 5
	s_cmp_ge_i32 s25, s39
	s_cbranch_scc1 .LBB0_219

.LBB0_219:
	s_cmp_eq_u32 s35, 7
	s_cbranch_scc0 .Lconv_ret_op
	s_mov_b64 s[8:9], 0
	s_branch .LBB0_99

.LBB0_247:
	s_bfe_u32 s1, s38, 0x60001
	s_or_b32 s18, s1, s64
	v_lshl_or_b32 v0, s18, 6, v12
	v_lshlrev_b32_e32 v1, 4, v0
	global_load_dwordx4 v[18:21], v1, s[72:73]
	global_load_dwordx4 v[22:25], v1, s[72:73] offset:256
	global_load_dwordx4 v[26:29], v1, s[72:73] offset:512
	global_load_dwordx4 v[30:33], v1, s[72:73] offset:768
	s_load_dwordx4 s[44:47], s[58:59], 0x60
	s_load_dwordx4 s[8:11], s[58:59], 0x70
	v_lshlrev_b32_e32 v2, 6, v0
	v_lshl_add_u32 v2, v13, 4, v2
	v_lshl_or_b32 v3, s18, 4, v12
	v_lshlrev_b32_e32 v3, 8, v3
	v_lshl_add_u32 v3, v13, 4, v3
	s_waitcnt lgkmcnt(0)
	global_load_dwordx4 v[50:53], v2, s[44:45]
	global_load_dwordx4 v[54:57], v2, s[44:45] offset:1024
	global_load_dwordx4 v[58:61], v2, s[44:45] offset:2048
	global_load_dwordx4 v[62:65], v2, s[44:45] offset:3072
	global_load_dwordx4 v[66:69], v2, s[46:47]
	global_load_dwordx4 v[70:73], v2, s[46:47] offset:1024
	global_load_dwordx4 v[74:77], v2, s[46:47] offset:2048
	global_load_dwordx4 v[78:81], v2, s[46:47] offset:3072
	global_load_dwordx4 v[34:37], v3, s[8:9]
	global_load_dwordx4 v[38:41], v3, s[8:9] offset:64
	global_load_dwordx4 v[42:45], v3, s[8:9] offset:128
	global_load_dwordx4 v[46:49], v3, s[8:9] offset:192
	global_load_dwordx4 v[188:191], v3, s[10:11]
	global_load_dwordx4 v[192:195], v3, s[10:11] offset:64
	global_load_dwordx4 v[196:199], v3, s[10:11] offset:128
	global_load_dwordx4 v[200:203], v3, s[10:11] offset:192
	s_and_b64 s[82:83], s[84:85], exec
	s_cselect_b32 s13, 10, 8
	s_cselect_b32 s0, 0x1000, 0
	s_lshl_b32 s12, 1, s13
	s_lshl_b32 s10, s3, s13
	s_add_i32 s10, s10, s0
	s_lshl_b32 s20, s25, 8
	s_sub_i32 s0, s12, 1
	s_sub_i32 s0, s0, s20
	s_mov_b32 s86, 0x8000
	s_mov_b32 s87, 0
	s_mov_b32 s88, 0x4000
	s_mov_b32 s89, 0
	s_mov_b32 s15, 1
	s_cmp_eq_u32 s39, 0
	s_cselect_b32 s0, s20, s0
	s_cbranch_scc1 .Lsc_fwd
	s_mov_b32 s86, 0xffff8000
	s_mov_b32 s87, -1
	s_mov_b32 s88, 0xffffc000
	s_mov_b32 s89, -1
	s_mov_b32 s15, -1
.Lsc_fwd:
	s_add_i32 s10, s10, s0
	v_lshrrev_b32_e32 v5, 2, v12
	v_and_b32_e32 v6, 3, v12
	v_lshlrev_b32_e32 v5, s13, v5
	v_mad_i32_i24 v6, v6, s15, v5
	v_add_u32_e32 v6, s10, v6
	s_lshl_b32 s0, s1, 5
	v_lshlrev_b32_e32 v7, 13, v6
	v_lshl_add_u32 v8, v13, 3, v7
	v_add_u32_e32 v8, s0, v8
	v_mov_b32_e32 v9, 0
	v_lshl_add_u64 v[130:131], s[70:71], 0, v[8:9]
	s_lshl_b32 s0, s1, 6
	v_lshlrev_b32_e32 v10, 12, v6
	v_lshl_add_u32 v10, v13, 4, v10
	v_add_u32_e32 v10, s0, v10
	v_mov_b32_e32 v11, 0
	v_lshl_add_u64 v[132:133], s[78:79], 0, v[10:11]
	global_load_dwordx2 v[82:83], v[130:131], off
	v_lshl_add_u64 v[130:131], v[130:131], 0, s[86:87]
	global_load_dwordx2 v[84:85], v[130:131], off
	v_lshl_add_u64 v[130:131], v[130:131], 0, s[86:87]
	global_load_dwordx2 v[86:87], v[130:131], off
	v_lshl_add_u64 v[130:131], v[130:131], 0, s[86:87]
	global_load_dwordx2 v[88:89], v[130:131], off
	v_lshl_add_u64 v[130:131], v[130:131], 0, s[86:87]
	global_load_dwordx2 v[90:91], v[130:131], off
	v_lshl_add_u64 v[130:131], v[130:131], 0, s[86:87]
	global_load_dwordx2 v[92:93], v[130:131], off
	v_lshl_add_u64 v[130:131], v[130:131], 0, s[86:87]
	global_load_dwordx2 v[94:95], v[130:131], off
	v_lshl_add_u64 v[130:131], v[130:131], 0, s[86:87]
	global_load_dwordx2 v[96:97], v[130:131], off
	v_lshl_add_u64 v[130:131], v[130:131], 0, s[86:87]
	global_load_dwordx2 v[98:99], v[130:131], off
	v_lshl_add_u64 v[130:131], v[130:131], 0, s[86:87]
	global_load_dwordx2 v[100:101], v[130:131], off
	v_lshl_add_u64 v[130:131], v[130:131], 0, s[86:87]
	global_load_dwordx2 v[102:103], v[130:131], off
	v_lshl_add_u64 v[130:131], v[130:131], 0, s[86:87]
	global_load_dwordx2 v[104:105], v[130:131], off
	v_lshl_add_u64 v[130:131], v[130:131], 0, s[86:87]
	s_mul_i32 s0, s43, 0x1100
	v_mul_u32_u24_e32 v134, 0x440, v13
	v_lshl_add_u32 v134, v12, 2, v134
	v_add_u32_e32 v134, s0, v134
	v_mul_u32_u24_e32 v135, 0x110, v12
	v_lshl_add_u32 v135, v13, 4, v135
	v_add_u32_e32 v135, s0, v135
	v_mov_b32_e32 v212, 0
	v_mov_b32_e32 v213, 0
	v_mov_b32_e32 v214, 0
	v_mov_b32_e32 v215, 0
	v_mov_b32_e32 v224, 0
	v_mov_b32_e32 v228, 0
	v_mov_b32_e32 v225, 0
	v_mov_b32_e32 v229, 0
	v_mov_b32_e32 v226, 0
	v_mov_b32_e32 v230, 0
	v_mov_b32_e32 v227, 0
	v_mov_b32_e32 v231, 0
	s_and_b64 s[82:83], s[84:85], exec
	s_cbranch_scc0 .Lsc_init_done
	s_cmp_lg_u32 s25, 0
	s_cbranch_scc1 .Lsc_init_k
	s_load_dwordx2 s[82:83], s[58:59], 0x10
	s_lshr_b32 s0, s18, 7
	s_lshl_b32 s0, s0, 16
	s_lshl_b32 s10, s39, 15
	s_add_i32 s0, s0, s10
	s_lshl_b32 s10, s1, 8
	s_add_i32 s0, s0, s10
	s_lshl_b32 s10, s3, 17
	s_add_i32 s0, s0, s10
	v_lshlrev_b32_e32 v5, 17, v13
	v_lshl_add_u32 v5, v12, 2, v5
	v_add_u32_e32 v5, s0, v5
	v_add_u32_e32 v6, 0x4000, v5
	s_waitcnt lgkmcnt(0)
	global_load_dword v224, v5, s[82:83]
	global_load_dword v228, v6, s[82:83]
	global_load_dword v225, v5, s[82:83] offset:64
	global_load_dword v229, v6, s[82:83] offset:64
	global_load_dword v226, v5, s[82:83] offset:128
	global_load_dword v230, v6, s[82:83] offset:128
	global_load_dword v227, v5, s[82:83] offset:192
	global_load_dword v231, v6, s[82:83] offset:192
	s_branch .Lsc_init_done
.Lsc_init_k:
	s_and_b64 s[82:83], s[66:67], exec
	s_cbranch_scc0 .Lsc_init_done
	s_lshl_b32 s0, s39, 15
	s_lshl_b32 s10, s1, 9
	s_add_i32 s0, s0, s10
	s_mul_i32 s10, s3, 0x30000
	s_add_i32 s0, s0, s10
	v_mul_u32_u24_e32 v150, 0x30000, v13
	v_lshl_add_u32 v150, v12, 2, v150
	v_add_u32_e32 v150, s0, v150
	global_load_dword v0, v150, s[74:75]
	global_load_dword v5, v150, s[74:75] offset:256
	global_load_dword v1, v150, s[74:75] offset:64
	global_load_dword v6, v150, s[74:75] offset:320
	global_load_dword v2, v150, s[74:75] offset:128
	global_load_dword v7, v150, s[74:75] offset:384
	global_load_dword v3, v150, s[74:75] offset:192
	global_load_dword v8, v150, s[74:75] offset:448
	s_cmp_lt_u32 s25, 2
	s_cbranch_scc1 .Lsc_e_done
	v_add_u32_e32 v171, 0x10000, v150
	global_load_dword v9, v171, s[74:75]
	global_load_dword v156, v171, s[74:75] offset:256
	global_load_dword v10, v171, s[74:75] offset:64
	global_load_dword v157, v171, s[74:75] offset:320
	global_load_dword v11, v171, s[74:75] offset:128
	global_load_dword v158, v171, s[74:75] offset:384
	global_load_dword v149, v171, s[74:75] offset:192
	global_load_dword v159, v171, s[74:75] offset:448
	s_cmp_lt_u32 s25, 3
	s_cbranch_scc1 .Lsc_e_done
	v_add_u32_e32 v171, 0x20000, v150
	global_load_dword v106, v171, s[74:75]
	global_load_dword v110, v171, s[74:75] offset:256
	global_load_dword v107, v171, s[74:75] offset:64
	global_load_dword v111, v171, s[74:75] offset:320
	global_load_dword v108, v171, s[74:75] offset:128
	global_load_dword v112, v171, s[74:75] offset:384
	global_load_dword v109, v171, s[74:75] offset:192
	global_load_dword v113, v171, s[74:75] offset:448
.Lsc_e_done:
	s_waitcnt vmcnt(0)
	v_mov_b32_e32 v204, v18
	v_mov_b32_e32 v208, v19
	v_mov_b32_e32 v205, v22
	v_mov_b32_e32 v209, v23
	v_mov_b32_e32 v206, v26
	v_mov_b32_e32 v210, v27
	v_mov_b32_e32 v207, v30
	v_mov_b32_e32 v211, v31
	v_mul_f32_e32 v160, v208, v208
	v_mul_f32_e32 v161, v209, v209
	v_mul_f32_e32 v162, v210, v210
	v_mul_f32_e32 v163, v211, v211
	v_add_f32_e32 v246, v204, v204
	v_add_f32_e32 v248, v205, v205
	v_add_f32_e32 v249, v206, v206
	v_add_f32_e32 v250, v207, v207
	v_fma_f32 v204, v204, v204, -v160
	v_fma_f32 v205, v205, v205, -v161
	v_fma_f32 v206, v206, v206, -v162
	v_fma_f32 v207, v207, v207, -v163
	v_mul_f32_e32 v208, v246, v208
	v_mul_f32_e32 v209, v248, v209
	v_mul_f32_e32 v210, v249, v210
	v_mul_f32_e32 v211, v250, v211
	v_mul_f32_e32 v160, v208, v208
	v_mul_f32_e32 v161, v209, v209
	v_mul_f32_e32 v162, v210, v210
	v_mul_f32_e32 v163, v211, v211
	v_add_f32_e32 v246, v204, v204
	v_add_f32_e32 v248, v205, v205
	v_add_f32_e32 v249, v206, v206
	v_add_f32_e32 v250, v207, v207
	v_fma_f32 v204, v204, v204, -v160
	v_fma_f32 v205, v205, v205, -v161
	v_fma_f32 v206, v206, v206, -v162
	v_fma_f32 v207, v207, v207, -v163
	v_mul_f32_e32 v208, v246, v208
	v_mul_f32_e32 v209, v248, v209
	v_mul_f32_e32 v210, v249, v210
	v_mul_f32_e32 v211, v250, v211
	v_mul_f32_e32 v160, v208, v208
	v_mul_f32_e32 v161, v209, v209
	v_mul_f32_e32 v162, v210, v210
	v_mul_f32_e32 v163, v211, v211
	v_add_f32_e32 v246, v204, v204
	v_add_f32_e32 v248, v205, v205
	v_add_f32_e32 v249, v206, v206
	v_add_f32_e32 v250, v207, v207
	v_fma_f32 v204, v204, v204, -v160
	v_fma_f32 v205, v205, v205, -v161
	v_fma_f32 v206, v206, v206, -v162
	v_fma_f32 v207, v207, v207, -v163
	v_mul_f32_e32 v208, v246, v208
	v_mul_f32_e32 v209, v248, v209
	v_mul_f32_e32 v210, v249, v210
	v_mul_f32_e32 v211, v250, v211
	v_mul_f32_e32 v160, v208, v208
	v_mul_f32_e32 v161, v209, v209
	v_mul_f32_e32 v162, v210, v210
	v_mul_f32_e32 v163, v211, v211
	v_add_f32_e32 v246, v204, v204
	v_add_f32_e32 v248, v205, v205
	v_add_f32_e32 v249, v206, v206
	v_add_f32_e32 v250, v207, v207
	v_fma_f32 v204, v204, v204, -v160
	v_fma_f32 v205, v205, v205, -v161
	v_fma_f32 v206, v206, v206, -v162
	v_fma_f32 v207, v207, v207, -v163
	v_mul_f32_e32 v208, v246, v208
	v_mul_f32_e32 v209, v248, v209
	v_mul_f32_e32 v210, v249, v210
	v_mul_f32_e32 v211, v250, v211
	v_mul_f32_e32 v160, v208, v208
	v_mul_f32_e32 v161, v209, v209
	v_mul_f32_e32 v162, v210, v210
	v_mul_f32_e32 v163, v211, v211
	v_add_f32_e32 v246, v204, v204
	v_add_f32_e32 v248, v205, v205
	v_add_f32_e32 v249, v206, v206
	v_add_f32_e32 v250, v207, v207
	v_fma_f32 v204, v204, v204, -v160
	v_fma_f32 v205, v205, v205, -v161
	v_fma_f32 v206, v206, v206, -v162
	v_fma_f32 v207, v207, v207, -v163
	v_mul_f32_e32 v208, v246, v208
	v_mul_f32_e32 v209, v248, v209
	v_mul_f32_e32 v210, v249, v210
	v_mul_f32_e32 v211, v250, v211
	v_mul_f32_e32 v160, v208, v208
	v_mul_f32_e32 v161, v209, v209
	v_mul_f32_e32 v162, v210, v210
	v_mul_f32_e32 v163, v211, v211
	v_add_f32_e32 v246, v204, v204
	v_add_f32_e32 v248, v205, v205
	v_add_f32_e32 v249, v206, v206
	v_add_f32_e32 v250, v207, v207
	v_fma_f32 v204, v204, v204, -v160
	v_fma_f32 v205, v205, v205, -v161
	v_fma_f32 v206, v206, v206, -v162
	v_fma_f32 v207, v207, v207, -v163
	v_mul_f32_e32 v208, v246, v208
	v_mul_f32_e32 v209, v248, v209
	v_mul_f32_e32 v210, v249, v210
	v_mul_f32_e32 v211, v250, v211
	v_mul_f32_e32 v160, v208, v208
	v_mul_f32_e32 v161, v209, v209
	v_mul_f32_e32 v162, v210, v210
	v_mul_f32_e32 v163, v211, v211
	v_add_f32_e32 v246, v204, v204
	v_add_f32_e32 v248, v205, v205
	v_add_f32_e32 v249, v206, v206
	v_add_f32_e32 v250, v207, v207
	v_fma_f32 v204, v204, v204, -v160
	v_fma_f32 v205, v205, v205, -v161
	v_fma_f32 v206, v206, v206, -v162
	v_fma_f32 v207, v207, v207, -v163
	v_mul_f32_e32 v208, v246, v208
	v_mul_f32_e32 v209, v248, v209
	v_mul_f32_e32 v210, v249, v210
	v_mul_f32_e32 v211, v250, v211
	v_mul_f32_e32 v160, v208, v208
	v_mul_f32_e32 v161, v209, v209
	v_mul_f32_e32 v162, v210, v210
	v_mul_f32_e32 v163, v211, v211
	v_add_f32_e32 v246, v204, v204
	v_add_f32_e32 v248, v205, v205
	v_add_f32_e32 v249, v206, v206
	v_add_f32_e32 v250, v207, v207
	v_fma_f32 v204, v204, v204, -v160
	v_fma_f32 v205, v205, v205, -v161
	v_fma_f32 v206, v206, v206, -v162
	v_fma_f32 v207, v207, v207, -v163
	v_mul_f32_e32 v208, v246, v208
	v_mul_f32_e32 v209, v248, v209
	v_mul_f32_e32 v210, v249, v210
	v_mul_f32_e32 v211, v250, v211
	v_mov_b32_e32 v224, v0
	v_mov_b32_e32 v228, v5
	v_mov_b32_e32 v225, v1
	v_mov_b32_e32 v229, v6
	v_mov_b32_e32 v226, v2
	v_mov_b32_e32 v230, v7
	v_mov_b32_e32 v227, v3
	v_mov_b32_e32 v231, v8
	s_cmp_lt_u32 s25, 2
	s_cbranch_scc1 .Lsc_init_done
	v_mul_f32_e32 v160, v208, v228
	v_mul_f32_e32 v246, v208, v224
	v_mul_f32_e32 v161, v209, v229
	v_mul_f32_e32 v248, v209, v225
	v_mul_f32_e32 v162, v210, v230
	v_mul_f32_e32 v249, v210, v226
	v_mul_f32_e32 v163, v211, v231
	v_mul_f32_e32 v250, v211, v227
	v_fma_f32 v160, v204, v224, -v160
	v_fma_f32 v246, v204, v228, v246
	v_fma_f32 v161, v205, v225, -v161
	v_fma_f32 v248, v205, v229, v248
	v_fma_f32 v162, v206, v226, -v162
	v_fma_f32 v249, v206, v230, v249
	v_fma_f32 v163, v207, v227, -v163
	v_fma_f32 v250, v207, v231, v250
	v_add_f32_e32 v224, v160, v9
	v_add_f32_e32 v228, v246, v156
	v_add_f32_e32 v225, v161, v10
	v_add_f32_e32 v229, v248, v157
	v_add_f32_e32 v226, v162, v11
	v_add_f32_e32 v230, v249, v158
	v_add_f32_e32 v227, v163, v149
	v_add_f32_e32 v231, v250, v159
	s_cmp_lt_u32 s25, 3
	s_cbranch_scc1 .Lsc_init_done
	v_mul_f32_e32 v160, v208, v228
	v_mul_f32_e32 v246, v208, v224
	v_mul_f32_e32 v161, v209, v229
	v_mul_f32_e32 v248, v209, v225
	v_mul_f32_e32 v162, v210, v230
	v_mul_f32_e32 v249, v210, v226
	v_mul_f32_e32 v163, v211, v231
	v_mul_f32_e32 v250, v211, v227
	v_fma_f32 v160, v204, v224, -v160
	v_fma_f32 v246, v204, v228, v246
	v_fma_f32 v161, v205, v225, -v161
	v_fma_f32 v248, v205, v229, v248
	v_fma_f32 v162, v206, v226, -v162
	v_fma_f32 v249, v206, v230, v249
	v_fma_f32 v163, v207, v227, -v163
	v_fma_f32 v250, v207, v231, v250
	v_add_f32_e32 v224, v160, v106
	v_add_f32_e32 v228, v246, v110
	v_add_f32_e32 v225, v161, v107
	v_add_f32_e32 v229, v248, v111
	v_add_f32_e32 v226, v162, v108
	v_add_f32_e32 v230, v249, v112
	v_add_f32_e32 v227, v163, v109
	v_add_f32_e32 v231, v250, v113
.Lsc_init_done:
	s_waitcnt vmcnt(0)
	v_mov_b32_e32 v216, v18
	v_mov_b32_e32 v220, v19
	v_xor_b32_e32 v232, 0x80000000, v19
	v_mov_b32_e32 v217, v22
	v_mov_b32_e32 v221, v23
	v_xor_b32_e32 v233, 0x80000000, v23
	v_mov_b32_e32 v218, v26
	v_mov_b32_e32 v222, v27
	v_xor_b32_e32 v234, 0x80000000, v27
	v_mov_b32_e32 v219, v30
	v_mov_b32_e32 v223, v31
	v_xor_b32_e32 v235, 0x80000000, v31
	v_mul_f32_e32 v160, v21, v66
	v_mul_f32_e32 v248, v20, v66
	v_mul_f32_e32 v161, v21, v67
	v_mul_f32_e32 v249, v20, v67
	v_mul_f32_e32 v162, v21, v68
	v_mul_f32_e32 v250, v20, v68
	v_mul_f32_e32 v163, v21, v69
	v_mul_f32_e32 v251, v20, v69
	v_fma_f32 v160, v20, v50, -v160
	v_fma_f32 v248, v21, v50, v248
	v_fma_f32 v161, v20, v51, -v161
	v_fma_f32 v249, v21, v51, v249
	v_fma_f32 v162, v20, v52, -v162
	v_fma_f32 v250, v21, v52, v250
	v_fma_f32 v163, v20, v53, -v163
	v_fma_f32 v251, v21, v53, v251
	v_cvt_pk_bf16_f32 v114, v160, v161
	v_cvt_pk_bf16_f32 v115, v162, v163
	v_cvt_pk_bf16_f32 v116, v248, v249
	v_cvt_pk_bf16_f32 v117, v250, v251
	v_mul_f32_e32 v160, v25, v70
	v_mul_f32_e32 v248, v24, v70
	v_mul_f32_e32 v161, v25, v71
	v_mul_f32_e32 v249, v24, v71
	v_mul_f32_e32 v162, v25, v72
	v_mul_f32_e32 v250, v24, v72
	v_mul_f32_e32 v163, v25, v73
	v_mul_f32_e32 v251, v24, v73
	v_fma_f32 v160, v24, v54, -v160
	v_fma_f32 v248, v25, v54, v248
	v_fma_f32 v161, v24, v55, -v161
	v_fma_f32 v249, v25, v55, v249
	v_fma_f32 v162, v24, v56, -v162
	v_fma_f32 v250, v25, v56, v250
	v_fma_f32 v163, v24, v57, -v163
	v_fma_f32 v251, v25, v57, v251
	v_cvt_pk_bf16_f32 v118, v160, v161
	v_cvt_pk_bf16_f32 v119, v162, v163
	v_cvt_pk_bf16_f32 v120, v248, v249
	v_cvt_pk_bf16_f32 v121, v250, v251
	v_mul_f32_e32 v160, v29, v74
	v_mul_f32_e32 v248, v28, v74
	v_mul_f32_e32 v161, v29, v75
	v_mul_f32_e32 v249, v28, v75
	v_mul_f32_e32 v162, v29, v76
	v_mul_f32_e32 v250, v28, v76
	v_mul_f32_e32 v163, v29, v77
	v_mul_f32_e32 v251, v28, v77
	v_fma_f32 v160, v28, v58, -v160
	v_fma_f32 v248, v29, v58, v248
	v_fma_f32 v161, v28, v59, -v161
	v_fma_f32 v249, v29, v59, v249
	v_fma_f32 v162, v28, v60, -v162
	v_fma_f32 v250, v29, v60, v250
	v_fma_f32 v163, v28, v61, -v163
	v_fma_f32 v251, v29, v61, v251
	v_cvt_pk_bf16_f32 v122, v160, v161
	v_cvt_pk_bf16_f32 v123, v162, v163
	v_cvt_pk_bf16_f32 v124, v248, v249
	v_cvt_pk_bf16_f32 v125, v250, v251
	v_mul_f32_e32 v160, v33, v78
	v_mul_f32_e32 v248, v32, v78
	v_mul_f32_e32 v161, v33, v79
	v_mul_f32_e32 v249, v32, v79
	v_mul_f32_e32 v162, v33, v80
	v_mul_f32_e32 v250, v32, v80
	v_mul_f32_e32 v163, v33, v81
	v_mul_f32_e32 v251, v32, v81
	v_fma_f32 v160, v32, v62, -v160
	v_fma_f32 v248, v33, v62, v248
	v_fma_f32 v161, v32, v63, -v161
	v_fma_f32 v249, v33, v63, v249
	v_fma_f32 v162, v32, v64, -v162
	v_fma_f32 v250, v33, v64, v250
	v_fma_f32 v163, v32, v65, -v163
	v_fma_f32 v251, v33, v65, v251
	v_cvt_pk_bf16_f32 v126, v160, v161
	v_cvt_pk_bf16_f32 v127, v162, v163
	v_cvt_pk_bf16_f32 v128, v248, v249
	v_cvt_pk_bf16_f32 v129, v250, v251
	v_xor_b32_e32 v160, 0x80000000, v188
	v_xor_b32_e32 v161, 0x80000000, v189
	v_xor_b32_e32 v162, 0x80000000, v190
	v_xor_b32_e32 v163, 0x80000000, v191
	v_cvt_pk_bf16_f32 v172, v34, v160
	v_cvt_pk_bf16_f32 v173, v35, v161
	v_cvt_pk_bf16_f32 v174, v36, v162
	v_cvt_pk_bf16_f32 v175, v37, v163
	v_xor_b32_e32 v160, 0x80000000, v192
	v_xor_b32_e32 v161, 0x80000000, v193
	v_xor_b32_e32 v162, 0x80000000, v194
	v_xor_b32_e32 v163, 0x80000000, v195
	v_cvt_pk_bf16_f32 v176, v38, v160
	v_cvt_pk_bf16_f32 v177, v39, v161
	v_cvt_pk_bf16_f32 v178, v40, v162
	v_cvt_pk_bf16_f32 v179, v41, v163
	v_xor_b32_e32 v160, 0x80000000, v196
	v_xor_b32_e32 v161, 0x80000000, v197
	v_xor_b32_e32 v162, 0x80000000, v198
	v_xor_b32_e32 v163, 0x80000000, v199
	v_cvt_pk_bf16_f32 v180, v42, v160
	v_cvt_pk_bf16_f32 v181, v43, v161
	v_cvt_pk_bf16_f32 v182, v44, v162
	v_cvt_pk_bf16_f32 v183, v45, v163
	v_xor_b32_e32 v160, 0x80000000, v200
	v_xor_b32_e32 v161, 0x80000000, v201
	v_xor_b32_e32 v162, 0x80000000, v202
	v_xor_b32_e32 v163, 0x80000000, v203
	v_cvt_pk_bf16_f32 v184, v46, v160
	v_cvt_pk_bf16_f32 v185, v47, v161
	v_cvt_pk_bf16_f32 v186, v48, v162
	v_cvt_pk_bf16_f32 v187, v49, v163
	s_nop 1
	v_mfma_f32_16x16x16_bf16 v[18:21], v[82:83], v[114:115], v[212:215]
	v_mfma_f32_16x16x16_bf16 v[22:25], v[82:83], v[116:117], v[212:215]
	v_mfma_f32_16x16x16_bf16 v[26:29], v[82:83], v[118:119], v[212:215]
	v_mfma_f32_16x16x16_bf16 v[30:33], v[82:83], v[120:121], v[212:215]
	v_mfma_f32_16x16x16_bf16 v[34:37], v[82:83], v[122:123], v[212:215]
	v_mfma_f32_16x16x16_bf16 v[38:41], v[82:83], v[124:125], v[212:215]
	v_mfma_f32_16x16x16_bf16 v[42:45], v[82:83], v[126:127], v[212:215]
	v_mfma_f32_16x16x16_bf16 v[46:49], v[82:83], v[128:129], v[212:215]
	s_mov_b32 s15, 0
	s_and_b64 s[82:83], s[80:81], exec
	s_cbranch_scc1 .Lsc_local_loop
.Lsc_loop:
	global_load_dwordx2 v[106:107], v[130:131], off
	v_lshl_add_u64 v[130:131], v[130:131], 0, s[86:87]
	global_load_dwordx2 v[108:109], v[130:131], off
	v_lshl_add_u64 v[130:131], v[130:131], 0, s[86:87]
	global_load_dwordx2 v[110:111], v[130:131], off
	v_lshl_add_u64 v[130:131], v[130:131], 0, s[86:87]
	global_load_dwordx2 v[112:113], v[130:131], off
	v_lshl_add_u64 v[130:131], v[130:131], 0, s[86:87]
	v_mfma_f32_16x16x16_bf16 v[50:53], v[84:85], v[114:115], v[212:215]
	v_fmac_f32_e32 v18, v232, v228
	v_fmac_f32_e32 v22, v220, v224
	v_fmac_f32_e32 v26, v233, v229
	v_fmac_f32_e32 v30, v221, v225
	v_mfma_f32_16x16x16_bf16 v[54:57], v[84:85], v[116:117], v[212:215]
	v_fmac_f32_e32 v34, v234, v230
	v_fmac_f32_e32 v38, v222, v226
	v_fmac_f32_e32 v42, v235, v231
	v_fmac_f32_e32 v46, v223, v227
	v_mfma_f32_16x16x16_bf16 v[58:61], v[84:85], v[118:119], v[212:215]
	v_fma_f32 v224, v216, v224, v18
	v_fma_f32 v228, v216, v228, v22
	v_fma_f32 v225, v217, v225, v26
	v_fma_f32 v229, v217, v229, v30
	v_mfma_f32_16x16x16_bf16 v[62:65], v[84:85], v[120:121], v[212:215]
	v_fma_f32 v226, v218, v226, v34
	v_fma_f32 v230, v218, v230, v38
	v_fma_f32 v227, v219, v227, v42
	v_fma_f32 v231, v219, v231, v46
	s_waitcnt lgkmcnt(0)
	v_mfma_f32_16x16x32_bf16 v[204:207], v[172:175], v[188:191], v[212:215]
	v_cvt_pk_bf16_f32 v136, v224, v228
	v_cvt_pk_bf16_f32 v137, v225, v229
	v_mfma_f32_16x16x32_bf16 v[208:211], v[176:179], v[192:195], v[212:215]
	v_cvt_pk_bf16_f32 v138, v226, v230
	v_cvt_pk_bf16_f32 v139, v227, v231
	ds_write2_b32 v134, v136, v137 offset0:0 offset1:16
	ds_write2_b32 v134, v138, v139 offset0:32 offset1:48
	v_mfma_f32_16x16x16_bf16 v[66:69], v[84:85], v[122:123], v[212:215]
	v_fmac_f32_e32 v19, v232, v228
	v_fmac_f32_e32 v23, v220, v224
	v_fmac_f32_e32 v27, v233, v229
	v_fmac_f32_e32 v31, v221, v225
	v_mfma_f32_16x16x16_bf16 v[70:73], v[84:85], v[124:125], v[212:215]
	v_fmac_f32_e32 v35, v234, v230
	v_fmac_f32_e32 v39, v222, v226
	v_fmac_f32_e32 v43, v235, v231
	v_fmac_f32_e32 v47, v223, v227
	v_mfma_f32_16x16x16_bf16 v[74:77], v[84:85], v[126:127], v[212:215]
	v_fma_f32 v224, v216, v224, v19
	v_fma_f32 v228, v216, v228, v23
	v_fma_f32 v225, v217, v225, v27
	v_fma_f32 v229, v217, v229, v31
	v_mfma_f32_16x16x16_bf16 v[78:81], v[84:85], v[128:129], v[212:215]
	v_fma_f32 v226, v218, v226, v35
	v_fma_f32 v230, v218, v230, v39
	v_fma_f32 v227, v219, v227, v43
	v_fma_f32 v231, v219, v231, v47
	v_mfma_f32_16x16x32_bf16 v[204:207], v[180:183], v[196:199], v[204:207]
	v_cvt_pk_bf16_f32 v136, v224, v228
	v_cvt_pk_bf16_f32 v137, v225, v229
	v_mfma_f32_16x16x32_bf16 v[208:211], v[184:187], v[200:203], v[208:211]
	v_cvt_pk_bf16_f32 v138, v226, v230
	v_cvt_pk_bf16_f32 v139, v227, v231
	ds_write2_b32 v134, v136, v137 offset0:68 offset1:84
	ds_write2_b32 v134, v138, v139 offset0:100 offset1:116
	v_fmac_f32_e32 v20, v232, v228
	v_fmac_f32_e32 v24, v220, v224
	v_fmac_f32_e32 v28, v233, v229
	v_fmac_f32_e32 v32, v221, v225
	v_fmac_f32_e32 v36, v234, v230
	v_fmac_f32_e32 v40, v222, v226
	v_fmac_f32_e32 v44, v235, v231
	v_fmac_f32_e32 v48, v223, v227
	v_fma_f32 v224, v216, v224, v20
	v_fma_f32 v228, v216, v228, v24
	v_fma_f32 v225, v217, v225, v28
	v_fma_f32 v229, v217, v229, v32
	v_fma_f32 v226, v218, v226, v36
	v_fma_f32 v230, v218, v230, v40
	v_fma_f32 v227, v219, v227, v44
	v_fma_f32 v231, v219, v231, v48
	v_cvt_pk_bf16_f32 v136, v224, v228
	v_cvt_pk_bf16_f32 v137, v225, v229
	v_cvt_pk_bf16_f32 v138, v226, v230
	v_cvt_pk_bf16_f32 v139, v227, v231
	ds_write2_b32 v134, v136, v137 offset0:136 offset1:152
	ds_write2_b32 v134, v138, v139 offset0:168 offset1:184
	v_fmac_f32_e32 v21, v232, v228
	v_fmac_f32_e32 v25, v220, v224
	v_fmac_f32_e32 v29, v233, v229
	v_fmac_f32_e32 v33, v221, v225
	v_fmac_f32_e32 v37, v234, v230
	v_fmac_f32_e32 v41, v222, v226
	v_fmac_f32_e32 v45, v235, v231
	v_fmac_f32_e32 v49, v223, v227
	v_fma_f32 v224, v216, v224, v21
	v_fma_f32 v228, v216, v228, v25
	v_fma_f32 v225, v217, v225, v29
	v_fma_f32 v229, v217, v229, v33
	v_fma_f32 v226, v218, v226, v37
	v_fma_f32 v230, v218, v230, v41
	v_fma_f32 v227, v219, v227, v45
	v_fma_f32 v231, v219, v231, v49
	v_cvt_pk_bf16_f32 v136, v224, v228
	v_cvt_pk_bf16_f32 v137, v225, v229
	v_cvt_pk_bf16_f32 v138, v226, v230
	v_cvt_pk_bf16_f32 v139, v227, v231
	ds_write2_b32 v134, v136, v137 offset0:204 offset1:220
	ds_write2_b32 v134, v138, v139 offset0:236 offset1:252
	s_cmp_eq_u32 s15, 0
	s_cbranch_scc1 .Lsc_skip_first
	v_add_f32_e32 v204, v204, v208
	v_add_f32_e32 v205, v205, v209
	v_add_f32_e32 v206, v206, v210
	v_add_f32_e32 v207, v207, v211
	global_store_dwordx4 v[132:133], v[204:207], off
	v_lshl_add_u64 v[132:133], v[132:133], 0, s[88:89]
.Lsc_skip_first:
	s_waitcnt lgkmcnt(0)
	ds_read_b128 v[188:191], v135 offset:0
	ds_read_b128 v[192:195], v135 offset:64
	ds_read_b128 v[196:199], v135 offset:128
	ds_read_b128 v[200:203], v135 offset:192
	v_mfma_f32_16x16x16_bf16 v[18:21], v[86:87], v[114:115], v[212:215]
	v_fmac_f32_e32 v50, v232, v228
	v_fmac_f32_e32 v54, v220, v224
	v_fmac_f32_e32 v58, v233, v229
	v_fmac_f32_e32 v62, v221, v225
	v_mfma_f32_16x16x16_bf16 v[22:25], v[86:87], v[116:117], v[212:215]
	v_fmac_f32_e32 v66, v234, v230
	v_fmac_f32_e32 v70, v222, v226
	v_fmac_f32_e32 v74, v235, v231
	v_fmac_f32_e32 v78, v223, v227
	v_mfma_f32_16x16x16_bf16 v[26:29], v[86:87], v[118:119], v[212:215]
	v_fma_f32 v224, v216, v224, v50
	v_fma_f32 v228, v216, v228, v54
	v_fma_f32 v225, v217, v225, v58
	v_fma_f32 v229, v217, v229, v62
	v_mfma_f32_16x16x16_bf16 v[30:33], v[86:87], v[120:121], v[212:215]
	v_fma_f32 v226, v218, v226, v66
	v_fma_f32 v230, v218, v230, v70
	v_fma_f32 v227, v219, v227, v74
	v_fma_f32 v231, v219, v231, v78
	s_waitcnt lgkmcnt(0)
	v_mfma_f32_16x16x32_bf16 v[204:207], v[172:175], v[188:191], v[212:215]
	v_cvt_pk_bf16_f32 v136, v224, v228
	v_cvt_pk_bf16_f32 v137, v225, v229
	v_mfma_f32_16x16x32_bf16 v[208:211], v[176:179], v[192:195], v[212:215]
	v_cvt_pk_bf16_f32 v138, v226, v230
	v_cvt_pk_bf16_f32 v139, v227, v231
	ds_write2_b32 v134, v136, v137 offset0:0 offset1:16
	ds_write2_b32 v134, v138, v139 offset0:32 offset1:48
	v_mfma_f32_16x16x16_bf16 v[34:37], v[86:87], v[122:123], v[212:215]
	v_fmac_f32_e32 v51, v232, v228
	v_fmac_f32_e32 v55, v220, v224
	v_fmac_f32_e32 v59, v233, v229
	v_fmac_f32_e32 v63, v221, v225
	v_mfma_f32_16x16x16_bf16 v[38:41], v[86:87], v[124:125], v[212:215]
	v_fmac_f32_e32 v67, v234, v230
	v_fmac_f32_e32 v71, v222, v226
	v_fmac_f32_e32 v75, v235, v231
	v_fmac_f32_e32 v79, v223, v227
	v_mfma_f32_16x16x16_bf16 v[42:45], v[86:87], v[126:127], v[212:215]
	v_fma_f32 v224, v216, v224, v51
	v_fma_f32 v228, v216, v228, v55
	v_fma_f32 v225, v217, v225, v59
	v_fma_f32 v229, v217, v229, v63
	v_mfma_f32_16x16x16_bf16 v[46:49], v[86:87], v[128:129], v[212:215]
	v_fma_f32 v226, v218, v226, v67
	v_fma_f32 v230, v218, v230, v71
	v_fma_f32 v227, v219, v227, v75
	v_fma_f32 v231, v219, v231, v79
	v_mfma_f32_16x16x32_bf16 v[204:207], v[180:183], v[196:199], v[204:207]
	v_cvt_pk_bf16_f32 v136, v224, v228
	v_cvt_pk_bf16_f32 v137, v225, v229
	v_mfma_f32_16x16x32_bf16 v[208:211], v[184:187], v[200:203], v[208:211]
	v_cvt_pk_bf16_f32 v138, v226, v230
	v_cvt_pk_bf16_f32 v139, v227, v231
	ds_write2_b32 v134, v136, v137 offset0:68 offset1:84
	ds_write2_b32 v134, v138, v139 offset0:100 offset1:116
	v_fmac_f32_e32 v52, v232, v228
	v_fmac_f32_e32 v56, v220, v224
	v_fmac_f32_e32 v60, v233, v229
	v_fmac_f32_e32 v64, v221, v225
	v_fmac_f32_e32 v68, v234, v230
	v_fmac_f32_e32 v72, v222, v226
	v_fmac_f32_e32 v76, v235, v231
	v_fmac_f32_e32 v80, v223, v227
	v_fma_f32 v224, v216, v224, v52
	v_fma_f32 v228, v216, v228, v56
	v_fma_f32 v225, v217, v225, v60
	v_fma_f32 v229, v217, v229, v64
	v_fma_f32 v226, v218, v226, v68
	v_fma_f32 v230, v218, v230, v72
	v_fma_f32 v227, v219, v227, v76
	v_fma_f32 v231, v219, v231, v80
	v_cvt_pk_bf16_f32 v136, v224, v228
	v_cvt_pk_bf16_f32 v137, v225, v229
	v_cvt_pk_bf16_f32 v138, v226, v230
	v_cvt_pk_bf16_f32 v139, v227, v231
	ds_write2_b32 v134, v136, v137 offset0:136 offset1:152
	ds_write2_b32 v134, v138, v139 offset0:168 offset1:184
	v_fmac_f32_e32 v53, v232, v228
	v_fmac_f32_e32 v57, v220, v224
	v_fmac_f32_e32 v61, v233, v229
	v_fmac_f32_e32 v65, v221, v225
	v_fmac_f32_e32 v69, v234, v230
	v_fmac_f32_e32 v73, v222, v226
	v_fmac_f32_e32 v77, v235, v231
	v_fmac_f32_e32 v81, v223, v227
	v_fma_f32 v224, v216, v224, v53
	v_fma_f32 v228, v216, v228, v57
	v_fma_f32 v225, v217, v225, v61
	v_fma_f32 v229, v217, v229, v65
	v_fma_f32 v226, v218, v226, v69
	v_fma_f32 v230, v218, v230, v73
	v_fma_f32 v227, v219, v227, v77
	v_fma_f32 v231, v219, v231, v81
	v_cvt_pk_bf16_f32 v136, v224, v228
	v_cvt_pk_bf16_f32 v137, v225, v229
	v_cvt_pk_bf16_f32 v138, v226, v230
	v_cvt_pk_bf16_f32 v139, v227, v231
	ds_write2_b32 v134, v136, v137 offset0:204 offset1:220
	ds_write2_b32 v134, v138, v139 offset0:236 offset1:252
	v_add_f32_e32 v204, v204, v208
	v_add_f32_e32 v205, v205, v209
	v_add_f32_e32 v206, v206, v210
	v_add_f32_e32 v207, v207, v211
	global_store_dwordx4 v[132:133], v[204:207], off
	v_lshl_add_u64 v[132:133], v[132:133], 0, s[88:89]
	s_waitcnt lgkmcnt(0)
	ds_read_b128 v[188:191], v135 offset:0
	ds_read_b128 v[192:195], v135 offset:64
	ds_read_b128 v[196:199], v135 offset:128
	ds_read_b128 v[200:203], v135 offset:192
	v_mfma_f32_16x16x16_bf16 v[50:53], v[88:89], v[114:115], v[212:215]
	v_fmac_f32_e32 v18, v232, v228
	v_fmac_f32_e32 v22, v220, v224
	v_fmac_f32_e32 v26, v233, v229
	v_fmac_f32_e32 v30, v221, v225
	v_mfma_f32_16x16x16_bf16 v[54:57], v[88:89], v[116:117], v[212:215]
	v_fmac_f32_e32 v34, v234, v230
	v_fmac_f32_e32 v38, v222, v226
	v_fmac_f32_e32 v42, v235, v231
	v_fmac_f32_e32 v46, v223, v227
	v_mfma_f32_16x16x16_bf16 v[58:61], v[88:89], v[118:119], v[212:215]
	v_fma_f32 v224, v216, v224, v18
	v_fma_f32 v228, v216, v228, v22
	v_fma_f32 v225, v217, v225, v26
	v_fma_f32 v229, v217, v229, v30
	v_mfma_f32_16x16x16_bf16 v[62:65], v[88:89], v[120:121], v[212:215]
	v_fma_f32 v226, v218, v226, v34
	v_fma_f32 v230, v218, v230, v38
	v_fma_f32 v227, v219, v227, v42
	v_fma_f32 v231, v219, v231, v46
	s_waitcnt lgkmcnt(0)
	v_mfma_f32_16x16x32_bf16 v[204:207], v[172:175], v[188:191], v[212:215]
	v_cvt_pk_bf16_f32 v136, v224, v228
	v_cvt_pk_bf16_f32 v137, v225, v229
	v_mfma_f32_16x16x32_bf16 v[208:211], v[176:179], v[192:195], v[212:215]
	v_cvt_pk_bf16_f32 v138, v226, v230
	v_cvt_pk_bf16_f32 v139, v227, v231
	ds_write2_b32 v134, v136, v137 offset0:0 offset1:16
	ds_write2_b32 v134, v138, v139 offset0:32 offset1:48
	v_mfma_f32_16x16x16_bf16 v[66:69], v[88:89], v[122:123], v[212:215]
	v_fmac_f32_e32 v19, v232, v228
	v_fmac_f32_e32 v23, v220, v224
	v_fmac_f32_e32 v27, v233, v229
	v_fmac_f32_e32 v31, v221, v225
	v_mfma_f32_16x16x16_bf16 v[70:73], v[88:89], v[124:125], v[212:215]
	v_fmac_f32_e32 v35, v234, v230
	v_fmac_f32_e32 v39, v222, v226
	v_fmac_f32_e32 v43, v235, v231
	v_fmac_f32_e32 v47, v223, v227
	v_mfma_f32_16x16x16_bf16 v[74:77], v[88:89], v[126:127], v[212:215]
	v_fma_f32 v224, v216, v224, v19
	v_fma_f32 v228, v216, v228, v23
	v_fma_f32 v225, v217, v225, v27
	v_fma_f32 v229, v217, v229, v31
	v_mfma_f32_16x16x16_bf16 v[78:81], v[88:89], v[128:129], v[212:215]
	v_fma_f32 v226, v218, v226, v35
	v_fma_f32 v230, v218, v230, v39
	v_fma_f32 v227, v219, v227, v43
	v_fma_f32 v231, v219, v231, v47
	v_mfma_f32_16x16x32_bf16 v[204:207], v[180:183], v[196:199], v[204:207]
	v_cvt_pk_bf16_f32 v136, v224, v228
	v_cvt_pk_bf16_f32 v137, v225, v229
	v_mfma_f32_16x16x32_bf16 v[208:211], v[184:187], v[200:203], v[208:211]
	v_cvt_pk_bf16_f32 v138, v226, v230
	v_cvt_pk_bf16_f32 v139, v227, v231
	ds_write2_b32 v134, v136, v137 offset0:68 offset1:84
	ds_write2_b32 v134, v138, v139 offset0:100 offset1:116
	v_fmac_f32_e32 v20, v232, v228
	v_fmac_f32_e32 v24, v220, v224
	v_fmac_f32_e32 v28, v233, v229
	v_fmac_f32_e32 v32, v221, v225
	v_fmac_f32_e32 v36, v234, v230
	v_fmac_f32_e32 v40, v222, v226
	v_fmac_f32_e32 v44, v235, v231
	v_fmac_f32_e32 v48, v223, v227
	v_fma_f32 v224, v216, v224, v20
	v_fma_f32 v228, v216, v228, v24
	v_fma_f32 v225, v217, v225, v28
	v_fma_f32 v229, v217, v229, v32
	v_fma_f32 v226, v218, v226, v36
	v_fma_f32 v230, v218, v230, v40
	v_fma_f32 v227, v219, v227, v44
	v_fma_f32 v231, v219, v231, v48
	v_cvt_pk_bf16_f32 v136, v224, v228
	v_cvt_pk_bf16_f32 v137, v225, v229
	v_cvt_pk_bf16_f32 v138, v226, v230
	v_cvt_pk_bf16_f32 v139, v227, v231
	ds_write2_b32 v134, v136, v137 offset0:136 offset1:152
	ds_write2_b32 v134, v138, v139 offset0:168 offset1:184
	v_fmac_f32_e32 v21, v232, v228
	v_fmac_f32_e32 v25, v220, v224
	v_fmac_f32_e32 v29, v233, v229
	v_fmac_f32_e32 v33, v221, v225
	v_fmac_f32_e32 v37, v234, v230
	v_fmac_f32_e32 v41, v222, v226
	v_fmac_f32_e32 v45, v235, v231
	v_fmac_f32_e32 v49, v223, v227
	v_fma_f32 v224, v216, v224, v21
	v_fma_f32 v228, v216, v228, v25
	v_fma_f32 v225, v217, v225, v29
	v_fma_f32 v229, v217, v229, v33
	v_fma_f32 v226, v218, v226, v37
	v_fma_f32 v230, v218, v230, v41
	v_fma_f32 v227, v219, v227, v45
	v_fma_f32 v231, v219, v231, v49
	v_cvt_pk_bf16_f32 v136, v224, v228
	v_cvt_pk_bf16_f32 v137, v225, v229
	v_cvt_pk_bf16_f32 v138, v226, v230
	v_cvt_pk_bf16_f32 v139, v227, v231
	ds_write2_b32 v134, v136, v137 offset0:204 offset1:220
	ds_write2_b32 v134, v138, v139 offset0:236 offset1:252
	v_add_f32_e32 v204, v204, v208
	v_add_f32_e32 v205, v205, v209
	v_add_f32_e32 v206, v206, v210
	v_add_f32_e32 v207, v207, v211
	global_store_dwordx4 v[132:133], v[204:207], off
	v_lshl_add_u64 v[132:133], v[132:133], 0, s[88:89]
	s_waitcnt lgkmcnt(0)
	ds_read_b128 v[188:191], v135 offset:0
	ds_read_b128 v[192:195], v135 offset:64
	ds_read_b128 v[196:199], v135 offset:128
	ds_read_b128 v[200:203], v135 offset:192
	s_waitcnt vmcnt(14)
	v_mfma_f32_16x16x16_bf16 v[18:21], v[90:91], v[114:115], v[212:215]
	v_fmac_f32_e32 v50, v232, v228
	v_fmac_f32_e32 v54, v220, v224
	v_fmac_f32_e32 v58, v233, v229
	v_fmac_f32_e32 v62, v221, v225
	v_mfma_f32_16x16x16_bf16 v[22:25], v[90:91], v[116:117], v[212:215]
	v_fmac_f32_e32 v66, v234, v230
	v_fmac_f32_e32 v70, v222, v226
	v_fmac_f32_e32 v74, v235, v231
	v_fmac_f32_e32 v78, v223, v227
	v_mfma_f32_16x16x16_bf16 v[26:29], v[90:91], v[118:119], v[212:215]
	v_fma_f32 v224, v216, v224, v50
	v_fma_f32 v228, v216, v228, v54
	v_fma_f32 v225, v217, v225, v58
	v_fma_f32 v229, v217, v229, v62
	v_mfma_f32_16x16x16_bf16 v[30:33], v[90:91], v[120:121], v[212:215]
	v_fma_f32 v226, v218, v226, v66
	v_fma_f32 v230, v218, v230, v70
	v_fma_f32 v227, v219, v227, v74
	v_fma_f32 v231, v219, v231, v78
	s_waitcnt lgkmcnt(0)
	v_mfma_f32_16x16x32_bf16 v[204:207], v[172:175], v[188:191], v[212:215]
	v_cvt_pk_bf16_f32 v136, v224, v228
	v_cvt_pk_bf16_f32 v137, v225, v229
	v_mfma_f32_16x16x32_bf16 v[208:211], v[176:179], v[192:195], v[212:215]
	v_cvt_pk_bf16_f32 v138, v226, v230
	v_cvt_pk_bf16_f32 v139, v227, v231
	ds_write2_b32 v134, v136, v137 offset0:0 offset1:16
	ds_write2_b32 v134, v138, v139 offset0:32 offset1:48
	v_mfma_f32_16x16x16_bf16 v[34:37], v[90:91], v[122:123], v[212:215]
	v_fmac_f32_e32 v51, v232, v228
	v_fmac_f32_e32 v55, v220, v224
	v_fmac_f32_e32 v59, v233, v229
	v_fmac_f32_e32 v63, v221, v225
	v_mfma_f32_16x16x16_bf16 v[38:41], v[90:91], v[124:125], v[212:215]
	v_fmac_f32_e32 v67, v234, v230
	v_fmac_f32_e32 v71, v222, v226
	v_fmac_f32_e32 v75, v235, v231
	v_fmac_f32_e32 v79, v223, v227
	v_mfma_f32_16x16x16_bf16 v[42:45], v[90:91], v[126:127], v[212:215]
	v_fma_f32 v224, v216, v224, v51
	v_fma_f32 v228, v216, v228, v55
	v_fma_f32 v225, v217, v225, v59
	v_fma_f32 v229, v217, v229, v63
	v_mfma_f32_16x16x16_bf16 v[46:49], v[90:91], v[128:129], v[212:215]
	v_fma_f32 v226, v218, v226, v67
	v_fma_f32 v230, v218, v230, v71
	v_fma_f32 v227, v219, v227, v75
	v_fma_f32 v231, v219, v231, v79
	v_mfma_f32_16x16x32_bf16 v[204:207], v[180:183], v[196:199], v[204:207]
	v_cvt_pk_bf16_f32 v136, v224, v228
	v_cvt_pk_bf16_f32 v137, v225, v229
	v_mfma_f32_16x16x32_bf16 v[208:211], v[184:187], v[200:203], v[208:211]
	v_cvt_pk_bf16_f32 v138, v226, v230
	v_cvt_pk_bf16_f32 v139, v227, v231
	ds_write2_b32 v134, v136, v137 offset0:68 offset1:84
	ds_write2_b32 v134, v138, v139 offset0:100 offset1:116
	v_fmac_f32_e32 v52, v232, v228
	v_fmac_f32_e32 v56, v220, v224
	v_fmac_f32_e32 v60, v233, v229
	v_fmac_f32_e32 v64, v221, v225
	v_fmac_f32_e32 v68, v234, v230
	v_fmac_f32_e32 v72, v222, v226
	v_fmac_f32_e32 v76, v235, v231
	v_fmac_f32_e32 v80, v223, v227
	v_fma_f32 v224, v216, v224, v52
	v_fma_f32 v228, v216, v228, v56
	v_fma_f32 v225, v217, v225, v60
	v_fma_f32 v229, v217, v229, v64
	v_fma_f32 v226, v218, v226, v68
	v_fma_f32 v230, v218, v230, v72
	v_fma_f32 v227, v219, v227, v76
	v_fma_f32 v231, v219, v231, v80
	v_cvt_pk_bf16_f32 v136, v224, v228
	v_cvt_pk_bf16_f32 v137, v225, v229
	v_cvt_pk_bf16_f32 v138, v226, v230
	v_cvt_pk_bf16_f32 v139, v227, v231
	ds_write2_b32 v134, v136, v137 offset0:136 offset1:152
	ds_write2_b32 v134, v138, v139 offset0:168 offset1:184
	v_fmac_f32_e32 v53, v232, v228
	v_fmac_f32_e32 v57, v220, v224
	v_fmac_f32_e32 v61, v233, v229
	v_fmac_f32_e32 v65, v221, v225
	v_fmac_f32_e32 v69, v234, v230
	v_fmac_f32_e32 v73, v222, v226
	v_fmac_f32_e32 v77, v235, v231
	v_fmac_f32_e32 v81, v223, v227
	v_fma_f32 v224, v216, v224, v53
	v_fma_f32 v228, v216, v228, v57
	v_fma_f32 v225, v217, v225, v61
	v_fma_f32 v229, v217, v229, v65
	v_fma_f32 v226, v218, v226, v69
	v_fma_f32 v230, v218, v230, v73
	v_fma_f32 v227, v219, v227, v77
	v_fma_f32 v231, v219, v231, v81
	v_cvt_pk_bf16_f32 v136, v224, v228
	v_cvt_pk_bf16_f32 v137, v225, v229
	v_cvt_pk_bf16_f32 v138, v226, v230
	v_cvt_pk_bf16_f32 v139, v227, v231
	ds_write2_b32 v134, v136, v137 offset0:204 offset1:220
	ds_write2_b32 v134, v138, v139 offset0:236 offset1:252
	v_add_f32_e32 v204, v204, v208
	v_add_f32_e32 v205, v205, v209
	v_add_f32_e32 v206, v206, v210
	v_add_f32_e32 v207, v207, v211
	global_store_dwordx4 v[132:133], v[204:207], off
	v_lshl_add_u64 v[132:133], v[132:133], 0, s[88:89]
	s_waitcnt lgkmcnt(0)
	ds_read_b128 v[188:191], v135 offset:0
	ds_read_b128 v[192:195], v135 offset:64
	ds_read_b128 v[196:199], v135 offset:128
	ds_read_b128 v[200:203], v135 offset:192
	global_load_dwordx2 v[82:83], v[130:131], off
	v_lshl_add_u64 v[130:131], v[130:131], 0, s[86:87]
	global_load_dwordx2 v[84:85], v[130:131], off
	v_lshl_add_u64 v[130:131], v[130:131], 0, s[86:87]
	global_load_dwordx2 v[86:87], v[130:131], off
	v_lshl_add_u64 v[130:131], v[130:131], 0, s[86:87]
	global_load_dwordx2 v[88:89], v[130:131], off
	v_lshl_add_u64 v[130:131], v[130:131], 0, s[86:87]
	v_mfma_f32_16x16x16_bf16 v[50:53], v[92:93], v[114:115], v[212:215]
	v_fmac_f32_e32 v18, v232, v228
	v_fmac_f32_e32 v22, v220, v224
	v_fmac_f32_e32 v26, v233, v229
	v_fmac_f32_e32 v30, v221, v225
	v_mfma_f32_16x16x16_bf16 v[54:57], v[92:93], v[116:117], v[212:215]
	v_fmac_f32_e32 v34, v234, v230
	v_fmac_f32_e32 v38, v222, v226
	v_fmac_f32_e32 v42, v235, v231
	v_fmac_f32_e32 v46, v223, v227
	v_mfma_f32_16x16x16_bf16 v[58:61], v[92:93], v[118:119], v[212:215]
	v_fma_f32 v224, v216, v224, v18
	v_fma_f32 v228, v216, v228, v22
	v_fma_f32 v225, v217, v225, v26
	v_fma_f32 v229, v217, v229, v30
	v_mfma_f32_16x16x16_bf16 v[62:65], v[92:93], v[120:121], v[212:215]
	v_fma_f32 v226, v218, v226, v34
	v_fma_f32 v230, v218, v230, v38
	v_fma_f32 v227, v219, v227, v42
	v_fma_f32 v231, v219, v231, v46
	s_waitcnt lgkmcnt(0)
	v_mfma_f32_16x16x32_bf16 v[204:207], v[172:175], v[188:191], v[212:215]
	v_cvt_pk_bf16_f32 v136, v224, v228
	v_cvt_pk_bf16_f32 v137, v225, v229
	v_mfma_f32_16x16x32_bf16 v[208:211], v[176:179], v[192:195], v[212:215]
	v_cvt_pk_bf16_f32 v138, v226, v230
	v_cvt_pk_bf16_f32 v139, v227, v231
	ds_write2_b32 v134, v136, v137 offset0:0 offset1:16
	ds_write2_b32 v134, v138, v139 offset0:32 offset1:48
	v_mfma_f32_16x16x16_bf16 v[66:69], v[92:93], v[122:123], v[212:215]
	v_fmac_f32_e32 v19, v232, v228
	v_fmac_f32_e32 v23, v220, v224
	v_fmac_f32_e32 v27, v233, v229
	v_fmac_f32_e32 v31, v221, v225
	v_mfma_f32_16x16x16_bf16 v[70:73], v[92:93], v[124:125], v[212:215]
	v_fmac_f32_e32 v35, v234, v230
	v_fmac_f32_e32 v39, v222, v226
	v_fmac_f32_e32 v43, v235, v231
	v_fmac_f32_e32 v47, v223, v227
	v_mfma_f32_16x16x16_bf16 v[74:77], v[92:93], v[126:127], v[212:215]
	v_fma_f32 v224, v216, v224, v19
	v_fma_f32 v228, v216, v228, v23
	v_fma_f32 v225, v217, v225, v27
	v_fma_f32 v229, v217, v229, v31
	v_mfma_f32_16x16x16_bf16 v[78:81], v[92:93], v[128:129], v[212:215]
	v_fma_f32 v226, v218, v226, v35
	v_fma_f32 v230, v218, v230, v39
	v_fma_f32 v227, v219, v227, v43
	v_fma_f32 v231, v219, v231, v47
	v_mfma_f32_16x16x32_bf16 v[204:207], v[180:183], v[196:199], v[204:207]
	v_cvt_pk_bf16_f32 v136, v224, v228
	v_cvt_pk_bf16_f32 v137, v225, v229
	v_mfma_f32_16x16x32_bf16 v[208:211], v[184:187], v[200:203], v[208:211]
	v_cvt_pk_bf16_f32 v138, v226, v230
	v_cvt_pk_bf16_f32 v139, v227, v231
	ds_write2_b32 v134, v136, v137 offset0:68 offset1:84
	ds_write2_b32 v134, v138, v139 offset0:100 offset1:116
	v_fmac_f32_e32 v20, v232, v228
	v_fmac_f32_e32 v24, v220, v224
	v_fmac_f32_e32 v28, v233, v229
	v_fmac_f32_e32 v32, v221, v225
	v_fmac_f32_e32 v36, v234, v230
	v_fmac_f32_e32 v40, v222, v226
	v_fmac_f32_e32 v44, v235, v231
	v_fmac_f32_e32 v48, v223, v227
	v_fma_f32 v224, v216, v224, v20
	v_fma_f32 v228, v216, v228, v24
	v_fma_f32 v225, v217, v225, v28
	v_fma_f32 v229, v217, v229, v32
	v_fma_f32 v226, v218, v226, v36
	v_fma_f32 v230, v218, v230, v40
	v_fma_f32 v227, v219, v227, v44
	v_fma_f32 v231, v219, v231, v48
	v_cvt_pk_bf16_f32 v136, v224, v228
	v_cvt_pk_bf16_f32 v137, v225, v229
	v_cvt_pk_bf16_f32 v138, v226, v230
	v_cvt_pk_bf16_f32 v139, v227, v231
	ds_write2_b32 v134, v136, v137 offset0:136 offset1:152
	ds_write2_b32 v134, v138, v139 offset0:168 offset1:184
	v_fmac_f32_e32 v21, v232, v228
	v_fmac_f32_e32 v25, v220, v224
	v_fmac_f32_e32 v29, v233, v229
	v_fmac_f32_e32 v33, v221, v225
	v_fmac_f32_e32 v37, v234, v230
	v_fmac_f32_e32 v41, v222, v226
	v_fmac_f32_e32 v45, v235, v231
	v_fmac_f32_e32 v49, v223, v227
	v_fma_f32 v224, v216, v224, v21
	v_fma_f32 v228, v216, v228, v25
	v_fma_f32 v225, v217, v225, v29
	v_fma_f32 v229, v217, v229, v33
	v_fma_f32 v226, v218, v226, v37
	v_fma_f32 v230, v218, v230, v41
	v_fma_f32 v227, v219, v227, v45
	v_fma_f32 v231, v219, v231, v49
	v_cvt_pk_bf16_f32 v136, v224, v228
	v_cvt_pk_bf16_f32 v137, v225, v229
	v_cvt_pk_bf16_f32 v138, v226, v230
	v_cvt_pk_bf16_f32 v139, v227, v231
	ds_write2_b32 v134, v136, v137 offset0:204 offset1:220
	ds_write2_b32 v134, v138, v139 offset0:236 offset1:252
	v_add_f32_e32 v204, v204, v208
	v_add_f32_e32 v205, v205, v209
	v_add_f32_e32 v206, v206, v210
	v_add_f32_e32 v207, v207, v211
	global_store_dwordx4 v[132:133], v[204:207], off
	v_lshl_add_u64 v[132:133], v[132:133], 0, s[88:89]
	s_waitcnt lgkmcnt(0)
	ds_read_b128 v[188:191], v135 offset:0
	ds_read_b128 v[192:195], v135 offset:64
	ds_read_b128 v[196:199], v135 offset:128
	ds_read_b128 v[200:203], v135 offset:192
	v_mfma_f32_16x16x16_bf16 v[18:21], v[94:95], v[114:115], v[212:215]
	v_fmac_f32_e32 v50, v232, v228
	v_fmac_f32_e32 v54, v220, v224
	v_fmac_f32_e32 v58, v233, v229
	v_fmac_f32_e32 v62, v221, v225
	v_mfma_f32_16x16x16_bf16 v[22:25], v[94:95], v[116:117], v[212:215]
	v_fmac_f32_e32 v66, v234, v230
	v_fmac_f32_e32 v70, v222, v226
	v_fmac_f32_e32 v74, v235, v231
	v_fmac_f32_e32 v78, v223, v227
	v_mfma_f32_16x16x16_bf16 v[26:29], v[94:95], v[118:119], v[212:215]
	v_fma_f32 v224, v216, v224, v50
	v_fma_f32 v228, v216, v228, v54
	v_fma_f32 v225, v217, v225, v58
	v_fma_f32 v229, v217, v229, v62
	v_mfma_f32_16x16x16_bf16 v[30:33], v[94:95], v[120:121], v[212:215]
	v_fma_f32 v226, v218, v226, v66
	v_fma_f32 v230, v218, v230, v70
	v_fma_f32 v227, v219, v227, v74
	v_fma_f32 v231, v219, v231, v78
	s_waitcnt lgkmcnt(0)
	v_mfma_f32_16x16x32_bf16 v[204:207], v[172:175], v[188:191], v[212:215]
	v_cvt_pk_bf16_f32 v136, v224, v228
	v_cvt_pk_bf16_f32 v137, v225, v229
	v_mfma_f32_16x16x32_bf16 v[208:211], v[176:179], v[192:195], v[212:215]
	v_cvt_pk_bf16_f32 v138, v226, v230
	v_cvt_pk_bf16_f32 v139, v227, v231
	ds_write2_b32 v134, v136, v137 offset0:0 offset1:16
	ds_write2_b32 v134, v138, v139 offset0:32 offset1:48
	v_mfma_f32_16x16x16_bf16 v[34:37], v[94:95], v[122:123], v[212:215]
	v_fmac_f32_e32 v51, v232, v228
	v_fmac_f32_e32 v55, v220, v224
	v_fmac_f32_e32 v59, v233, v229
	v_fmac_f32_e32 v63, v221, v225
	v_mfma_f32_16x16x16_bf16 v[38:41], v[94:95], v[124:125], v[212:215]
	v_fmac_f32_e32 v67, v234, v230
	v_fmac_f32_e32 v71, v222, v226
	v_fmac_f32_e32 v75, v235, v231
	v_fmac_f32_e32 v79, v223, v227
	v_mfma_f32_16x16x16_bf16 v[42:45], v[94:95], v[126:127], v[212:215]
	v_fma_f32 v224, v216, v224, v51
	v_fma_f32 v228, v216, v228, v55
	v_fma_f32 v225, v217, v225, v59
	v_fma_f32 v229, v217, v229, v63
	v_mfma_f32_16x16x16_bf16 v[46:49], v[94:95], v[128:129], v[212:215]
	v_fma_f32 v226, v218, v226, v67
	v_fma_f32 v230, v218, v230, v71
	v_fma_f32 v227, v219, v227, v75
	v_fma_f32 v231, v219, v231, v79
	v_mfma_f32_16x16x32_bf16 v[204:207], v[180:183], v[196:199], v[204:207]
	v_cvt_pk_bf16_f32 v136, v224, v228
	v_cvt_pk_bf16_f32 v137, v225, v229
	v_mfma_f32_16x16x32_bf16 v[208:211], v[184:187], v[200:203], v[208:211]
	v_cvt_pk_bf16_f32 v138, v226, v230
	v_cvt_pk_bf16_f32 v139, v227, v231
	ds_write2_b32 v134, v136, v137 offset0:68 offset1:84
	ds_write2_b32 v134, v138, v139 offset0:100 offset1:116
	v_fmac_f32_e32 v52, v232, v228
	v_fmac_f32_e32 v56, v220, v224
	v_fmac_f32_e32 v60, v233, v229
	v_fmac_f32_e32 v64, v221, v225
	v_fmac_f32_e32 v68, v234, v230
	v_fmac_f32_e32 v72, v222, v226
	v_fmac_f32_e32 v76, v235, v231
	v_fmac_f32_e32 v80, v223, v227
	v_fma_f32 v224, v216, v224, v52
	v_fma_f32 v228, v216, v228, v56
	v_fma_f32 v225, v217, v225, v60
	v_fma_f32 v229, v217, v229, v64
	v_fma_f32 v226, v218, v226, v68
	v_fma_f32 v230, v218, v230, v72
	v_fma_f32 v227, v219, v227, v76
	v_fma_f32 v231, v219, v231, v80
	v_cvt_pk_bf16_f32 v136, v224, v228
	v_cvt_pk_bf16_f32 v137, v225, v229
	v_cvt_pk_bf16_f32 v138, v226, v230
	v_cvt_pk_bf16_f32 v139, v227, v231
	ds_write2_b32 v134, v136, v137 offset0:136 offset1:152
	ds_write2_b32 v134, v138, v139 offset0:168 offset1:184
	v_fmac_f32_e32 v53, v232, v228
	v_fmac_f32_e32 v57, v220, v224
	v_fmac_f32_e32 v61, v233, v229
	v_fmac_f32_e32 v65, v221, v225
	v_fmac_f32_e32 v69, v234, v230
	v_fmac_f32_e32 v73, v222, v226
	v_fmac_f32_e32 v77, v235, v231
	v_fmac_f32_e32 v81, v223, v227
	v_fma_f32 v224, v216, v224, v53
	v_fma_f32 v228, v216, v228, v57
	v_fma_f32 v225, v217, v225, v61
	v_fma_f32 v229, v217, v229, v65
	v_fma_f32 v226, v218, v226, v69
	v_fma_f32 v230, v218, v230, v73
	v_fma_f32 v227, v219, v227, v77
	v_fma_f32 v231, v219, v231, v81
	v_cvt_pk_bf16_f32 v136, v224, v228
	v_cvt_pk_bf16_f32 v137, v225, v229
	v_cvt_pk_bf16_f32 v138, v226, v230
	v_cvt_pk_bf16_f32 v139, v227, v231
	ds_write2_b32 v134, v136, v137 offset0:204 offset1:220
	ds_write2_b32 v134, v138, v139 offset0:236 offset1:252
	v_add_f32_e32 v204, v204, v208
	v_add_f32_e32 v205, v205, v209
	v_add_f32_e32 v206, v206, v210
	v_add_f32_e32 v207, v207, v211
	global_store_dwordx4 v[132:133], v[204:207], off
	v_lshl_add_u64 v[132:133], v[132:133], 0, s[88:89]
	s_waitcnt lgkmcnt(0)
	ds_read_b128 v[188:191], v135 offset:0
	ds_read_b128 v[192:195], v135 offset:64
	ds_read_b128 v[196:199], v135 offset:128
	ds_read_b128 v[200:203], v135 offset:192
	v_mfma_f32_16x16x16_bf16 v[50:53], v[96:97], v[114:115], v[212:215]
	v_fmac_f32_e32 v18, v232, v228
	v_fmac_f32_e32 v22, v220, v224
	v_fmac_f32_e32 v26, v233, v229
	v_fmac_f32_e32 v30, v221, v225
	v_mfma_f32_16x16x16_bf16 v[54:57], v[96:97], v[116:117], v[212:215]
	v_fmac_f32_e32 v34, v234, v230
	v_fmac_f32_e32 v38, v222, v226
	v_fmac_f32_e32 v42, v235, v231
	v_fmac_f32_e32 v46, v223, v227
	v_mfma_f32_16x16x16_bf16 v[58:61], v[96:97], v[118:119], v[212:215]
	v_fma_f32 v224, v216, v224, v18
	v_fma_f32 v228, v216, v228, v22
	v_fma_f32 v225, v217, v225, v26
	v_fma_f32 v229, v217, v229, v30
	v_mfma_f32_16x16x16_bf16 v[62:65], v[96:97], v[120:121], v[212:215]
	v_fma_f32 v226, v218, v226, v34
	v_fma_f32 v230, v218, v230, v38
	v_fma_f32 v227, v219, v227, v42
	v_fma_f32 v231, v219, v231, v46
	s_waitcnt lgkmcnt(0)
	v_mfma_f32_16x16x32_bf16 v[204:207], v[172:175], v[188:191], v[212:215]
	v_cvt_pk_bf16_f32 v136, v224, v228
	v_cvt_pk_bf16_f32 v137, v225, v229
	v_mfma_f32_16x16x32_bf16 v[208:211], v[176:179], v[192:195], v[212:215]
	v_cvt_pk_bf16_f32 v138, v226, v230
	v_cvt_pk_bf16_f32 v139, v227, v231
	ds_write2_b32 v134, v136, v137 offset0:0 offset1:16
	ds_write2_b32 v134, v138, v139 offset0:32 offset1:48
	v_mfma_f32_16x16x16_bf16 v[66:69], v[96:97], v[122:123], v[212:215]
	v_fmac_f32_e32 v19, v232, v228
	v_fmac_f32_e32 v23, v220, v224
	v_fmac_f32_e32 v27, v233, v229
	v_fmac_f32_e32 v31, v221, v225
	v_mfma_f32_16x16x16_bf16 v[70:73], v[96:97], v[124:125], v[212:215]
	v_fmac_f32_e32 v35, v234, v230
	v_fmac_f32_e32 v39, v222, v226
	v_fmac_f32_e32 v43, v235, v231
	v_fmac_f32_e32 v47, v223, v227
	v_mfma_f32_16x16x16_bf16 v[74:77], v[96:97], v[126:127], v[212:215]
	v_fma_f32 v224, v216, v224, v19
	v_fma_f32 v228, v216, v228, v23
	v_fma_f32 v225, v217, v225, v27
	v_fma_f32 v229, v217, v229, v31
	v_mfma_f32_16x16x16_bf16 v[78:81], v[96:97], v[128:129], v[212:215]
	v_fma_f32 v226, v218, v226, v35
	v_fma_f32 v230, v218, v230, v39
	v_fma_f32 v227, v219, v227, v43
	v_fma_f32 v231, v219, v231, v47
	v_mfma_f32_16x16x32_bf16 v[204:207], v[180:183], v[196:199], v[204:207]
	v_cvt_pk_bf16_f32 v136, v224, v228
	v_cvt_pk_bf16_f32 v137, v225, v229
	v_mfma_f32_16x16x32_bf16 v[208:211], v[184:187], v[200:203], v[208:211]
	v_cvt_pk_bf16_f32 v138, v226, v230
	v_cvt_pk_bf16_f32 v139, v227, v231
	ds_write2_b32 v134, v136, v137 offset0:68 offset1:84
	ds_write2_b32 v134, v138, v139 offset0:100 offset1:116
	v_fmac_f32_e32 v20, v232, v228
	v_fmac_f32_e32 v24, v220, v224
	v_fmac_f32_e32 v28, v233, v229
	v_fmac_f32_e32 v32, v221, v225
	v_fmac_f32_e32 v36, v234, v230
	v_fmac_f32_e32 v40, v222, v226
	v_fmac_f32_e32 v44, v235, v231
	v_fmac_f32_e32 v48, v223, v227
	v_fma_f32 v224, v216, v224, v20
	v_fma_f32 v228, v216, v228, v24
	v_fma_f32 v225, v217, v225, v28
	v_fma_f32 v229, v217, v229, v32
	v_fma_f32 v226, v218, v226, v36
	v_fma_f32 v230, v218, v230, v40
	v_fma_f32 v227, v219, v227, v44
	v_fma_f32 v231, v219, v231, v48
	v_cvt_pk_bf16_f32 v136, v224, v228
	v_cvt_pk_bf16_f32 v137, v225, v229
	v_cvt_pk_bf16_f32 v138, v226, v230
	v_cvt_pk_bf16_f32 v139, v227, v231
	ds_write2_b32 v134, v136, v137 offset0:136 offset1:152
	ds_write2_b32 v134, v138, v139 offset0:168 offset1:184
	v_fmac_f32_e32 v21, v232, v228
	v_fmac_f32_e32 v25, v220, v224
	v_fmac_f32_e32 v29, v233, v229
	v_fmac_f32_e32 v33, v221, v225
	v_fmac_f32_e32 v37, v234, v230
	v_fmac_f32_e32 v41, v222, v226
	v_fmac_f32_e32 v45, v235, v231
	v_fmac_f32_e32 v49, v223, v227
	v_fma_f32 v224, v216, v224, v21
	v_fma_f32 v228, v216, v228, v25
	v_fma_f32 v225, v217, v225, v29
	v_fma_f32 v229, v217, v229, v33
	v_fma_f32 v226, v218, v226, v37
	v_fma_f32 v230, v218, v230, v41
	v_fma_f32 v227, v219, v227, v45
	v_fma_f32 v231, v219, v231, v49
	v_cvt_pk_bf16_f32 v136, v224, v228
	v_cvt_pk_bf16_f32 v137, v225, v229
	v_cvt_pk_bf16_f32 v138, v226, v230
	v_cvt_pk_bf16_f32 v139, v227, v231
	ds_write2_b32 v134, v136, v137 offset0:204 offset1:220
	ds_write2_b32 v134, v138, v139 offset0:236 offset1:252
	v_add_f32_e32 v204, v204, v208
	v_add_f32_e32 v205, v205, v209
	v_add_f32_e32 v206, v206, v210
	v_add_f32_e32 v207, v207, v211
	global_store_dwordx4 v[132:133], v[204:207], off
	v_lshl_add_u64 v[132:133], v[132:133], 0, s[88:89]
	s_waitcnt lgkmcnt(0)
	ds_read_b128 v[188:191], v135 offset:0
	ds_read_b128 v[192:195], v135 offset:64
	ds_read_b128 v[196:199], v135 offset:128
	ds_read_b128 v[200:203], v135 offset:192
	s_waitcnt vmcnt(14)
	v_mfma_f32_16x16x16_bf16 v[18:21], v[98:99], v[114:115], v[212:215]
	v_fmac_f32_e32 v50, v232, v228
	v_fmac_f32_e32 v54, v220, v224
	v_fmac_f32_e32 v58, v233, v229
	v_fmac_f32_e32 v62, v221, v225
	v_mfma_f32_16x16x16_bf16 v[22:25], v[98:99], v[116:117], v[212:215]
	v_fmac_f32_e32 v66, v234, v230
	v_fmac_f32_e32 v70, v222, v226
	v_fmac_f32_e32 v74, v235, v231
	v_fmac_f32_e32 v78, v223, v227
	v_mfma_f32_16x16x16_bf16 v[26:29], v[98:99], v[118:119], v[212:215]
	v_fma_f32 v224, v216, v224, v50
	v_fma_f32 v228, v216, v228, v54
	v_fma_f32 v225, v217, v225, v58
	v_fma_f32 v229, v217, v229, v62
	v_mfma_f32_16x16x16_bf16 v[30:33], v[98:99], v[120:121], v[212:215]
	v_fma_f32 v226, v218, v226, v66
	v_fma_f32 v230, v218, v230, v70
	v_fma_f32 v227, v219, v227, v74
	v_fma_f32 v231, v219, v231, v78
	s_waitcnt lgkmcnt(0)
	v_mfma_f32_16x16x32_bf16 v[204:207], v[172:175], v[188:191], v[212:215]
	v_cvt_pk_bf16_f32 v136, v224, v228
	v_cvt_pk_bf16_f32 v137, v225, v229
	v_mfma_f32_16x16x32_bf16 v[208:211], v[176:179], v[192:195], v[212:215]
	v_cvt_pk_bf16_f32 v138, v226, v230
	v_cvt_pk_bf16_f32 v139, v227, v231
	ds_write2_b32 v134, v136, v137 offset0:0 offset1:16
	ds_write2_b32 v134, v138, v139 offset0:32 offset1:48
	v_mfma_f32_16x16x16_bf16 v[34:37], v[98:99], v[122:123], v[212:215]
	v_fmac_f32_e32 v51, v232, v228
	v_fmac_f32_e32 v55, v220, v224
	v_fmac_f32_e32 v59, v233, v229
	v_fmac_f32_e32 v63, v221, v225
	v_mfma_f32_16x16x16_bf16 v[38:41], v[98:99], v[124:125], v[212:215]
	v_fmac_f32_e32 v67, v234, v230
	v_fmac_f32_e32 v71, v222, v226
	v_fmac_f32_e32 v75, v235, v231
	v_fmac_f32_e32 v79, v223, v227
	v_mfma_f32_16x16x16_bf16 v[42:45], v[98:99], v[126:127], v[212:215]
	v_fma_f32 v224, v216, v224, v51
	v_fma_f32 v228, v216, v228, v55
	v_fma_f32 v225, v217, v225, v59
	v_fma_f32 v229, v217, v229, v63
	v_mfma_f32_16x16x16_bf16 v[46:49], v[98:99], v[128:129], v[212:215]
	v_fma_f32 v226, v218, v226, v67
	v_fma_f32 v230, v218, v230, v71
	v_fma_f32 v227, v219, v227, v75
	v_fma_f32 v231, v219, v231, v79
	v_mfma_f32_16x16x32_bf16 v[204:207], v[180:183], v[196:199], v[204:207]
	v_cvt_pk_bf16_f32 v136, v224, v228
	v_cvt_pk_bf16_f32 v137, v225, v229
	v_mfma_f32_16x16x32_bf16 v[208:211], v[184:187], v[200:203], v[208:211]
	v_cvt_pk_bf16_f32 v138, v226, v230
	v_cvt_pk_bf16_f32 v139, v227, v231
	ds_write2_b32 v134, v136, v137 offset0:68 offset1:84
	ds_write2_b32 v134, v138, v139 offset0:100 offset1:116
	v_fmac_f32_e32 v52, v232, v228
	v_fmac_f32_e32 v56, v220, v224
	v_fmac_f32_e32 v60, v233, v229
	v_fmac_f32_e32 v64, v221, v225
	v_fmac_f32_e32 v68, v234, v230
	v_fmac_f32_e32 v72, v222, v226
	v_fmac_f32_e32 v76, v235, v231
	v_fmac_f32_e32 v80, v223, v227
	v_fma_f32 v224, v216, v224, v52
	v_fma_f32 v228, v216, v228, v56
	v_fma_f32 v225, v217, v225, v60
	v_fma_f32 v229, v217, v229, v64
	v_fma_f32 v226, v218, v226, v68
	v_fma_f32 v230, v218, v230, v72
	v_fma_f32 v227, v219, v227, v76
	v_fma_f32 v231, v219, v231, v80
	v_cvt_pk_bf16_f32 v136, v224, v228
	v_cvt_pk_bf16_f32 v137, v225, v229
	v_cvt_pk_bf16_f32 v138, v226, v230
	v_cvt_pk_bf16_f32 v139, v227, v231
	ds_write2_b32 v134, v136, v137 offset0:136 offset1:152
	ds_write2_b32 v134, v138, v139 offset0:168 offset1:184
	v_fmac_f32_e32 v53, v232, v228
	v_fmac_f32_e32 v57, v220, v224
	v_fmac_f32_e32 v61, v233, v229
	v_fmac_f32_e32 v65, v221, v225
	v_fmac_f32_e32 v69, v234, v230
	v_fmac_f32_e32 v73, v222, v226
	v_fmac_f32_e32 v77, v235, v231
	v_fmac_f32_e32 v81, v223, v227
	v_fma_f32 v224, v216, v224, v53
	v_fma_f32 v228, v216, v228, v57
	v_fma_f32 v225, v217, v225, v61
	v_fma_f32 v229, v217, v229, v65
	v_fma_f32 v226, v218, v226, v69
	v_fma_f32 v230, v218, v230, v73
	v_fma_f32 v227, v219, v227, v77
	v_fma_f32 v231, v219, v231, v81
	v_cvt_pk_bf16_f32 v136, v224, v228
	v_cvt_pk_bf16_f32 v137, v225, v229
	v_cvt_pk_bf16_f32 v138, v226, v230
	v_cvt_pk_bf16_f32 v139, v227, v231
	ds_write2_b32 v134, v136, v137 offset0:204 offset1:220
	ds_write2_b32 v134, v138, v139 offset0:236 offset1:252
	v_add_f32_e32 v204, v204, v208
	v_add_f32_e32 v205, v205, v209
	v_add_f32_e32 v206, v206, v210
	v_add_f32_e32 v207, v207, v211
	global_store_dwordx4 v[132:133], v[204:207], off
	v_lshl_add_u64 v[132:133], v[132:133], 0, s[88:89]
	s_waitcnt lgkmcnt(0)
	ds_read_b128 v[188:191], v135 offset:0
	ds_read_b128 v[192:195], v135 offset:64
	ds_read_b128 v[196:199], v135 offset:128
	ds_read_b128 v[200:203], v135 offset:192
	global_load_dwordx2 v[90:91], v[130:131], off
	v_lshl_add_u64 v[130:131], v[130:131], 0, s[86:87]
	global_load_dwordx2 v[92:93], v[130:131], off
	v_lshl_add_u64 v[130:131], v[130:131], 0, s[86:87]
	global_load_dwordx2 v[94:95], v[130:131], off
	v_lshl_add_u64 v[130:131], v[130:131], 0, s[86:87]
	global_load_dwordx2 v[96:97], v[130:131], off
	v_lshl_add_u64 v[130:131], v[130:131], 0, s[86:87]
	v_mfma_f32_16x16x16_bf16 v[50:53], v[100:101], v[114:115], v[212:215]
	v_fmac_f32_e32 v18, v232, v228
	v_fmac_f32_e32 v22, v220, v224
	v_fmac_f32_e32 v26, v233, v229
	v_fmac_f32_e32 v30, v221, v225
	v_mfma_f32_16x16x16_bf16 v[54:57], v[100:101], v[116:117], v[212:215]
	v_fmac_f32_e32 v34, v234, v230
	v_fmac_f32_e32 v38, v222, v226
	v_fmac_f32_e32 v42, v235, v231
	v_fmac_f32_e32 v46, v223, v227
	v_mfma_f32_16x16x16_bf16 v[58:61], v[100:101], v[118:119], v[212:215]
	v_fma_f32 v224, v216, v224, v18
	v_fma_f32 v228, v216, v228, v22
	v_fma_f32 v225, v217, v225, v26
	v_fma_f32 v229, v217, v229, v30
	v_mfma_f32_16x16x16_bf16 v[62:65], v[100:101], v[120:121], v[212:215]
	v_fma_f32 v226, v218, v226, v34
	v_fma_f32 v230, v218, v230, v38
	v_fma_f32 v227, v219, v227, v42
	v_fma_f32 v231, v219, v231, v46
	s_waitcnt lgkmcnt(0)
	v_mfma_f32_16x16x32_bf16 v[204:207], v[172:175], v[188:191], v[212:215]
	v_cvt_pk_bf16_f32 v136, v224, v228
	v_cvt_pk_bf16_f32 v137, v225, v229
	v_mfma_f32_16x16x32_bf16 v[208:211], v[176:179], v[192:195], v[212:215]
	v_cvt_pk_bf16_f32 v138, v226, v230
	v_cvt_pk_bf16_f32 v139, v227, v231
	ds_write2_b32 v134, v136, v137 offset0:0 offset1:16
	ds_write2_b32 v134, v138, v139 offset0:32 offset1:48
	v_mfma_f32_16x16x16_bf16 v[66:69], v[100:101], v[122:123], v[212:215]
	v_fmac_f32_e32 v19, v232, v228
	v_fmac_f32_e32 v23, v220, v224
	v_fmac_f32_e32 v27, v233, v229
	v_fmac_f32_e32 v31, v221, v225
	v_mfma_f32_16x16x16_bf16 v[70:73], v[100:101], v[124:125], v[212:215]
	v_fmac_f32_e32 v35, v234, v230
	v_fmac_f32_e32 v39, v222, v226
	v_fmac_f32_e32 v43, v235, v231
	v_fmac_f32_e32 v47, v223, v227
	v_mfma_f32_16x16x16_bf16 v[74:77], v[100:101], v[126:127], v[212:215]
	v_fma_f32 v224, v216, v224, v19
	v_fma_f32 v228, v216, v228, v23
	v_fma_f32 v225, v217, v225, v27
	v_fma_f32 v229, v217, v229, v31
	v_mfma_f32_16x16x16_bf16 v[78:81], v[100:101], v[128:129], v[212:215]
	v_fma_f32 v226, v218, v226, v35
	v_fma_f32 v230, v218, v230, v39
	v_fma_f32 v227, v219, v227, v43
	v_fma_f32 v231, v219, v231, v47
	v_mfma_f32_16x16x32_bf16 v[204:207], v[180:183], v[196:199], v[204:207]
	v_cvt_pk_bf16_f32 v136, v224, v228
	v_cvt_pk_bf16_f32 v137, v225, v229
	v_mfma_f32_16x16x32_bf16 v[208:211], v[184:187], v[200:203], v[208:211]
	v_cvt_pk_bf16_f32 v138, v226, v230
	v_cvt_pk_bf16_f32 v139, v227, v231
	ds_write2_b32 v134, v136, v137 offset0:68 offset1:84
	ds_write2_b32 v134, v138, v139 offset0:100 offset1:116
	v_fmac_f32_e32 v20, v232, v228
	v_fmac_f32_e32 v24, v220, v224
	v_fmac_f32_e32 v28, v233, v229
	v_fmac_f32_e32 v32, v221, v225
	v_fmac_f32_e32 v36, v234, v230
	v_fmac_f32_e32 v40, v222, v226
	v_fmac_f32_e32 v44, v235, v231
	v_fmac_f32_e32 v48, v223, v227
	v_fma_f32 v224, v216, v224, v20
	v_fma_f32 v228, v216, v228, v24
	v_fma_f32 v225, v217, v225, v28
	v_fma_f32 v229, v217, v229, v32
	v_fma_f32 v226, v218, v226, v36
	v_fma_f32 v230, v218, v230, v40
	v_fma_f32 v227, v219, v227, v44
	v_fma_f32 v231, v219, v231, v48
	v_cvt_pk_bf16_f32 v136, v224, v228
	v_cvt_pk_bf16_f32 v137, v225, v229
	v_cvt_pk_bf16_f32 v138, v226, v230
	v_cvt_pk_bf16_f32 v139, v227, v231
	ds_write2_b32 v134, v136, v137 offset0:136 offset1:152
	ds_write2_b32 v134, v138, v139 offset0:168 offset1:184
	v_fmac_f32_e32 v21, v232, v228
	v_fmac_f32_e32 v25, v220, v224
	v_fmac_f32_e32 v29, v233, v229
	v_fmac_f32_e32 v33, v221, v225
	v_fmac_f32_e32 v37, v234, v230
	v_fmac_f32_e32 v41, v222, v226
	v_fmac_f32_e32 v45, v235, v231
	v_fmac_f32_e32 v49, v223, v227
	v_fma_f32 v224, v216, v224, v21
	v_fma_f32 v228, v216, v228, v25
	v_fma_f32 v225, v217, v225, v29
	v_fma_f32 v229, v217, v229, v33
	v_fma_f32 v226, v218, v226, v37
	v_fma_f32 v230, v218, v230, v41
	v_fma_f32 v227, v219, v227, v45
	v_fma_f32 v231, v219, v231, v49
	v_cvt_pk_bf16_f32 v136, v224, v228
	v_cvt_pk_bf16_f32 v137, v225, v229
	v_cvt_pk_bf16_f32 v138, v226, v230
	v_cvt_pk_bf16_f32 v139, v227, v231
	ds_write2_b32 v134, v136, v137 offset0:204 offset1:220
	ds_write2_b32 v134, v138, v139 offset0:236 offset1:252
	v_add_f32_e32 v204, v204, v208
	v_add_f32_e32 v205, v205, v209
	v_add_f32_e32 v206, v206, v210
	v_add_f32_e32 v207, v207, v211
	global_store_dwordx4 v[132:133], v[204:207], off
	v_lshl_add_u64 v[132:133], v[132:133], 0, s[88:89]
	s_waitcnt lgkmcnt(0)
	ds_read_b128 v[188:191], v135 offset:0
	ds_read_b128 v[192:195], v135 offset:64
	ds_read_b128 v[196:199], v135 offset:128
	ds_read_b128 v[200:203], v135 offset:192
	v_mfma_f32_16x16x16_bf16 v[18:21], v[102:103], v[114:115], v[212:215]
	v_fmac_f32_e32 v50, v232, v228
	v_fmac_f32_e32 v54, v220, v224
	v_fmac_f32_e32 v58, v233, v229
	v_fmac_f32_e32 v62, v221, v225
	v_mfma_f32_16x16x16_bf16 v[22:25], v[102:103], v[116:117], v[212:215]
	v_fmac_f32_e32 v66, v234, v230
	v_fmac_f32_e32 v70, v222, v226
	v_fmac_f32_e32 v74, v235, v231
	v_fmac_f32_e32 v78, v223, v227
	v_mfma_f32_16x16x16_bf16 v[26:29], v[102:103], v[118:119], v[212:215]
	v_fma_f32 v224, v216, v224, v50
	v_fma_f32 v228, v216, v228, v54
	v_fma_f32 v225, v217, v225, v58
	v_fma_f32 v229, v217, v229, v62
	v_mfma_f32_16x16x16_bf16 v[30:33], v[102:103], v[120:121], v[212:215]
	v_fma_f32 v226, v218, v226, v66
	v_fma_f32 v230, v218, v230, v70
	v_fma_f32 v227, v219, v227, v74
	v_fma_f32 v231, v219, v231, v78
	s_waitcnt lgkmcnt(0)
	v_mfma_f32_16x16x32_bf16 v[204:207], v[172:175], v[188:191], v[212:215]
	v_cvt_pk_bf16_f32 v136, v224, v228
	v_cvt_pk_bf16_f32 v137, v225, v229
	v_mfma_f32_16x16x32_bf16 v[208:211], v[176:179], v[192:195], v[212:215]
	v_cvt_pk_bf16_f32 v138, v226, v230
	v_cvt_pk_bf16_f32 v139, v227, v231
	ds_write2_b32 v134, v136, v137 offset0:0 offset1:16
	ds_write2_b32 v134, v138, v139 offset0:32 offset1:48
	v_mfma_f32_16x16x16_bf16 v[34:37], v[102:103], v[122:123], v[212:215]
	v_fmac_f32_e32 v51, v232, v228
	v_fmac_f32_e32 v55, v220, v224
	v_fmac_f32_e32 v59, v233, v229
	v_fmac_f32_e32 v63, v221, v225
	v_mfma_f32_16x16x16_bf16 v[38:41], v[102:103], v[124:125], v[212:215]
	v_fmac_f32_e32 v67, v234, v230
	v_fmac_f32_e32 v71, v222, v226
	v_fmac_f32_e32 v75, v235, v231
	v_fmac_f32_e32 v79, v223, v227
	v_mfma_f32_16x16x16_bf16 v[42:45], v[102:103], v[126:127], v[212:215]
	v_fma_f32 v224, v216, v224, v51
	v_fma_f32 v228, v216, v228, v55
	v_fma_f32 v225, v217, v225, v59
	v_fma_f32 v229, v217, v229, v63
	v_mfma_f32_16x16x16_bf16 v[46:49], v[102:103], v[128:129], v[212:215]
	v_fma_f32 v226, v218, v226, v67
	v_fma_f32 v230, v218, v230, v71
	v_fma_f32 v227, v219, v227, v75
	v_fma_f32 v231, v219, v231, v79
	v_mfma_f32_16x16x32_bf16 v[204:207], v[180:183], v[196:199], v[204:207]
	v_cvt_pk_bf16_f32 v136, v224, v228
	v_cvt_pk_bf16_f32 v137, v225, v229
	v_mfma_f32_16x16x32_bf16 v[208:211], v[184:187], v[200:203], v[208:211]
	v_cvt_pk_bf16_f32 v138, v226, v230
	v_cvt_pk_bf16_f32 v139, v227, v231
	ds_write2_b32 v134, v136, v137 offset0:68 offset1:84
	ds_write2_b32 v134, v138, v139 offset0:100 offset1:116
	v_fmac_f32_e32 v52, v232, v228
	v_fmac_f32_e32 v56, v220, v224
	v_fmac_f32_e32 v60, v233, v229
	v_fmac_f32_e32 v64, v221, v225
	v_fmac_f32_e32 v68, v234, v230
	v_fmac_f32_e32 v72, v222, v226
	v_fmac_f32_e32 v76, v235, v231
	v_fmac_f32_e32 v80, v223, v227
	v_fma_f32 v224, v216, v224, v52
	v_fma_f32 v228, v216, v228, v56
	v_fma_f32 v225, v217, v225, v60
	v_fma_f32 v229, v217, v229, v64
	v_fma_f32 v226, v218, v226, v68
	v_fma_f32 v230, v218, v230, v72
	v_fma_f32 v227, v219, v227, v76
	v_fma_f32 v231, v219, v231, v80
	v_cvt_pk_bf16_f32 v136, v224, v228
	v_cvt_pk_bf16_f32 v137, v225, v229
	v_cvt_pk_bf16_f32 v138, v226, v230
	v_cvt_pk_bf16_f32 v139, v227, v231
	ds_write2_b32 v134, v136, v137 offset0:136 offset1:152
	ds_write2_b32 v134, v138, v139 offset0:168 offset1:184
	v_fmac_f32_e32 v53, v232, v228
	v_fmac_f32_e32 v57, v220, v224
	v_fmac_f32_e32 v61, v233, v229
	v_fmac_f32_e32 v65, v221, v225
	v_fmac_f32_e32 v69, v234, v230
	v_fmac_f32_e32 v73, v222, v226
	v_fmac_f32_e32 v77, v235, v231
	v_fmac_f32_e32 v81, v223, v227
	v_fma_f32 v224, v216, v224, v53
	v_fma_f32 v228, v216, v228, v57
	v_fma_f32 v225, v217, v225, v61
	v_fma_f32 v229, v217, v229, v65
	v_fma_f32 v226, v218, v226, v69
	v_fma_f32 v230, v218, v230, v73
	v_fma_f32 v227, v219, v227, v77
	v_fma_f32 v231, v219, v231, v81
	v_cvt_pk_bf16_f32 v136, v224, v228
	v_cvt_pk_bf16_f32 v137, v225, v229
	v_cvt_pk_bf16_f32 v138, v226, v230
	v_cvt_pk_bf16_f32 v139, v227, v231
	ds_write2_b32 v134, v136, v137 offset0:204 offset1:220
	ds_write2_b32 v134, v138, v139 offset0:236 offset1:252
	v_add_f32_e32 v204, v204, v208
	v_add_f32_e32 v205, v205, v209
	v_add_f32_e32 v206, v206, v210
	v_add_f32_e32 v207, v207, v211
	global_store_dwordx4 v[132:133], v[204:207], off
	v_lshl_add_u64 v[132:133], v[132:133], 0, s[88:89]
	s_waitcnt lgkmcnt(0)
	ds_read_b128 v[188:191], v135 offset:0
	ds_read_b128 v[192:195], v135 offset:64
	ds_read_b128 v[196:199], v135 offset:128
	ds_read_b128 v[200:203], v135 offset:192
	v_mfma_f32_16x16x16_bf16 v[50:53], v[104:105], v[114:115], v[212:215]
	v_fmac_f32_e32 v18, v232, v228
	v_fmac_f32_e32 v22, v220, v224
	v_fmac_f32_e32 v26, v233, v229
	v_fmac_f32_e32 v30, v221, v225
	v_mfma_f32_16x16x16_bf16 v[54:57], v[104:105], v[116:117], v[212:215]
	v_fmac_f32_e32 v34, v234, v230
	v_fmac_f32_e32 v38, v222, v226
	v_fmac_f32_e32 v42, v235, v231
	v_fmac_f32_e32 v46, v223, v227
	v_mfma_f32_16x16x16_bf16 v[58:61], v[104:105], v[118:119], v[212:215]
	v_fma_f32 v224, v216, v224, v18
	v_fma_f32 v228, v216, v228, v22
	v_fma_f32 v225, v217, v225, v26
	v_fma_f32 v229, v217, v229, v30
	v_mfma_f32_16x16x16_bf16 v[62:65], v[104:105], v[120:121], v[212:215]
	v_fma_f32 v226, v218, v226, v34
	v_fma_f32 v230, v218, v230, v38
	v_fma_f32 v227, v219, v227, v42
	v_fma_f32 v231, v219, v231, v46
	s_waitcnt lgkmcnt(0)
	v_mfma_f32_16x16x32_bf16 v[204:207], v[172:175], v[188:191], v[212:215]
	v_cvt_pk_bf16_f32 v136, v224, v228
	v_cvt_pk_bf16_f32 v137, v225, v229
	v_mfma_f32_16x16x32_bf16 v[208:211], v[176:179], v[192:195], v[212:215]
	v_cvt_pk_bf16_f32 v138, v226, v230
	v_cvt_pk_bf16_f32 v139, v227, v231
	ds_write2_b32 v134, v136, v137 offset0:0 offset1:16
	ds_write2_b32 v134, v138, v139 offset0:32 offset1:48
	v_mfma_f32_16x16x16_bf16 v[66:69], v[104:105], v[122:123], v[212:215]
	v_fmac_f32_e32 v19, v232, v228
	v_fmac_f32_e32 v23, v220, v224
	v_fmac_f32_e32 v27, v233, v229
	v_fmac_f32_e32 v31, v221, v225
	v_mfma_f32_16x16x16_bf16 v[70:73], v[104:105], v[124:125], v[212:215]
	v_fmac_f32_e32 v35, v234, v230
	v_fmac_f32_e32 v39, v222, v226
	v_fmac_f32_e32 v43, v235, v231
	v_fmac_f32_e32 v47, v223, v227
	v_mfma_f32_16x16x16_bf16 v[74:77], v[104:105], v[126:127], v[212:215]
	v_fma_f32 v224, v216, v224, v19
	v_fma_f32 v228, v216, v228, v23
	v_fma_f32 v225, v217, v225, v27
	v_fma_f32 v229, v217, v229, v31
	v_mfma_f32_16x16x16_bf16 v[78:81], v[104:105], v[128:129], v[212:215]
	v_fma_f32 v226, v218, v226, v35
	v_fma_f32 v230, v218, v230, v39
	v_fma_f32 v227, v219, v227, v43
	v_fma_f32 v231, v219, v231, v47
	v_mfma_f32_16x16x32_bf16 v[204:207], v[180:183], v[196:199], v[204:207]
	v_cvt_pk_bf16_f32 v136, v224, v228
	v_cvt_pk_bf16_f32 v137, v225, v229
	v_mfma_f32_16x16x32_bf16 v[208:211], v[184:187], v[200:203], v[208:211]
	v_cvt_pk_bf16_f32 v138, v226, v230
	v_cvt_pk_bf16_f32 v139, v227, v231
	ds_write2_b32 v134, v136, v137 offset0:68 offset1:84
	ds_write2_b32 v134, v138, v139 offset0:100 offset1:116
	v_fmac_f32_e32 v20, v232, v228
	v_fmac_f32_e32 v24, v220, v224
	v_fmac_f32_e32 v28, v233, v229
	v_fmac_f32_e32 v32, v221, v225
	v_fmac_f32_e32 v36, v234, v230
	v_fmac_f32_e32 v40, v222, v226
	v_fmac_f32_e32 v44, v235, v231
	v_fmac_f32_e32 v48, v223, v227
	v_fma_f32 v224, v216, v224, v20
	v_fma_f32 v228, v216, v228, v24
	v_fma_f32 v225, v217, v225, v28
	v_fma_f32 v229, v217, v229, v32
	v_fma_f32 v226, v218, v226, v36
	v_fma_f32 v230, v218, v230, v40
	v_fma_f32 v227, v219, v227, v44
	v_fma_f32 v231, v219, v231, v48
	v_cvt_pk_bf16_f32 v136, v224, v228
	v_cvt_pk_bf16_f32 v137, v225, v229
	v_cvt_pk_bf16_f32 v138, v226, v230
	v_cvt_pk_bf16_f32 v139, v227, v231
	ds_write2_b32 v134, v136, v137 offset0:136 offset1:152
	ds_write2_b32 v134, v138, v139 offset0:168 offset1:184
	v_fmac_f32_e32 v21, v232, v228
	v_fmac_f32_e32 v25, v220, v224
	v_fmac_f32_e32 v29, v233, v229
	v_fmac_f32_e32 v33, v221, v225
	v_fmac_f32_e32 v37, v234, v230
	v_fmac_f32_e32 v41, v222, v226
	v_fmac_f32_e32 v45, v235, v231
	v_fmac_f32_e32 v49, v223, v227
	v_fma_f32 v224, v216, v224, v21
	v_fma_f32 v228, v216, v228, v25
	v_fma_f32 v225, v217, v225, v29
	v_fma_f32 v229, v217, v229, v33
	v_fma_f32 v226, v218, v226, v37
	v_fma_f32 v230, v218, v230, v41
	v_fma_f32 v227, v219, v227, v45
	v_fma_f32 v231, v219, v231, v49
	v_cvt_pk_bf16_f32 v136, v224, v228
	v_cvt_pk_bf16_f32 v137, v225, v229
	v_cvt_pk_bf16_f32 v138, v226, v230
	v_cvt_pk_bf16_f32 v139, v227, v231
	ds_write2_b32 v134, v136, v137 offset0:204 offset1:220
	ds_write2_b32 v134, v138, v139 offset0:236 offset1:252
	v_add_f32_e32 v204, v204, v208
	v_add_f32_e32 v205, v205, v209
	v_add_f32_e32 v206, v206, v210
	v_add_f32_e32 v207, v207, v211
	global_store_dwordx4 v[132:133], v[204:207], off
	v_lshl_add_u64 v[132:133], v[132:133], 0, s[88:89]
	s_waitcnt lgkmcnt(0)
	ds_read_b128 v[188:191], v135 offset:0
	ds_read_b128 v[192:195], v135 offset:64
	ds_read_b128 v[196:199], v135 offset:128
	ds_read_b128 v[200:203], v135 offset:192
	s_waitcnt vmcnt(14)
	v_mfma_f32_16x16x16_bf16 v[18:21], v[106:107], v[114:115], v[212:215]
	v_fmac_f32_e32 v50, v232, v228
	v_fmac_f32_e32 v54, v220, v224
	v_fmac_f32_e32 v58, v233, v229
	v_fmac_f32_e32 v62, v221, v225
	v_mfma_f32_16x16x16_bf16 v[22:25], v[106:107], v[116:117], v[212:215]
	v_fmac_f32_e32 v66, v234, v230
	v_fmac_f32_e32 v70, v222, v226
	v_fmac_f32_e32 v74, v235, v231
	v_fmac_f32_e32 v78, v223, v227
	v_mfma_f32_16x16x16_bf16 v[26:29], v[106:107], v[118:119], v[212:215]
	v_fma_f32 v224, v216, v224, v50
	v_fma_f32 v228, v216, v228, v54
	v_fma_f32 v225, v217, v225, v58
	v_fma_f32 v229, v217, v229, v62
	v_mfma_f32_16x16x16_bf16 v[30:33], v[106:107], v[120:121], v[212:215]
	v_fma_f32 v226, v218, v226, v66
	v_fma_f32 v230, v218, v230, v70
	v_fma_f32 v227, v219, v227, v74
	v_fma_f32 v231, v219, v231, v78
	s_waitcnt lgkmcnt(0)
	v_mfma_f32_16x16x32_bf16 v[204:207], v[172:175], v[188:191], v[212:215]
	v_cvt_pk_bf16_f32 v136, v224, v228
	v_cvt_pk_bf16_f32 v137, v225, v229
	v_mfma_f32_16x16x32_bf16 v[208:211], v[176:179], v[192:195], v[212:215]
	v_cvt_pk_bf16_f32 v138, v226, v230
	v_cvt_pk_bf16_f32 v139, v227, v231
	ds_write2_b32 v134, v136, v137 offset0:0 offset1:16
	ds_write2_b32 v134, v138, v139 offset0:32 offset1:48
	v_mfma_f32_16x16x16_bf16 v[34:37], v[106:107], v[122:123], v[212:215]
	v_fmac_f32_e32 v51, v232, v228
	v_fmac_f32_e32 v55, v220, v224
	v_fmac_f32_e32 v59, v233, v229
	v_fmac_f32_e32 v63, v221, v225
	v_mfma_f32_16x16x16_bf16 v[38:41], v[106:107], v[124:125], v[212:215]
	v_fmac_f32_e32 v67, v234, v230
	v_fmac_f32_e32 v71, v222, v226
	v_fmac_f32_e32 v75, v235, v231
	v_fmac_f32_e32 v79, v223, v227
	v_mfma_f32_16x16x16_bf16 v[42:45], v[106:107], v[126:127], v[212:215]
	v_fma_f32 v224, v216, v224, v51
	v_fma_f32 v228, v216, v228, v55
	v_fma_f32 v225, v217, v225, v59
	v_fma_f32 v229, v217, v229, v63
	v_mfma_f32_16x16x16_bf16 v[46:49], v[106:107], v[128:129], v[212:215]
	v_fma_f32 v226, v218, v226, v67
	v_fma_f32 v230, v218, v230, v71
	v_fma_f32 v227, v219, v227, v75
	v_fma_f32 v231, v219, v231, v79
	v_mfma_f32_16x16x32_bf16 v[204:207], v[180:183], v[196:199], v[204:207]
	v_cvt_pk_bf16_f32 v136, v224, v228
	v_cvt_pk_bf16_f32 v137, v225, v229
	v_mfma_f32_16x16x32_bf16 v[208:211], v[184:187], v[200:203], v[208:211]
	v_cvt_pk_bf16_f32 v138, v226, v230
	v_cvt_pk_bf16_f32 v139, v227, v231
	ds_write2_b32 v134, v136, v137 offset0:68 offset1:84
	ds_write2_b32 v134, v138, v139 offset0:100 offset1:116
	v_fmac_f32_e32 v52, v232, v228
	v_fmac_f32_e32 v56, v220, v224
	v_fmac_f32_e32 v60, v233, v229
	v_fmac_f32_e32 v64, v221, v225
	v_fmac_f32_e32 v68, v234, v230
	v_fmac_f32_e32 v72, v222, v226
	v_fmac_f32_e32 v76, v235, v231
	v_fmac_f32_e32 v80, v223, v227
	v_fma_f32 v224, v216, v224, v52
	v_fma_f32 v228, v216, v228, v56
	v_fma_f32 v225, v217, v225, v60
	v_fma_f32 v229, v217, v229, v64
	v_fma_f32 v226, v218, v226, v68
	v_fma_f32 v230, v218, v230, v72
	v_fma_f32 v227, v219, v227, v76
	v_fma_f32 v231, v219, v231, v80
	v_cvt_pk_bf16_f32 v136, v224, v228
	v_cvt_pk_bf16_f32 v137, v225, v229
	v_cvt_pk_bf16_f32 v138, v226, v230
	v_cvt_pk_bf16_f32 v139, v227, v231
	ds_write2_b32 v134, v136, v137 offset0:136 offset1:152
	ds_write2_b32 v134, v138, v139 offset0:168 offset1:184
	v_fmac_f32_e32 v53, v232, v228
	v_fmac_f32_e32 v57, v220, v224
	v_fmac_f32_e32 v61, v233, v229
	v_fmac_f32_e32 v65, v221, v225
	v_fmac_f32_e32 v69, v234, v230
	v_fmac_f32_e32 v73, v222, v226
	v_fmac_f32_e32 v77, v235, v231
	v_fmac_f32_e32 v81, v223, v227
	v_fma_f32 v224, v216, v224, v53
	v_fma_f32 v228, v216, v228, v57
	v_fma_f32 v225, v217, v225, v61
	v_fma_f32 v229, v217, v229, v65
	v_fma_f32 v226, v218, v226, v69
	v_fma_f32 v230, v218, v230, v73
	v_fma_f32 v227, v219, v227, v77
	v_fma_f32 v231, v219, v231, v81
	v_cvt_pk_bf16_f32 v136, v224, v228
	v_cvt_pk_bf16_f32 v137, v225, v229
	v_cvt_pk_bf16_f32 v138, v226, v230
	v_cvt_pk_bf16_f32 v139, v227, v231
	ds_write2_b32 v134, v136, v137 offset0:204 offset1:220
	ds_write2_b32 v134, v138, v139 offset0:236 offset1:252
	v_add_f32_e32 v204, v204, v208
	v_add_f32_e32 v205, v205, v209
	v_add_f32_e32 v206, v206, v210
	v_add_f32_e32 v207, v207, v211
	global_store_dwordx4 v[132:133], v[204:207], off
	v_lshl_add_u64 v[132:133], v[132:133], 0, s[88:89]
	s_waitcnt lgkmcnt(0)
	ds_read_b128 v[188:191], v135 offset:0
	ds_read_b128 v[192:195], v135 offset:64
	ds_read_b128 v[196:199], v135 offset:128
	ds_read_b128 v[200:203], v135 offset:192
	global_load_dwordx2 v[98:99], v[130:131], off
	v_lshl_add_u64 v[130:131], v[130:131], 0, s[86:87]
	global_load_dwordx2 v[100:101], v[130:131], off
	v_lshl_add_u64 v[130:131], v[130:131], 0, s[86:87]
	global_load_dwordx2 v[102:103], v[130:131], off
	v_lshl_add_u64 v[130:131], v[130:131], 0, s[86:87]
	global_load_dwordx2 v[104:105], v[130:131], off
	v_lshl_add_u64 v[130:131], v[130:131], 0, s[86:87]
	v_mfma_f32_16x16x16_bf16 v[50:53], v[108:109], v[114:115], v[212:215]
	v_fmac_f32_e32 v18, v232, v228
	v_fmac_f32_e32 v22, v220, v224
	v_fmac_f32_e32 v26, v233, v229
	v_fmac_f32_e32 v30, v221, v225
	v_mfma_f32_16x16x16_bf16 v[54:57], v[108:109], v[116:117], v[212:215]
	v_fmac_f32_e32 v34, v234, v230
	v_fmac_f32_e32 v38, v222, v226
	v_fmac_f32_e32 v42, v235, v231
	v_fmac_f32_e32 v46, v223, v227
	v_mfma_f32_16x16x16_bf16 v[58:61], v[108:109], v[118:119], v[212:215]
	v_fma_f32 v224, v216, v224, v18
	v_fma_f32 v228, v216, v228, v22
	v_fma_f32 v225, v217, v225, v26
	v_fma_f32 v229, v217, v229, v30
	v_mfma_f32_16x16x16_bf16 v[62:65], v[108:109], v[120:121], v[212:215]
	v_fma_f32 v226, v218, v226, v34
	v_fma_f32 v230, v218, v230, v38
	v_fma_f32 v227, v219, v227, v42
	v_fma_f32 v231, v219, v231, v46
	s_waitcnt lgkmcnt(0)
	v_mfma_f32_16x16x32_bf16 v[204:207], v[172:175], v[188:191], v[212:215]
	v_cvt_pk_bf16_f32 v136, v224, v228
	v_cvt_pk_bf16_f32 v137, v225, v229
	v_mfma_f32_16x16x32_bf16 v[208:211], v[176:179], v[192:195], v[212:215]
	v_cvt_pk_bf16_f32 v138, v226, v230
	v_cvt_pk_bf16_f32 v139, v227, v231
	ds_write2_b32 v134, v136, v137 offset0:0 offset1:16
	ds_write2_b32 v134, v138, v139 offset0:32 offset1:48
	v_mfma_f32_16x16x16_bf16 v[66:69], v[108:109], v[122:123], v[212:215]
	v_fmac_f32_e32 v19, v232, v228
	v_fmac_f32_e32 v23, v220, v224
	v_fmac_f32_e32 v27, v233, v229
	v_fmac_f32_e32 v31, v221, v225
	v_mfma_f32_16x16x16_bf16 v[70:73], v[108:109], v[124:125], v[212:215]
	v_fmac_f32_e32 v35, v234, v230
	v_fmac_f32_e32 v39, v222, v226
	v_fmac_f32_e32 v43, v235, v231
	v_fmac_f32_e32 v47, v223, v227
	v_mfma_f32_16x16x16_bf16 v[74:77], v[108:109], v[126:127], v[212:215]
	v_fma_f32 v224, v216, v224, v19
	v_fma_f32 v228, v216, v228, v23
	v_fma_f32 v225, v217, v225, v27
	v_fma_f32 v229, v217, v229, v31
	v_mfma_f32_16x16x16_bf16 v[78:81], v[108:109], v[128:129], v[212:215]
	v_fma_f32 v226, v218, v226, v35
	v_fma_f32 v230, v218, v230, v39
	v_fma_f32 v227, v219, v227, v43
	v_fma_f32 v231, v219, v231, v47
	v_mfma_f32_16x16x32_bf16 v[204:207], v[180:183], v[196:199], v[204:207]
	v_cvt_pk_bf16_f32 v136, v224, v228
	v_cvt_pk_bf16_f32 v137, v225, v229
	v_mfma_f32_16x16x32_bf16 v[208:211], v[184:187], v[200:203], v[208:211]
	v_cvt_pk_bf16_f32 v138, v226, v230
	v_cvt_pk_bf16_f32 v139, v227, v231
	ds_write2_b32 v134, v136, v137 offset0:68 offset1:84
	ds_write2_b32 v134, v138, v139 offset0:100 offset1:116
	v_fmac_f32_e32 v20, v232, v228
	v_fmac_f32_e32 v24, v220, v224
	v_fmac_f32_e32 v28, v233, v229
	v_fmac_f32_e32 v32, v221, v225
	v_fmac_f32_e32 v36, v234, v230
	v_fmac_f32_e32 v40, v222, v226
	v_fmac_f32_e32 v44, v235, v231
	v_fmac_f32_e32 v48, v223, v227
	v_fma_f32 v224, v216, v224, v20
	v_fma_f32 v228, v216, v228, v24
	v_fma_f32 v225, v217, v225, v28
	v_fma_f32 v229, v217, v229, v32
	v_fma_f32 v226, v218, v226, v36
	v_fma_f32 v230, v218, v230, v40
	v_fma_f32 v227, v219, v227, v44
	v_fma_f32 v231, v219, v231, v48
	v_cvt_pk_bf16_f32 v136, v224, v228
	v_cvt_pk_bf16_f32 v137, v225, v229
	v_cvt_pk_bf16_f32 v138, v226, v230
	v_cvt_pk_bf16_f32 v139, v227, v231
	ds_write2_b32 v134, v136, v137 offset0:136 offset1:152
	ds_write2_b32 v134, v138, v139 offset0:168 offset1:184
	v_fmac_f32_e32 v21, v232, v228
	v_fmac_f32_e32 v25, v220, v224
	v_fmac_f32_e32 v29, v233, v229
	v_fmac_f32_e32 v33, v221, v225
	v_fmac_f32_e32 v37, v234, v230
	v_fmac_f32_e32 v41, v222, v226
	v_fmac_f32_e32 v45, v235, v231
	v_fmac_f32_e32 v49, v223, v227
	v_fma_f32 v224, v216, v224, v21
	v_fma_f32 v228, v216, v228, v25
	v_fma_f32 v225, v217, v225, v29
	v_fma_f32 v229, v217, v229, v33
	v_fma_f32 v226, v218, v226, v37
	v_fma_f32 v230, v218, v230, v41
	v_fma_f32 v227, v219, v227, v45
	v_fma_f32 v231, v219, v231, v49
	v_cvt_pk_bf16_f32 v136, v224, v228
	v_cvt_pk_bf16_f32 v137, v225, v229
	v_cvt_pk_bf16_f32 v138, v226, v230
	v_cvt_pk_bf16_f32 v139, v227, v231
	ds_write2_b32 v134, v136, v137 offset0:204 offset1:220
	ds_write2_b32 v134, v138, v139 offset0:236 offset1:252
	v_add_f32_e32 v204, v204, v208
	v_add_f32_e32 v205, v205, v209
	v_add_f32_e32 v206, v206, v210
	v_add_f32_e32 v207, v207, v211
	global_store_dwordx4 v[132:133], v[204:207], off
	v_lshl_add_u64 v[132:133], v[132:133], 0, s[88:89]
	s_waitcnt lgkmcnt(0)
	ds_read_b128 v[188:191], v135 offset:0
	ds_read_b128 v[192:195], v135 offset:64
	ds_read_b128 v[196:199], v135 offset:128
	ds_read_b128 v[200:203], v135 offset:192
	v_mfma_f32_16x16x16_bf16 v[18:21], v[110:111], v[114:115], v[212:215]
	v_fmac_f32_e32 v50, v232, v228
	v_fmac_f32_e32 v54, v220, v224
	v_fmac_f32_e32 v58, v233, v229
	v_fmac_f32_e32 v62, v221, v225
	v_mfma_f32_16x16x16_bf16 v[22:25], v[110:111], v[116:117], v[212:215]
	v_fmac_f32_e32 v66, v234, v230
	v_fmac_f32_e32 v70, v222, v226
	v_fmac_f32_e32 v74, v235, v231
	v_fmac_f32_e32 v78, v223, v227
	v_mfma_f32_16x16x16_bf16 v[26:29], v[110:111], v[118:119], v[212:215]
	v_fma_f32 v224, v216, v224, v50
	v_fma_f32 v228, v216, v228, v54
	v_fma_f32 v225, v217, v225, v58
	v_fma_f32 v229, v217, v229, v62
	v_mfma_f32_16x16x16_bf16 v[30:33], v[110:111], v[120:121], v[212:215]
	v_fma_f32 v226, v218, v226, v66
	v_fma_f32 v230, v218, v230, v70
	v_fma_f32 v227, v219, v227, v74
	v_fma_f32 v231, v219, v231, v78
	s_waitcnt lgkmcnt(0)
	v_mfma_f32_16x16x32_bf16 v[204:207], v[172:175], v[188:191], v[212:215]
	v_cvt_pk_bf16_f32 v136, v224, v228
	v_cvt_pk_bf16_f32 v137, v225, v229
	v_mfma_f32_16x16x32_bf16 v[208:211], v[176:179], v[192:195], v[212:215]
	v_cvt_pk_bf16_f32 v138, v226, v230
	v_cvt_pk_bf16_f32 v139, v227, v231
	ds_write2_b32 v134, v136, v137 offset0:0 offset1:16
	ds_write2_b32 v134, v138, v139 offset0:32 offset1:48
	v_mfma_f32_16x16x16_bf16 v[34:37], v[110:111], v[122:123], v[212:215]
	v_fmac_f32_e32 v51, v232, v228
	v_fmac_f32_e32 v55, v220, v224
	v_fmac_f32_e32 v59, v233, v229
	v_fmac_f32_e32 v63, v221, v225
	v_mfma_f32_16x16x16_bf16 v[38:41], v[110:111], v[124:125], v[212:215]
	v_fmac_f32_e32 v67, v234, v230
	v_fmac_f32_e32 v71, v222, v226
	v_fmac_f32_e32 v75, v235, v231
	v_fmac_f32_e32 v79, v223, v227
	v_mfma_f32_16x16x16_bf16 v[42:45], v[110:111], v[126:127], v[212:215]
	v_fma_f32 v224, v216, v224, v51
	v_fma_f32 v228, v216, v228, v55
	v_fma_f32 v225, v217, v225, v59
	v_fma_f32 v229, v217, v229, v63
	v_mfma_f32_16x16x16_bf16 v[46:49], v[110:111], v[128:129], v[212:215]
	v_fma_f32 v226, v218, v226, v67
	v_fma_f32 v230, v218, v230, v71
	v_fma_f32 v227, v219, v227, v75
	v_fma_f32 v231, v219, v231, v79
	v_mfma_f32_16x16x32_bf16 v[204:207], v[180:183], v[196:199], v[204:207]
	v_cvt_pk_bf16_f32 v136, v224, v228
	v_cvt_pk_bf16_f32 v137, v225, v229
	v_mfma_f32_16x16x32_bf16 v[208:211], v[184:187], v[200:203], v[208:211]
	v_cvt_pk_bf16_f32 v138, v226, v230
	v_cvt_pk_bf16_f32 v139, v227, v231
	ds_write2_b32 v134, v136, v137 offset0:68 offset1:84
	ds_write2_b32 v134, v138, v139 offset0:100 offset1:116
	v_fmac_f32_e32 v52, v232, v228
	v_fmac_f32_e32 v56, v220, v224
	v_fmac_f32_e32 v60, v233, v229
	v_fmac_f32_e32 v64, v221, v225
	v_fmac_f32_e32 v68, v234, v230
	v_fmac_f32_e32 v72, v222, v226
	v_fmac_f32_e32 v76, v235, v231
	v_fmac_f32_e32 v80, v223, v227
	v_fma_f32 v224, v216, v224, v52
	v_fma_f32 v228, v216, v228, v56
	v_fma_f32 v225, v217, v225, v60
	v_fma_f32 v229, v217, v229, v64
	v_fma_f32 v226, v218, v226, v68
	v_fma_f32 v230, v218, v230, v72
	v_fma_f32 v227, v219, v227, v76
	v_fma_f32 v231, v219, v231, v80
	v_cvt_pk_bf16_f32 v136, v224, v228
	v_cvt_pk_bf16_f32 v137, v225, v229
	v_cvt_pk_bf16_f32 v138, v226, v230
	v_cvt_pk_bf16_f32 v139, v227, v231
	ds_write2_b32 v134, v136, v137 offset0:136 offset1:152
	ds_write2_b32 v134, v138, v139 offset0:168 offset1:184
	v_fmac_f32_e32 v53, v232, v228
	v_fmac_f32_e32 v57, v220, v224
	v_fmac_f32_e32 v61, v233, v229
	v_fmac_f32_e32 v65, v221, v225
	v_fmac_f32_e32 v69, v234, v230
	v_fmac_f32_e32 v73, v222, v226
	v_fmac_f32_e32 v77, v235, v231
	v_fmac_f32_e32 v81, v223, v227
	v_fma_f32 v224, v216, v224, v53
	v_fma_f32 v228, v216, v228, v57
	v_fma_f32 v225, v217, v225, v61
	v_fma_f32 v229, v217, v229, v65
	v_fma_f32 v226, v218, v226, v69
	v_fma_f32 v230, v218, v230, v73
	v_fma_f32 v227, v219, v227, v77
	v_fma_f32 v231, v219, v231, v81
	v_cvt_pk_bf16_f32 v136, v224, v228
	v_cvt_pk_bf16_f32 v137, v225, v229
	v_cvt_pk_bf16_f32 v138, v226, v230
	v_cvt_pk_bf16_f32 v139, v227, v231
	ds_write2_b32 v134, v136, v137 offset0:204 offset1:220
	ds_write2_b32 v134, v138, v139 offset0:236 offset1:252
	v_add_f32_e32 v204, v204, v208
	v_add_f32_e32 v205, v205, v209
	v_add_f32_e32 v206, v206, v210
	v_add_f32_e32 v207, v207, v211
	global_store_dwordx4 v[132:133], v[204:207], off
	v_lshl_add_u64 v[132:133], v[132:133], 0, s[88:89]
	s_waitcnt lgkmcnt(0)
	ds_read_b128 v[188:191], v135 offset:0
	ds_read_b128 v[192:195], v135 offset:64
	ds_read_b128 v[196:199], v135 offset:128
	ds_read_b128 v[200:203], v135 offset:192
	v_mfma_f32_16x16x16_bf16 v[50:53], v[112:113], v[114:115], v[212:215]
	v_fmac_f32_e32 v18, v232, v228
	v_fmac_f32_e32 v22, v220, v224
	v_fmac_f32_e32 v26, v233, v229
	v_fmac_f32_e32 v30, v221, v225
	v_mfma_f32_16x16x16_bf16 v[54:57], v[112:113], v[116:117], v[212:215]
	v_fmac_f32_e32 v34, v234, v230
	v_fmac_f32_e32 v38, v222, v226
	v_fmac_f32_e32 v42, v235, v231
	v_fmac_f32_e32 v46, v223, v227
	v_mfma_f32_16x16x16_bf16 v[58:61], v[112:113], v[118:119], v[212:215]
	v_fma_f32 v224, v216, v224, v18
	v_fma_f32 v228, v216, v228, v22
	v_fma_f32 v225, v217, v225, v26
	v_fma_f32 v229, v217, v229, v30
	v_mfma_f32_16x16x16_bf16 v[62:65], v[112:113], v[120:121], v[212:215]
	v_fma_f32 v226, v218, v226, v34
	v_fma_f32 v230, v218, v230, v38
	v_fma_f32 v227, v219, v227, v42
	v_fma_f32 v231, v219, v231, v46
	s_waitcnt lgkmcnt(0)
	v_mfma_f32_16x16x32_bf16 v[204:207], v[172:175], v[188:191], v[212:215]
	v_cvt_pk_bf16_f32 v136, v224, v228
	v_cvt_pk_bf16_f32 v137, v225, v229
	v_mfma_f32_16x16x32_bf16 v[208:211], v[176:179], v[192:195], v[212:215]
	v_cvt_pk_bf16_f32 v138, v226, v230
	v_cvt_pk_bf16_f32 v139, v227, v231
	ds_write2_b32 v134, v136, v137 offset0:0 offset1:16
	ds_write2_b32 v134, v138, v139 offset0:32 offset1:48
	v_mfma_f32_16x16x16_bf16 v[66:69], v[112:113], v[122:123], v[212:215]
	v_fmac_f32_e32 v19, v232, v228
	v_fmac_f32_e32 v23, v220, v224
	v_fmac_f32_e32 v27, v233, v229
	v_fmac_f32_e32 v31, v221, v225
	v_mfma_f32_16x16x16_bf16 v[70:73], v[112:113], v[124:125], v[212:215]
	v_fmac_f32_e32 v35, v234, v230
	v_fmac_f32_e32 v39, v222, v226
	v_fmac_f32_e32 v43, v235, v231
	v_fmac_f32_e32 v47, v223, v227
	v_mfma_f32_16x16x16_bf16 v[74:77], v[112:113], v[126:127], v[212:215]
	v_fma_f32 v224, v216, v224, v19
	v_fma_f32 v228, v216, v228, v23
	v_fma_f32 v225, v217, v225, v27
	v_fma_f32 v229, v217, v229, v31
	v_mfma_f32_16x16x16_bf16 v[78:81], v[112:113], v[128:129], v[212:215]
	v_fma_f32 v226, v218, v226, v35
	v_fma_f32 v230, v218, v230, v39
	v_fma_f32 v227, v219, v227, v43
	v_fma_f32 v231, v219, v231, v47
	v_mfma_f32_16x16x32_bf16 v[204:207], v[180:183], v[196:199], v[204:207]
	v_cvt_pk_bf16_f32 v136, v224, v228
	v_cvt_pk_bf16_f32 v137, v225, v229
	v_mfma_f32_16x16x32_bf16 v[208:211], v[184:187], v[200:203], v[208:211]
	v_cvt_pk_bf16_f32 v138, v226, v230
	v_cvt_pk_bf16_f32 v139, v227, v231
	ds_write2_b32 v134, v136, v137 offset0:68 offset1:84
	ds_write2_b32 v134, v138, v139 offset0:100 offset1:116
	v_fmac_f32_e32 v20, v232, v228
	v_fmac_f32_e32 v24, v220, v224
	v_fmac_f32_e32 v28, v233, v229
	v_fmac_f32_e32 v32, v221, v225
	v_fmac_f32_e32 v36, v234, v230
	v_fmac_f32_e32 v40, v222, v226
	v_fmac_f32_e32 v44, v235, v231
	v_fmac_f32_e32 v48, v223, v227
	v_fma_f32 v224, v216, v224, v20
	v_fma_f32 v228, v216, v228, v24
	v_fma_f32 v225, v217, v225, v28
	v_fma_f32 v229, v217, v229, v32
	v_fma_f32 v226, v218, v226, v36
	v_fma_f32 v230, v218, v230, v40
	v_fma_f32 v227, v219, v227, v44
	v_fma_f32 v231, v219, v231, v48
	v_cvt_pk_bf16_f32 v136, v224, v228
	v_cvt_pk_bf16_f32 v137, v225, v229
	v_cvt_pk_bf16_f32 v138, v226, v230
	v_cvt_pk_bf16_f32 v139, v227, v231
	ds_write2_b32 v134, v136, v137 offset0:136 offset1:152
	ds_write2_b32 v134, v138, v139 offset0:168 offset1:184
	v_fmac_f32_e32 v21, v232, v228
	v_fmac_f32_e32 v25, v220, v224
	v_fmac_f32_e32 v29, v233, v229
	v_fmac_f32_e32 v33, v221, v225
	v_fmac_f32_e32 v37, v234, v230
	v_fmac_f32_e32 v41, v222, v226
	v_fmac_f32_e32 v45, v235, v231
	v_fmac_f32_e32 v49, v223, v227
	v_fma_f32 v224, v216, v224, v21
	v_fma_f32 v228, v216, v228, v25
	v_fma_f32 v225, v217, v225, v29
	v_fma_f32 v229, v217, v229, v33
	v_fma_f32 v226, v218, v226, v37
	v_fma_f32 v230, v218, v230, v41
	v_fma_f32 v227, v219, v227, v45
	v_fma_f32 v231, v219, v231, v49
	v_cvt_pk_bf16_f32 v136, v224, v228
	v_cvt_pk_bf16_f32 v137, v225, v229
	v_cvt_pk_bf16_f32 v138, v226, v230
	v_cvt_pk_bf16_f32 v139, v227, v231
	ds_write2_b32 v134, v136, v137 offset0:204 offset1:220
	ds_write2_b32 v134, v138, v139 offset0:236 offset1:252
	v_add_f32_e32 v204, v204, v208
	v_add_f32_e32 v205, v205, v209
	v_add_f32_e32 v206, v206, v210
	v_add_f32_e32 v207, v207, v211
	global_store_dwordx4 v[132:133], v[204:207], off
	v_lshl_add_u64 v[132:133], v[132:133], 0, s[88:89]
	s_waitcnt lgkmcnt(0)
	ds_read_b128 v[188:191], v135 offset:0
	ds_read_b128 v[192:195], v135 offset:64
	ds_read_b128 v[196:199], v135 offset:128
	ds_read_b128 v[200:203], v135 offset:192
	s_waitcnt vmcnt(14)
	v_mfma_f32_16x16x16_bf16 v[18:21], v[82:83], v[114:115], v[212:215]
	v_fmac_f32_e32 v50, v232, v228
	v_fmac_f32_e32 v54, v220, v224
	v_fmac_f32_e32 v58, v233, v229
	v_fmac_f32_e32 v62, v221, v225
	v_mfma_f32_16x16x16_bf16 v[22:25], v[82:83], v[116:117], v[212:215]
	v_fmac_f32_e32 v66, v234, v230
	v_fmac_f32_e32 v70, v222, v226
	v_fmac_f32_e32 v74, v235, v231
	v_fmac_f32_e32 v78, v223, v227
	v_mfma_f32_16x16x16_bf16 v[26:29], v[82:83], v[118:119], v[212:215]
	v_fma_f32 v224, v216, v224, v50
	v_fma_f32 v228, v216, v228, v54
	v_fma_f32 v225, v217, v225, v58
	v_fma_f32 v229, v217, v229, v62
	v_mfma_f32_16x16x16_bf16 v[30:33], v[82:83], v[120:121], v[212:215]
	v_fma_f32 v226, v218, v226, v66
	v_fma_f32 v230, v218, v230, v70
	v_fma_f32 v227, v219, v227, v74
	v_fma_f32 v231, v219, v231, v78
	s_waitcnt lgkmcnt(0)
	v_mfma_f32_16x16x32_bf16 v[204:207], v[172:175], v[188:191], v[212:215]
	v_cvt_pk_bf16_f32 v136, v224, v228
	v_cvt_pk_bf16_f32 v137, v225, v229
	v_mfma_f32_16x16x32_bf16 v[208:211], v[176:179], v[192:195], v[212:215]
	v_cvt_pk_bf16_f32 v138, v226, v230
	v_cvt_pk_bf16_f32 v139, v227, v231
	ds_write2_b32 v134, v136, v137 offset0:0 offset1:16
	ds_write2_b32 v134, v138, v139 offset0:32 offset1:48
	v_mfma_f32_16x16x16_bf16 v[34:37], v[82:83], v[122:123], v[212:215]
	v_fmac_f32_e32 v51, v232, v228
	v_fmac_f32_e32 v55, v220, v224
	v_fmac_f32_e32 v59, v233, v229
	v_fmac_f32_e32 v63, v221, v225
	v_mfma_f32_16x16x16_bf16 v[38:41], v[82:83], v[124:125], v[212:215]
	v_fmac_f32_e32 v67, v234, v230
	v_fmac_f32_e32 v71, v222, v226
	v_fmac_f32_e32 v75, v235, v231
	v_fmac_f32_e32 v79, v223, v227
	v_mfma_f32_16x16x16_bf16 v[42:45], v[82:83], v[126:127], v[212:215]
	v_fma_f32 v224, v216, v224, v51
	v_fma_f32 v228, v216, v228, v55
	v_fma_f32 v225, v217, v225, v59
	v_fma_f32 v229, v217, v229, v63
	v_mfma_f32_16x16x16_bf16 v[46:49], v[82:83], v[128:129], v[212:215]
	v_fma_f32 v226, v218, v226, v67
	v_fma_f32 v230, v218, v230, v71
	v_fma_f32 v227, v219, v227, v75
	v_fma_f32 v231, v219, v231, v79
	v_mfma_f32_16x16x32_bf16 v[204:207], v[180:183], v[196:199], v[204:207]
	v_cvt_pk_bf16_f32 v136, v224, v228
	v_cvt_pk_bf16_f32 v137, v225, v229
	v_mfma_f32_16x16x32_bf16 v[208:211], v[184:187], v[200:203], v[208:211]
	v_cvt_pk_bf16_f32 v138, v226, v230
	v_cvt_pk_bf16_f32 v139, v227, v231
	ds_write2_b32 v134, v136, v137 offset0:68 offset1:84
	ds_write2_b32 v134, v138, v139 offset0:100 offset1:116
	v_fmac_f32_e32 v52, v232, v228
	v_fmac_f32_e32 v56, v220, v224
	v_fmac_f32_e32 v60, v233, v229
	v_fmac_f32_e32 v64, v221, v225
	v_fmac_f32_e32 v68, v234, v230
	v_fmac_f32_e32 v72, v222, v226
	v_fmac_f32_e32 v76, v235, v231
	v_fmac_f32_e32 v80, v223, v227
	v_fma_f32 v224, v216, v224, v52
	v_fma_f32 v228, v216, v228, v56
	v_fma_f32 v225, v217, v225, v60
	v_fma_f32 v229, v217, v229, v64
	v_fma_f32 v226, v218, v226, v68
	v_fma_f32 v230, v218, v230, v72
	v_fma_f32 v227, v219, v227, v76
	v_fma_f32 v231, v219, v231, v80
	v_cvt_pk_bf16_f32 v136, v224, v228
	v_cvt_pk_bf16_f32 v137, v225, v229
	v_cvt_pk_bf16_f32 v138, v226, v230
	v_cvt_pk_bf16_f32 v139, v227, v231
	ds_write2_b32 v134, v136, v137 offset0:136 offset1:152
	ds_write2_b32 v134, v138, v139 offset0:168 offset1:184
	v_fmac_f32_e32 v53, v232, v228
	v_fmac_f32_e32 v57, v220, v224
	v_fmac_f32_e32 v61, v233, v229
	v_fmac_f32_e32 v65, v221, v225
	v_fmac_f32_e32 v69, v234, v230
	v_fmac_f32_e32 v73, v222, v226
	v_fmac_f32_e32 v77, v235, v231
	v_fmac_f32_e32 v81, v223, v227
	v_fma_f32 v224, v216, v224, v53
	v_fma_f32 v228, v216, v228, v57
	v_fma_f32 v225, v217, v225, v61
	v_fma_f32 v229, v217, v229, v65
	v_fma_f32 v226, v218, v226, v69
	v_fma_f32 v230, v218, v230, v73
	v_fma_f32 v227, v219, v227, v77
	v_fma_f32 v231, v219, v231, v81
	v_cvt_pk_bf16_f32 v136, v224, v228
	v_cvt_pk_bf16_f32 v137, v225, v229
	v_cvt_pk_bf16_f32 v138, v226, v230
	v_cvt_pk_bf16_f32 v139, v227, v231
	ds_write2_b32 v134, v136, v137 offset0:204 offset1:220
	ds_write2_b32 v134, v138, v139 offset0:236 offset1:252
	v_add_f32_e32 v204, v204, v208
	v_add_f32_e32 v205, v205, v209
	v_add_f32_e32 v206, v206, v210
	v_add_f32_e32 v207, v207, v211
	global_store_dwordx4 v[132:133], v[204:207], off
	v_lshl_add_u64 v[132:133], v[132:133], 0, s[88:89]
	s_waitcnt lgkmcnt(0)
	ds_read_b128 v[188:191], v135 offset:0
	ds_read_b128 v[192:195], v135 offset:64
	ds_read_b128 v[196:199], v135 offset:128
	ds_read_b128 v[200:203], v135 offset:192
	s_add_i32 s15, s15, 1
	s_cmp_lt_u32 s15, 4
	s_cbranch_scc1 .Lsc_loop
	s_waitcnt lgkmcnt(0)
	v_mfma_f32_16x16x32_bf16 v[204:207], v[172:175], v[188:191], v[212:215]
	v_mfma_f32_16x16x32_bf16 v[208:211], v[176:179], v[192:195], v[212:215]
	v_mfma_f32_16x16x32_bf16 v[204:207], v[180:183], v[196:199], v[204:207]
	v_mfma_f32_16x16x32_bf16 v[208:211], v[184:187], v[200:203], v[208:211]
	s_nop 7
	s_nop 1
	v_add_f32_e32 v204, v204, v208
	v_add_f32_e32 v205, v205, v209
	v_add_f32_e32 v206, v206, v210
	v_add_f32_e32 v207, v207, v211
	global_store_dwordx4 v[132:133], v[204:207], off
	s_branch .Lsc_final
.Lsc_local_loop:
	global_load_dwordx2 v[106:107], v[130:131], off
	v_lshl_add_u64 v[130:131], v[130:131], 0, s[86:87]
	global_load_dwordx2 v[108:109], v[130:131], off
	v_lshl_add_u64 v[130:131], v[130:131], 0, s[86:87]
	global_load_dwordx2 v[110:111], v[130:131], off
	v_lshl_add_u64 v[130:131], v[130:131], 0, s[86:87]
	global_load_dwordx2 v[112:113], v[130:131], off
	v_lshl_add_u64 v[130:131], v[130:131], 0, s[86:87]
	v_fmac_f32_e32 v18, v232, v228
	v_fmac_f32_e32 v22, v220, v224
	v_mfma_f32_16x16x16_bf16 v[50:53], v[84:85], v[114:115], v[212:215]
	v_fmac_f32_e32 v26, v233, v229
	v_fmac_f32_e32 v30, v221, v225
	v_fmac_f32_e32 v34, v234, v230
	v_fmac_f32_e32 v38, v222, v226
	v_mfma_f32_16x16x16_bf16 v[54:57], v[84:85], v[116:117], v[212:215]
	v_fmac_f32_e32 v42, v235, v231
	v_fmac_f32_e32 v46, v223, v227
	v_fma_f32 v224, v216, v224, v18
	v_fma_f32 v228, v216, v228, v22
	v_mfma_f32_16x16x16_bf16 v[58:61], v[84:85], v[118:119], v[212:215]
	v_fma_f32 v225, v217, v225, v26
	v_fma_f32 v229, v217, v229, v30
	v_fma_f32 v226, v218, v226, v34
	v_fma_f32 v230, v218, v230, v38
	v_mfma_f32_16x16x16_bf16 v[62:65], v[84:85], v[120:121], v[212:215]
	v_fma_f32 v227, v219, v227, v42
	v_fma_f32 v231, v219, v231, v46
	v_fmac_f32_e32 v19, v232, v228
	v_fmac_f32_e32 v23, v220, v224
	v_mfma_f32_16x16x16_bf16 v[66:69], v[84:85], v[122:123], v[212:215]
	v_fmac_f32_e32 v27, v233, v229
	v_fmac_f32_e32 v31, v221, v225
	v_fmac_f32_e32 v35, v234, v230
	v_fmac_f32_e32 v39, v222, v226
	v_mfma_f32_16x16x16_bf16 v[70:73], v[84:85], v[124:125], v[212:215]
	v_fmac_f32_e32 v43, v235, v231
	v_fmac_f32_e32 v47, v223, v227
	v_fma_f32 v224, v216, v224, v19
	v_fma_f32 v228, v216, v228, v23
	v_mfma_f32_16x16x16_bf16 v[74:77], v[84:85], v[126:127], v[212:215]
	v_fma_f32 v225, v217, v225, v27
	v_fma_f32 v229, v217, v229, v31
	v_fma_f32 v226, v218, v226, v35
	v_fma_f32 v230, v218, v230, v39
	v_mfma_f32_16x16x16_bf16 v[78:81], v[84:85], v[128:129], v[212:215]
	v_fma_f32 v227, v219, v227, v43
	v_fma_f32 v231, v219, v231, v47
	v_fmac_f32_e32 v20, v232, v228
	v_fmac_f32_e32 v24, v220, v224
	v_fmac_f32_e32 v28, v233, v229
	v_fmac_f32_e32 v32, v221, v225
	v_fmac_f32_e32 v36, v234, v230
	v_fmac_f32_e32 v40, v222, v226
	v_fmac_f32_e32 v44, v235, v231
	v_fmac_f32_e32 v48, v223, v227
	v_fma_f32 v224, v216, v224, v20
	v_fma_f32 v228, v216, v228, v24
	v_fma_f32 v225, v217, v225, v28
	v_fma_f32 v229, v217, v229, v32
	v_fma_f32 v226, v218, v226, v36
	v_fma_f32 v230, v218, v230, v40
	v_fma_f32 v227, v219, v227, v44
	v_fma_f32 v231, v219, v231, v48
	v_fmac_f32_e32 v21, v232, v228
	v_fmac_f32_e32 v25, v220, v224
	v_fmac_f32_e32 v29, v233, v229
	v_fmac_f32_e32 v33, v221, v225
	v_fmac_f32_e32 v37, v234, v230
	v_fmac_f32_e32 v41, v222, v226
	v_fmac_f32_e32 v45, v235, v231
	v_fmac_f32_e32 v49, v223, v227
	v_fma_f32 v224, v216, v224, v21
	v_fma_f32 v228, v216, v228, v25
	v_fma_f32 v225, v217, v225, v29
	v_fma_f32 v229, v217, v229, v33
	v_fma_f32 v226, v218, v226, v37
	v_fma_f32 v230, v218, v230, v41
	v_fma_f32 v227, v219, v227, v45
	v_fma_f32 v231, v219, v231, v49
	v_fmac_f32_e32 v50, v232, v228
	v_fmac_f32_e32 v54, v220, v224
	v_mfma_f32_16x16x16_bf16 v[18:21], v[86:87], v[114:115], v[212:215]
	v_fmac_f32_e32 v58, v233, v229
	v_fmac_f32_e32 v62, v221, v225
	v_fmac_f32_e32 v66, v234, v230
	v_fmac_f32_e32 v70, v222, v226
	v_mfma_f32_16x16x16_bf16 v[22:25], v[86:87], v[116:117], v[212:215]
	v_fmac_f32_e32 v74, v235, v231
	v_fmac_f32_e32 v78, v223, v227
	v_fma_f32 v224, v216, v224, v50
	v_fma_f32 v228, v216, v228, v54
	v_mfma_f32_16x16x16_bf16 v[26:29], v[86:87], v[118:119], v[212:215]
	v_fma_f32 v225, v217, v225, v58
	v_fma_f32 v229, v217, v229, v62
	v_fma_f32 v226, v218, v226, v66
	v_fma_f32 v230, v218, v230, v70
	v_mfma_f32_16x16x16_bf16 v[30:33], v[86:87], v[120:121], v[212:215]
	v_fma_f32 v227, v219, v227, v74
	v_fma_f32 v231, v219, v231, v78
	v_fmac_f32_e32 v51, v232, v228
	v_fmac_f32_e32 v55, v220, v224
	v_mfma_f32_16x16x16_bf16 v[34:37], v[86:87], v[122:123], v[212:215]
	v_fmac_f32_e32 v59, v233, v229
	v_fmac_f32_e32 v63, v221, v225
	v_fmac_f32_e32 v67, v234, v230
	v_fmac_f32_e32 v71, v222, v226
	v_mfma_f32_16x16x16_bf16 v[38:41], v[86:87], v[124:125], v[212:215]
	v_fmac_f32_e32 v75, v235, v231
	v_fmac_f32_e32 v79, v223, v227
	v_fma_f32 v224, v216, v224, v51
	v_fma_f32 v228, v216, v228, v55
	v_mfma_f32_16x16x16_bf16 v[42:45], v[86:87], v[126:127], v[212:215]
	v_fma_f32 v225, v217, v225, v59
	v_fma_f32 v229, v217, v229, v63
	v_fma_f32 v226, v218, v226, v67
	v_fma_f32 v230, v218, v230, v71
	v_mfma_f32_16x16x16_bf16 v[46:49], v[86:87], v[128:129], v[212:215]
	v_fma_f32 v227, v219, v227, v75
	v_fma_f32 v231, v219, v231, v79
	v_fmac_f32_e32 v52, v232, v228
	v_fmac_f32_e32 v56, v220, v224
	v_fmac_f32_e32 v60, v233, v229
	v_fmac_f32_e32 v64, v221, v225
	v_fmac_f32_e32 v68, v234, v230
	v_fmac_f32_e32 v72, v222, v226
	v_fmac_f32_e32 v76, v235, v231
	v_fmac_f32_e32 v80, v223, v227
	v_fma_f32 v224, v216, v224, v52
	v_fma_f32 v228, v216, v228, v56
	v_fma_f32 v225, v217, v225, v60
	v_fma_f32 v229, v217, v229, v64
	v_fma_f32 v226, v218, v226, v68
	v_fma_f32 v230, v218, v230, v72
	v_fma_f32 v227, v219, v227, v76
	v_fma_f32 v231, v219, v231, v80
	v_fmac_f32_e32 v53, v232, v228
	v_fmac_f32_e32 v57, v220, v224
	v_fmac_f32_e32 v61, v233, v229
	v_fmac_f32_e32 v65, v221, v225
	v_fmac_f32_e32 v69, v234, v230
	v_fmac_f32_e32 v73, v222, v226
	v_fmac_f32_e32 v77, v235, v231
	v_fmac_f32_e32 v81, v223, v227
	v_fma_f32 v224, v216, v224, v53
	v_fma_f32 v228, v216, v228, v57
	v_fma_f32 v225, v217, v225, v61
	v_fma_f32 v229, v217, v229, v65
	v_fma_f32 v226, v218, v226, v69
	v_fma_f32 v230, v218, v230, v73
	v_fma_f32 v227, v219, v227, v77
	v_fma_f32 v231, v219, v231, v81
	v_fmac_f32_e32 v18, v232, v228
	v_fmac_f32_e32 v22, v220, v224
	v_mfma_f32_16x16x16_bf16 v[50:53], v[88:89], v[114:115], v[212:215]
	v_fmac_f32_e32 v26, v233, v229
	v_fmac_f32_e32 v30, v221, v225
	v_fmac_f32_e32 v34, v234, v230
	v_fmac_f32_e32 v38, v222, v226
	v_mfma_f32_16x16x16_bf16 v[54:57], v[88:89], v[116:117], v[212:215]
	v_fmac_f32_e32 v42, v235, v231
	v_fmac_f32_e32 v46, v223, v227
	v_fma_f32 v224, v216, v224, v18
	v_fma_f32 v228, v216, v228, v22
	v_mfma_f32_16x16x16_bf16 v[58:61], v[88:89], v[118:119], v[212:215]
	v_fma_f32 v225, v217, v225, v26
	v_fma_f32 v229, v217, v229, v30
	v_fma_f32 v226, v218, v226, v34
	v_fma_f32 v230, v218, v230, v38
	v_mfma_f32_16x16x16_bf16 v[62:65], v[88:89], v[120:121], v[212:215]
	v_fma_f32 v227, v219, v227, v42
	v_fma_f32 v231, v219, v231, v46
	v_fmac_f32_e32 v19, v232, v228
	v_fmac_f32_e32 v23, v220, v224
	v_mfma_f32_16x16x16_bf16 v[66:69], v[88:89], v[122:123], v[212:215]
	v_fmac_f32_e32 v27, v233, v229
	v_fmac_f32_e32 v31, v221, v225
	v_fmac_f32_e32 v35, v234, v230
	v_fmac_f32_e32 v39, v222, v226
	v_mfma_f32_16x16x16_bf16 v[70:73], v[88:89], v[124:125], v[212:215]
	v_fmac_f32_e32 v43, v235, v231
	v_fmac_f32_e32 v47, v223, v227
	v_fma_f32 v224, v216, v224, v19
	v_fma_f32 v228, v216, v228, v23
	v_mfma_f32_16x16x16_bf16 v[74:77], v[88:89], v[126:127], v[212:215]
	v_fma_f32 v225, v217, v225, v27
	v_fma_f32 v229, v217, v229, v31
	v_fma_f32 v226, v218, v226, v35
	v_fma_f32 v230, v218, v230, v39
	v_mfma_f32_16x16x16_bf16 v[78:81], v[88:89], v[128:129], v[212:215]
	v_fma_f32 v227, v219, v227, v43
	v_fma_f32 v231, v219, v231, v47
	v_fmac_f32_e32 v20, v232, v228
	v_fmac_f32_e32 v24, v220, v224
	v_fmac_f32_e32 v28, v233, v229
	v_fmac_f32_e32 v32, v221, v225
	v_fmac_f32_e32 v36, v234, v230
	v_fmac_f32_e32 v40, v222, v226
	v_fmac_f32_e32 v44, v235, v231
	v_fmac_f32_e32 v48, v223, v227
	v_fma_f32 v224, v216, v224, v20
	v_fma_f32 v228, v216, v228, v24
	v_fma_f32 v225, v217, v225, v28
	v_fma_f32 v229, v217, v229, v32
	v_fma_f32 v226, v218, v226, v36
	v_fma_f32 v230, v218, v230, v40
	v_fma_f32 v227, v219, v227, v44
	v_fma_f32 v231, v219, v231, v48
	v_fmac_f32_e32 v21, v232, v228
	v_fmac_f32_e32 v25, v220, v224
	v_fmac_f32_e32 v29, v233, v229
	v_fmac_f32_e32 v33, v221, v225
	v_fmac_f32_e32 v37, v234, v230
	v_fmac_f32_e32 v41, v222, v226
	v_fmac_f32_e32 v45, v235, v231
	v_fmac_f32_e32 v49, v223, v227
	v_fma_f32 v224, v216, v224, v21
	v_fma_f32 v228, v216, v228, v25
	v_fma_f32 v225, v217, v225, v29
	v_fma_f32 v229, v217, v229, v33
	v_fma_f32 v226, v218, v226, v37
	v_fma_f32 v230, v218, v230, v41
	v_fma_f32 v227, v219, v227, v45
	v_fma_f32 v231, v219, v231, v49
	s_waitcnt vmcnt(8)
	v_fmac_f32_e32 v50, v232, v228
	v_fmac_f32_e32 v54, v220, v224
	v_mfma_f32_16x16x16_bf16 v[18:21], v[90:91], v[114:115], v[212:215]
	v_fmac_f32_e32 v58, v233, v229
	v_fmac_f32_e32 v62, v221, v225
	v_fmac_f32_e32 v66, v234, v230
	v_fmac_f32_e32 v70, v222, v226
	v_mfma_f32_16x16x16_bf16 v[22:25], v[90:91], v[116:117], v[212:215]
	v_fmac_f32_e32 v74, v235, v231
	v_fmac_f32_e32 v78, v223, v227
	v_fma_f32 v224, v216, v224, v50
	v_fma_f32 v228, v216, v228, v54
	v_mfma_f32_16x16x16_bf16 v[26:29], v[90:91], v[118:119], v[212:215]
	v_fma_f32 v225, v217, v225, v58
	v_fma_f32 v229, v217, v229, v62
	v_fma_f32 v226, v218, v226, v66
	v_fma_f32 v230, v218, v230, v70
	v_mfma_f32_16x16x16_bf16 v[30:33], v[90:91], v[120:121], v[212:215]
	v_fma_f32 v227, v219, v227, v74
	v_fma_f32 v231, v219, v231, v78
	v_fmac_f32_e32 v51, v232, v228
	v_fmac_f32_e32 v55, v220, v224
	v_mfma_f32_16x16x16_bf16 v[34:37], v[90:91], v[122:123], v[212:215]
	v_fmac_f32_e32 v59, v233, v229
	v_fmac_f32_e32 v63, v221, v225
	v_fmac_f32_e32 v67, v234, v230
	v_fmac_f32_e32 v71, v222, v226
	v_mfma_f32_16x16x16_bf16 v[38:41], v[90:91], v[124:125], v[212:215]
	v_fmac_f32_e32 v75, v235, v231
	v_fmac_f32_e32 v79, v223, v227
	v_fma_f32 v224, v216, v224, v51
	v_fma_f32 v228, v216, v228, v55
	v_mfma_f32_16x16x16_bf16 v[42:45], v[90:91], v[126:127], v[212:215]
	v_fma_f32 v225, v217, v225, v59
	v_fma_f32 v229, v217, v229, v63
	v_fma_f32 v226, v218, v226, v67
	v_fma_f32 v230, v218, v230, v71
	v_mfma_f32_16x16x16_bf16 v[46:49], v[90:91], v[128:129], v[212:215]
	v_fma_f32 v227, v219, v227, v75
	v_fma_f32 v231, v219, v231, v79
	v_fmac_f32_e32 v52, v232, v228
	v_fmac_f32_e32 v56, v220, v224
	v_fmac_f32_e32 v60, v233, v229
	v_fmac_f32_e32 v64, v221, v225
	v_fmac_f32_e32 v68, v234, v230
	v_fmac_f32_e32 v72, v222, v226
	v_fmac_f32_e32 v76, v235, v231
	v_fmac_f32_e32 v80, v223, v227
	v_fma_f32 v224, v216, v224, v52
	v_fma_f32 v228, v216, v228, v56
	v_fma_f32 v225, v217, v225, v60
	v_fma_f32 v229, v217, v229, v64
	v_fma_f32 v226, v218, v226, v68
	v_fma_f32 v230, v218, v230, v72
	v_fma_f32 v227, v219, v227, v76
	v_fma_f32 v231, v219, v231, v80
	v_fmac_f32_e32 v53, v232, v228
	v_fmac_f32_e32 v57, v220, v224
	v_fmac_f32_e32 v61, v233, v229
	v_fmac_f32_e32 v65, v221, v225
	v_fmac_f32_e32 v69, v234, v230
	v_fmac_f32_e32 v73, v222, v226
	v_fmac_f32_e32 v77, v235, v231
	v_fmac_f32_e32 v81, v223, v227
	v_fma_f32 v224, v216, v224, v53
	v_fma_f32 v228, v216, v228, v57
	v_fma_f32 v225, v217, v225, v61
	v_fma_f32 v229, v217, v229, v65
	v_fma_f32 v226, v218, v226, v69
	v_fma_f32 v230, v218, v230, v73
	v_fma_f32 v227, v219, v227, v77
	v_fma_f32 v231, v219, v231, v81
	global_load_dwordx2 v[82:83], v[130:131], off
	v_lshl_add_u64 v[130:131], v[130:131], 0, s[86:87]
	global_load_dwordx2 v[84:85], v[130:131], off
	v_lshl_add_u64 v[130:131], v[130:131], 0, s[86:87]
	global_load_dwordx2 v[86:87], v[130:131], off
	v_lshl_add_u64 v[130:131], v[130:131], 0, s[86:87]
	global_load_dwordx2 v[88:89], v[130:131], off
	v_lshl_add_u64 v[130:131], v[130:131], 0, s[86:87]
	v_fmac_f32_e32 v18, v232, v228
	v_fmac_f32_e32 v22, v220, v224
	v_mfma_f32_16x16x16_bf16 v[50:53], v[92:93], v[114:115], v[212:215]
	v_fmac_f32_e32 v26, v233, v229
	v_fmac_f32_e32 v30, v221, v225
	v_fmac_f32_e32 v34, v234, v230
	v_fmac_f32_e32 v38, v222, v226
	v_mfma_f32_16x16x16_bf16 v[54:57], v[92:93], v[116:117], v[212:215]
	v_fmac_f32_e32 v42, v235, v231
	v_fmac_f32_e32 v46, v223, v227
	v_fma_f32 v224, v216, v224, v18
	v_fma_f32 v228, v216, v228, v22
	v_mfma_f32_16x16x16_bf16 v[58:61], v[92:93], v[118:119], v[212:215]
	v_fma_f32 v225, v217, v225, v26
	v_fma_f32 v229, v217, v229, v30
	v_fma_f32 v226, v218, v226, v34
	v_fma_f32 v230, v218, v230, v38
	v_mfma_f32_16x16x16_bf16 v[62:65], v[92:93], v[120:121], v[212:215]
	v_fma_f32 v227, v219, v227, v42
	v_fma_f32 v231, v219, v231, v46
	v_fmac_f32_e32 v19, v232, v228
	v_fmac_f32_e32 v23, v220, v224
	v_mfma_f32_16x16x16_bf16 v[66:69], v[92:93], v[122:123], v[212:215]
	v_fmac_f32_e32 v27, v233, v229
	v_fmac_f32_e32 v31, v221, v225
	v_fmac_f32_e32 v35, v234, v230
	v_fmac_f32_e32 v39, v222, v226
	v_mfma_f32_16x16x16_bf16 v[70:73], v[92:93], v[124:125], v[212:215]
	v_fmac_f32_e32 v43, v235, v231
	v_fmac_f32_e32 v47, v223, v227
	v_fma_f32 v224, v216, v224, v19
	v_fma_f32 v228, v216, v228, v23
	v_mfma_f32_16x16x16_bf16 v[74:77], v[92:93], v[126:127], v[212:215]
	v_fma_f32 v225, v217, v225, v27
	v_fma_f32 v229, v217, v229, v31
	v_fma_f32 v226, v218, v226, v35
	v_fma_f32 v230, v218, v230, v39
	v_mfma_f32_16x16x16_bf16 v[78:81], v[92:93], v[128:129], v[212:215]
	v_fma_f32 v227, v219, v227, v43
	v_fma_f32 v231, v219, v231, v47
	v_fmac_f32_e32 v20, v232, v228
	v_fmac_f32_e32 v24, v220, v224
	v_fmac_f32_e32 v28, v233, v229
	v_fmac_f32_e32 v32, v221, v225
	v_fmac_f32_e32 v36, v234, v230
	v_fmac_f32_e32 v40, v222, v226
	v_fmac_f32_e32 v44, v235, v231
	v_fmac_f32_e32 v48, v223, v227
	v_fma_f32 v224, v216, v224, v20
	v_fma_f32 v228, v216, v228, v24
	v_fma_f32 v225, v217, v225, v28
	v_fma_f32 v229, v217, v229, v32
	v_fma_f32 v226, v218, v226, v36
	v_fma_f32 v230, v218, v230, v40
	v_fma_f32 v227, v219, v227, v44
	v_fma_f32 v231, v219, v231, v48
	v_fmac_f32_e32 v21, v232, v228
	v_fmac_f32_e32 v25, v220, v224
	v_fmac_f32_e32 v29, v233, v229
	v_fmac_f32_e32 v33, v221, v225
	v_fmac_f32_e32 v37, v234, v230
	v_fmac_f32_e32 v41, v222, v226
	v_fmac_f32_e32 v45, v235, v231
	v_fmac_f32_e32 v49, v223, v227
	v_fma_f32 v224, v216, v224, v21
	v_fma_f32 v228, v216, v228, v25
	v_fma_f32 v225, v217, v225, v29
	v_fma_f32 v229, v217, v229, v33
	v_fma_f32 v226, v218, v226, v37
	v_fma_f32 v230, v218, v230, v41
	v_fma_f32 v227, v219, v227, v45
	v_fma_f32 v231, v219, v231, v49
	v_fmac_f32_e32 v50, v232, v228
	v_fmac_f32_e32 v54, v220, v224
	v_mfma_f32_16x16x16_bf16 v[18:21], v[94:95], v[114:115], v[212:215]
	v_fmac_f32_e32 v58, v233, v229
	v_fmac_f32_e32 v62, v221, v225
	v_fmac_f32_e32 v66, v234, v230
	v_fmac_f32_e32 v70, v222, v226
	v_mfma_f32_16x16x16_bf16 v[22:25], v[94:95], v[116:117], v[212:215]
	v_fmac_f32_e32 v74, v235, v231
	v_fmac_f32_e32 v78, v223, v227
	v_fma_f32 v224, v216, v224, v50
	v_fma_f32 v228, v216, v228, v54
	v_mfma_f32_16x16x16_bf16 v[26:29], v[94:95], v[118:119], v[212:215]
	v_fma_f32 v225, v217, v225, v58
	v_fma_f32 v229, v217, v229, v62
	v_fma_f32 v226, v218, v226, v66
	v_fma_f32 v230, v218, v230, v70
	v_mfma_f32_16x16x16_bf16 v[30:33], v[94:95], v[120:121], v[212:215]
	v_fma_f32 v227, v219, v227, v74
	v_fma_f32 v231, v219, v231, v78
	v_fmac_f32_e32 v51, v232, v228
	v_fmac_f32_e32 v55, v220, v224
	v_mfma_f32_16x16x16_bf16 v[34:37], v[94:95], v[122:123], v[212:215]
	v_fmac_f32_e32 v59, v233, v229
	v_fmac_f32_e32 v63, v221, v225
	v_fmac_f32_e32 v67, v234, v230
	v_fmac_f32_e32 v71, v222, v226
	v_mfma_f32_16x16x16_bf16 v[38:41], v[94:95], v[124:125], v[212:215]
	v_fmac_f32_e32 v75, v235, v231
	v_fmac_f32_e32 v79, v223, v227
	v_fma_f32 v224, v216, v224, v51
	v_fma_f32 v228, v216, v228, v55
	v_mfma_f32_16x16x16_bf16 v[42:45], v[94:95], v[126:127], v[212:215]
	v_fma_f32 v225, v217, v225, v59
	v_fma_f32 v229, v217, v229, v63
	v_fma_f32 v226, v218, v226, v67
	v_fma_f32 v230, v218, v230, v71
	v_mfma_f32_16x16x16_bf16 v[46:49], v[94:95], v[128:129], v[212:215]
	v_fma_f32 v227, v219, v227, v75
	v_fma_f32 v231, v219, v231, v79
	v_fmac_f32_e32 v52, v232, v228
	v_fmac_f32_e32 v56, v220, v224
	v_fmac_f32_e32 v60, v233, v229
	v_fmac_f32_e32 v64, v221, v225
	v_fmac_f32_e32 v68, v234, v230
	v_fmac_f32_e32 v72, v222, v226
	v_fmac_f32_e32 v76, v235, v231
	v_fmac_f32_e32 v80, v223, v227
	v_fma_f32 v224, v216, v224, v52
	v_fma_f32 v228, v216, v228, v56
	v_fma_f32 v225, v217, v225, v60
	v_fma_f32 v229, v217, v229, v64
	v_fma_f32 v226, v218, v226, v68
	v_fma_f32 v230, v218, v230, v72
	v_fma_f32 v227, v219, v227, v76
	v_fma_f32 v231, v219, v231, v80
	v_fmac_f32_e32 v53, v232, v228
	v_fmac_f32_e32 v57, v220, v224
	v_fmac_f32_e32 v61, v233, v229
	v_fmac_f32_e32 v65, v221, v225
	v_fmac_f32_e32 v69, v234, v230
	v_fmac_f32_e32 v73, v222, v226
	v_fmac_f32_e32 v77, v235, v231
	v_fmac_f32_e32 v81, v223, v227
	v_fma_f32 v224, v216, v224, v53
	v_fma_f32 v228, v216, v228, v57
	v_fma_f32 v225, v217, v225, v61
	v_fma_f32 v229, v217, v229, v65
	v_fma_f32 v226, v218, v226, v69
	v_fma_f32 v230, v218, v230, v73
	v_fma_f32 v227, v219, v227, v77
	v_fma_f32 v231, v219, v231, v81
	v_fmac_f32_e32 v18, v232, v228
	v_fmac_f32_e32 v22, v220, v224
	v_mfma_f32_16x16x16_bf16 v[50:53], v[96:97], v[114:115], v[212:215]
	v_fmac_f32_e32 v26, v233, v229
	v_fmac_f32_e32 v30, v221, v225
	v_fmac_f32_e32 v34, v234, v230
	v_fmac_f32_e32 v38, v222, v226
	v_mfma_f32_16x16x16_bf16 v[54:57], v[96:97], v[116:117], v[212:215]
	v_fmac_f32_e32 v42, v235, v231
	v_fmac_f32_e32 v46, v223, v227
	v_fma_f32 v224, v216, v224, v18
	v_fma_f32 v228, v216, v228, v22
	v_mfma_f32_16x16x16_bf16 v[58:61], v[96:97], v[118:119], v[212:215]
	v_fma_f32 v225, v217, v225, v26
	v_fma_f32 v229, v217, v229, v30
	v_fma_f32 v226, v218, v226, v34
	v_fma_f32 v230, v218, v230, v38
	v_mfma_f32_16x16x16_bf16 v[62:65], v[96:97], v[120:121], v[212:215]
	v_fma_f32 v227, v219, v227, v42
	v_fma_f32 v231, v219, v231, v46
	v_fmac_f32_e32 v19, v232, v228
	v_fmac_f32_e32 v23, v220, v224
	v_mfma_f32_16x16x16_bf16 v[66:69], v[96:97], v[122:123], v[212:215]
	v_fmac_f32_e32 v27, v233, v229
	v_fmac_f32_e32 v31, v221, v225
	v_fmac_f32_e32 v35, v234, v230
	v_fmac_f32_e32 v39, v222, v226
	v_mfma_f32_16x16x16_bf16 v[70:73], v[96:97], v[124:125], v[212:215]
	v_fmac_f32_e32 v43, v235, v231
	v_fmac_f32_e32 v47, v223, v227
	v_fma_f32 v224, v216, v224, v19
	v_fma_f32 v228, v216, v228, v23
	v_mfma_f32_16x16x16_bf16 v[74:77], v[96:97], v[126:127], v[212:215]
	v_fma_f32 v225, v217, v225, v27
	v_fma_f32 v229, v217, v229, v31
	v_fma_f32 v226, v218, v226, v35
	v_fma_f32 v230, v218, v230, v39
	v_mfma_f32_16x16x16_bf16 v[78:81], v[96:97], v[128:129], v[212:215]
	v_fma_f32 v227, v219, v227, v43
	v_fma_f32 v231, v219, v231, v47
	v_fmac_f32_e32 v20, v232, v228
	v_fmac_f32_e32 v24, v220, v224
	v_fmac_f32_e32 v28, v233, v229
	v_fmac_f32_e32 v32, v221, v225
	v_fmac_f32_e32 v36, v234, v230
	v_fmac_f32_e32 v40, v222, v226
	v_fmac_f32_e32 v44, v235, v231
	v_fmac_f32_e32 v48, v223, v227
	v_fma_f32 v224, v216, v224, v20
	v_fma_f32 v228, v216, v228, v24
	v_fma_f32 v225, v217, v225, v28
	v_fma_f32 v229, v217, v229, v32
	v_fma_f32 v226, v218, v226, v36
	v_fma_f32 v230, v218, v230, v40
	v_fma_f32 v227, v219, v227, v44
	v_fma_f32 v231, v219, v231, v48
	v_fmac_f32_e32 v21, v232, v228
	v_fmac_f32_e32 v25, v220, v224
	v_fmac_f32_e32 v29, v233, v229
	v_fmac_f32_e32 v33, v221, v225
	v_fmac_f32_e32 v37, v234, v230
	v_fmac_f32_e32 v41, v222, v226
	v_fmac_f32_e32 v45, v235, v231
	v_fmac_f32_e32 v49, v223, v227
	v_fma_f32 v224, v216, v224, v21
	v_fma_f32 v228, v216, v228, v25
	v_fma_f32 v225, v217, v225, v29
	v_fma_f32 v229, v217, v229, v33
	v_fma_f32 v226, v218, v226, v37
	v_fma_f32 v230, v218, v230, v41
	v_fma_f32 v227, v219, v227, v45
	v_fma_f32 v231, v219, v231, v49
	s_waitcnt vmcnt(8)
	v_fmac_f32_e32 v50, v232, v228
	v_fmac_f32_e32 v54, v220, v224
	v_mfma_f32_16x16x16_bf16 v[18:21], v[98:99], v[114:115], v[212:215]
	v_fmac_f32_e32 v58, v233, v229
	v_fmac_f32_e32 v62, v221, v225
	v_fmac_f32_e32 v66, v234, v230
	v_fmac_f32_e32 v70, v222, v226
	v_mfma_f32_16x16x16_bf16 v[22:25], v[98:99], v[116:117], v[212:215]
	v_fmac_f32_e32 v74, v235, v231
	v_fmac_f32_e32 v78, v223, v227
	v_fma_f32 v224, v216, v224, v50
	v_fma_f32 v228, v216, v228, v54
	v_mfma_f32_16x16x16_bf16 v[26:29], v[98:99], v[118:119], v[212:215]
	v_fma_f32 v225, v217, v225, v58
	v_fma_f32 v229, v217, v229, v62
	v_fma_f32 v226, v218, v226, v66
	v_fma_f32 v230, v218, v230, v70
	v_mfma_f32_16x16x16_bf16 v[30:33], v[98:99], v[120:121], v[212:215]
	v_fma_f32 v227, v219, v227, v74
	v_fma_f32 v231, v219, v231, v78
	v_fmac_f32_e32 v51, v232, v228
	v_fmac_f32_e32 v55, v220, v224
	v_mfma_f32_16x16x16_bf16 v[34:37], v[98:99], v[122:123], v[212:215]
	v_fmac_f32_e32 v59, v233, v229
	v_fmac_f32_e32 v63, v221, v225
	v_fmac_f32_e32 v67, v234, v230
	v_fmac_f32_e32 v71, v222, v226
	v_mfma_f32_16x16x16_bf16 v[38:41], v[98:99], v[124:125], v[212:215]
	v_fmac_f32_e32 v75, v235, v231
	v_fmac_f32_e32 v79, v223, v227
	v_fma_f32 v224, v216, v224, v51
	v_fma_f32 v228, v216, v228, v55
	v_mfma_f32_16x16x16_bf16 v[42:45], v[98:99], v[126:127], v[212:215]
	v_fma_f32 v225, v217, v225, v59
	v_fma_f32 v229, v217, v229, v63
	v_fma_f32 v226, v218, v226, v67
	v_fma_f32 v230, v218, v230, v71
	v_mfma_f32_16x16x16_bf16 v[46:49], v[98:99], v[128:129], v[212:215]
	v_fma_f32 v227, v219, v227, v75
	v_fma_f32 v231, v219, v231, v79
	v_fmac_f32_e32 v52, v232, v228
	v_fmac_f32_e32 v56, v220, v224
	v_fmac_f32_e32 v60, v233, v229
	v_fmac_f32_e32 v64, v221, v225
	v_fmac_f32_e32 v68, v234, v230
	v_fmac_f32_e32 v72, v222, v226
	v_fmac_f32_e32 v76, v235, v231
	v_fmac_f32_e32 v80, v223, v227
	v_fma_f32 v224, v216, v224, v52
	v_fma_f32 v228, v216, v228, v56
	v_fma_f32 v225, v217, v225, v60
	v_fma_f32 v229, v217, v229, v64
	v_fma_f32 v226, v218, v226, v68
	v_fma_f32 v230, v218, v230, v72
	v_fma_f32 v227, v219, v227, v76
	v_fma_f32 v231, v219, v231, v80
	v_fmac_f32_e32 v53, v232, v228
	v_fmac_f32_e32 v57, v220, v224
	v_fmac_f32_e32 v61, v233, v229
	v_fmac_f32_e32 v65, v221, v225
	v_fmac_f32_e32 v69, v234, v230
	v_fmac_f32_e32 v73, v222, v226
	v_fmac_f32_e32 v77, v235, v231
	v_fmac_f32_e32 v81, v223, v227
	v_fma_f32 v224, v216, v224, v53
	v_fma_f32 v228, v216, v228, v57
	v_fma_f32 v225, v217, v225, v61
	v_fma_f32 v229, v217, v229, v65
	v_fma_f32 v226, v218, v226, v69
	v_fma_f32 v230, v218, v230, v73
	v_fma_f32 v227, v219, v227, v77
	v_fma_f32 v231, v219, v231, v81
	global_load_dwordx2 v[90:91], v[130:131], off
	v_lshl_add_u64 v[130:131], v[130:131], 0, s[86:87]
	global_load_dwordx2 v[92:93], v[130:131], off
	v_lshl_add_u64 v[130:131], v[130:131], 0, s[86:87]
	global_load_dwordx2 v[94:95], v[130:131], off
	v_lshl_add_u64 v[130:131], v[130:131], 0, s[86:87]
	global_load_dwordx2 v[96:97], v[130:131], off
	v_lshl_add_u64 v[130:131], v[130:131], 0, s[86:87]
	v_fmac_f32_e32 v18, v232, v228
	v_fmac_f32_e32 v22, v220, v224
	v_mfma_f32_16x16x16_bf16 v[50:53], v[100:101], v[114:115], v[212:215]
	v_fmac_f32_e32 v26, v233, v229
	v_fmac_f32_e32 v30, v221, v225
	v_fmac_f32_e32 v34, v234, v230
	v_fmac_f32_e32 v38, v222, v226
	v_mfma_f32_16x16x16_bf16 v[54:57], v[100:101], v[116:117], v[212:215]
	v_fmac_f32_e32 v42, v235, v231
	v_fmac_f32_e32 v46, v223, v227
	v_fma_f32 v224, v216, v224, v18
	v_fma_f32 v228, v216, v228, v22
	v_mfma_f32_16x16x16_bf16 v[58:61], v[100:101], v[118:119], v[212:215]
	v_fma_f32 v225, v217, v225, v26
	v_fma_f32 v229, v217, v229, v30
	v_fma_f32 v226, v218, v226, v34
	v_fma_f32 v230, v218, v230, v38
	v_mfma_f32_16x16x16_bf16 v[62:65], v[100:101], v[120:121], v[212:215]
	v_fma_f32 v227, v219, v227, v42
	v_fma_f32 v231, v219, v231, v46
	v_fmac_f32_e32 v19, v232, v228
	v_fmac_f32_e32 v23, v220, v224
	v_mfma_f32_16x16x16_bf16 v[66:69], v[100:101], v[122:123], v[212:215]
	v_fmac_f32_e32 v27, v233, v229
	v_fmac_f32_e32 v31, v221, v225
	v_fmac_f32_e32 v35, v234, v230
	v_fmac_f32_e32 v39, v222, v226
	v_mfma_f32_16x16x16_bf16 v[70:73], v[100:101], v[124:125], v[212:215]
	v_fmac_f32_e32 v43, v235, v231
	v_fmac_f32_e32 v47, v223, v227
	v_fma_f32 v224, v216, v224, v19
	v_fma_f32 v228, v216, v228, v23
	v_mfma_f32_16x16x16_bf16 v[74:77], v[100:101], v[126:127], v[212:215]
	v_fma_f32 v225, v217, v225, v27
	v_fma_f32 v229, v217, v229, v31
	v_fma_f32 v226, v218, v226, v35
	v_fma_f32 v230, v218, v230, v39
	v_mfma_f32_16x16x16_bf16 v[78:81], v[100:101], v[128:129], v[212:215]
	v_fma_f32 v227, v219, v227, v43
	v_fma_f32 v231, v219, v231, v47
	v_fmac_f32_e32 v20, v232, v228
	v_fmac_f32_e32 v24, v220, v224
	v_fmac_f32_e32 v28, v233, v229
	v_fmac_f32_e32 v32, v221, v225
	v_fmac_f32_e32 v36, v234, v230
	v_fmac_f32_e32 v40, v222, v226
	v_fmac_f32_e32 v44, v235, v231
	v_fmac_f32_e32 v48, v223, v227
	v_fma_f32 v224, v216, v224, v20
	v_fma_f32 v228, v216, v228, v24
	v_fma_f32 v225, v217, v225, v28
	v_fma_f32 v229, v217, v229, v32
	v_fma_f32 v226, v218, v226, v36
	v_fma_f32 v230, v218, v230, v40
	v_fma_f32 v227, v219, v227, v44
	v_fma_f32 v231, v219, v231, v48
	v_fmac_f32_e32 v21, v232, v228
	v_fmac_f32_e32 v25, v220, v224
	v_fmac_f32_e32 v29, v233, v229
	v_fmac_f32_e32 v33, v221, v225
	v_fmac_f32_e32 v37, v234, v230
	v_fmac_f32_e32 v41, v222, v226
	v_fmac_f32_e32 v45, v235, v231
	v_fmac_f32_e32 v49, v223, v227
	v_fma_f32 v224, v216, v224, v21
	v_fma_f32 v228, v216, v228, v25
	v_fma_f32 v225, v217, v225, v29
	v_fma_f32 v229, v217, v229, v33
	v_fma_f32 v226, v218, v226, v37
	v_fma_f32 v230, v218, v230, v41
	v_fma_f32 v227, v219, v227, v45
	v_fma_f32 v231, v219, v231, v49
	v_fmac_f32_e32 v50, v232, v228
	v_fmac_f32_e32 v54, v220, v224
	v_mfma_f32_16x16x16_bf16 v[18:21], v[102:103], v[114:115], v[212:215]
	v_fmac_f32_e32 v58, v233, v229
	v_fmac_f32_e32 v62, v221, v225
	v_fmac_f32_e32 v66, v234, v230
	v_fmac_f32_e32 v70, v222, v226
	v_mfma_f32_16x16x16_bf16 v[22:25], v[102:103], v[116:117], v[212:215]
	v_fmac_f32_e32 v74, v235, v231
	v_fmac_f32_e32 v78, v223, v227
	v_fma_f32 v224, v216, v224, v50
	v_fma_f32 v228, v216, v228, v54
	v_mfma_f32_16x16x16_bf16 v[26:29], v[102:103], v[118:119], v[212:215]
	v_fma_f32 v225, v217, v225, v58
	v_fma_f32 v229, v217, v229, v62
	v_fma_f32 v226, v218, v226, v66
	v_fma_f32 v230, v218, v230, v70
	v_mfma_f32_16x16x16_bf16 v[30:33], v[102:103], v[120:121], v[212:215]
	v_fma_f32 v227, v219, v227, v74
	v_fma_f32 v231, v219, v231, v78
	v_fmac_f32_e32 v51, v232, v228
	v_fmac_f32_e32 v55, v220, v224
	v_mfma_f32_16x16x16_bf16 v[34:37], v[102:103], v[122:123], v[212:215]
	v_fmac_f32_e32 v59, v233, v229
	v_fmac_f32_e32 v63, v221, v225
	v_fmac_f32_e32 v67, v234, v230
	v_fmac_f32_e32 v71, v222, v226
	v_mfma_f32_16x16x16_bf16 v[38:41], v[102:103], v[124:125], v[212:215]
	v_fmac_f32_e32 v75, v235, v231
	v_fmac_f32_e32 v79, v223, v227
	v_fma_f32 v224, v216, v224, v51
	v_fma_f32 v228, v216, v228, v55
	v_mfma_f32_16x16x16_bf16 v[42:45], v[102:103], v[126:127], v[212:215]
	v_fma_f32 v225, v217, v225, v59
	v_fma_f32 v229, v217, v229, v63
	v_fma_f32 v226, v218, v226, v67
	v_fma_f32 v230, v218, v230, v71
	v_mfma_f32_16x16x16_bf16 v[46:49], v[102:103], v[128:129], v[212:215]
	v_fma_f32 v227, v219, v227, v75
	v_fma_f32 v231, v219, v231, v79
	v_fmac_f32_e32 v52, v232, v228
	v_fmac_f32_e32 v56, v220, v224
	v_fmac_f32_e32 v60, v233, v229
	v_fmac_f32_e32 v64, v221, v225
	v_fmac_f32_e32 v68, v234, v230
	v_fmac_f32_e32 v72, v222, v226
	v_fmac_f32_e32 v76, v235, v231
	v_fmac_f32_e32 v80, v223, v227
	v_fma_f32 v224, v216, v224, v52
	v_fma_f32 v228, v216, v228, v56
	v_fma_f32 v225, v217, v225, v60
	v_fma_f32 v229, v217, v229, v64
	v_fma_f32 v226, v218, v226, v68
	v_fma_f32 v230, v218, v230, v72
	v_fma_f32 v227, v219, v227, v76
	v_fma_f32 v231, v219, v231, v80
	v_fmac_f32_e32 v53, v232, v228
	v_fmac_f32_e32 v57, v220, v224
	v_fmac_f32_e32 v61, v233, v229
	v_fmac_f32_e32 v65, v221, v225
	v_fmac_f32_e32 v69, v234, v230
	v_fmac_f32_e32 v73, v222, v226
	v_fmac_f32_e32 v77, v235, v231
	v_fmac_f32_e32 v81, v223, v227
	v_fma_f32 v224, v216, v224, v53
	v_fma_f32 v228, v216, v228, v57
	v_fma_f32 v225, v217, v225, v61
	v_fma_f32 v229, v217, v229, v65
	v_fma_f32 v226, v218, v226, v69
	v_fma_f32 v230, v218, v230, v73
	v_fma_f32 v227, v219, v227, v77
	v_fma_f32 v231, v219, v231, v81
	v_fmac_f32_e32 v18, v232, v228
	v_fmac_f32_e32 v22, v220, v224
	v_mfma_f32_16x16x16_bf16 v[50:53], v[104:105], v[114:115], v[212:215]
	v_fmac_f32_e32 v26, v233, v229
	v_fmac_f32_e32 v30, v221, v225
	v_fmac_f32_e32 v34, v234, v230
	v_fmac_f32_e32 v38, v222, v226
	v_mfma_f32_16x16x16_bf16 v[54:57], v[104:105], v[116:117], v[212:215]
	v_fmac_f32_e32 v42, v235, v231
	v_fmac_f32_e32 v46, v223, v227
	v_fma_f32 v224, v216, v224, v18
	v_fma_f32 v228, v216, v228, v22
	v_mfma_f32_16x16x16_bf16 v[58:61], v[104:105], v[118:119], v[212:215]
	v_fma_f32 v225, v217, v225, v26
	v_fma_f32 v229, v217, v229, v30
	v_fma_f32 v226, v218, v226, v34
	v_fma_f32 v230, v218, v230, v38
	v_mfma_f32_16x16x16_bf16 v[62:65], v[104:105], v[120:121], v[212:215]
	v_fma_f32 v227, v219, v227, v42
	v_fma_f32 v231, v219, v231, v46
	v_fmac_f32_e32 v19, v232, v228
	v_fmac_f32_e32 v23, v220, v224
	v_mfma_f32_16x16x16_bf16 v[66:69], v[104:105], v[122:123], v[212:215]
	v_fmac_f32_e32 v27, v233, v229
	v_fmac_f32_e32 v31, v221, v225
	v_fmac_f32_e32 v35, v234, v230
	v_fmac_f32_e32 v39, v222, v226
	v_mfma_f32_16x16x16_bf16 v[70:73], v[104:105], v[124:125], v[212:215]
	v_fmac_f32_e32 v43, v235, v231
	v_fmac_f32_e32 v47, v223, v227
	v_fma_f32 v224, v216, v224, v19
	v_fma_f32 v228, v216, v228, v23
	v_mfma_f32_16x16x16_bf16 v[74:77], v[104:105], v[126:127], v[212:215]
	v_fma_f32 v225, v217, v225, v27
	v_fma_f32 v229, v217, v229, v31
	v_fma_f32 v226, v218, v226, v35
	v_fma_f32 v230, v218, v230, v39
	v_mfma_f32_16x16x16_bf16 v[78:81], v[104:105], v[128:129], v[212:215]
	v_fma_f32 v227, v219, v227, v43
	v_fma_f32 v231, v219, v231, v47
	v_fmac_f32_e32 v20, v232, v228
	v_fmac_f32_e32 v24, v220, v224
	v_fmac_f32_e32 v28, v233, v229
	v_fmac_f32_e32 v32, v221, v225
	v_fmac_f32_e32 v36, v234, v230
	v_fmac_f32_e32 v40, v222, v226
	v_fmac_f32_e32 v44, v235, v231
	v_fmac_f32_e32 v48, v223, v227
	v_fma_f32 v224, v216, v224, v20
	v_fma_f32 v228, v216, v228, v24
	v_fma_f32 v225, v217, v225, v28
	v_fma_f32 v229, v217, v229, v32
	v_fma_f32 v226, v218, v226, v36
	v_fma_f32 v230, v218, v230, v40
	v_fma_f32 v227, v219, v227, v44
	v_fma_f32 v231, v219, v231, v48
	v_fmac_f32_e32 v21, v232, v228
	v_fmac_f32_e32 v25, v220, v224
	v_fmac_f32_e32 v29, v233, v229
	v_fmac_f32_e32 v33, v221, v225
	v_fmac_f32_e32 v37, v234, v230
	v_fmac_f32_e32 v41, v222, v226
	v_fmac_f32_e32 v45, v235, v231
	v_fmac_f32_e32 v49, v223, v227
	v_fma_f32 v224, v216, v224, v21
	v_fma_f32 v228, v216, v228, v25
	v_fma_f32 v225, v217, v225, v29
	v_fma_f32 v229, v217, v229, v33
	v_fma_f32 v226, v218, v226, v37
	v_fma_f32 v230, v218, v230, v41
	v_fma_f32 v227, v219, v227, v45
	v_fma_f32 v231, v219, v231, v49
	s_waitcnt vmcnt(8)
	v_fmac_f32_e32 v50, v232, v228
	v_fmac_f32_e32 v54, v220, v224
	v_mfma_f32_16x16x16_bf16 v[18:21], v[106:107], v[114:115], v[212:215]
	v_fmac_f32_e32 v58, v233, v229
	v_fmac_f32_e32 v62, v221, v225
	v_fmac_f32_e32 v66, v234, v230
	v_fmac_f32_e32 v70, v222, v226
	v_mfma_f32_16x16x16_bf16 v[22:25], v[106:107], v[116:117], v[212:215]
	v_fmac_f32_e32 v74, v235, v231
	v_fmac_f32_e32 v78, v223, v227
	v_fma_f32 v224, v216, v224, v50
	v_fma_f32 v228, v216, v228, v54
	v_mfma_f32_16x16x16_bf16 v[26:29], v[106:107], v[118:119], v[212:215]
	v_fma_f32 v225, v217, v225, v58
	v_fma_f32 v229, v217, v229, v62
	v_fma_f32 v226, v218, v226, v66
	v_fma_f32 v230, v218, v230, v70
	v_mfma_f32_16x16x16_bf16 v[30:33], v[106:107], v[120:121], v[212:215]
	v_fma_f32 v227, v219, v227, v74
	v_fma_f32 v231, v219, v231, v78
	v_fmac_f32_e32 v51, v232, v228
	v_fmac_f32_e32 v55, v220, v224
	v_mfma_f32_16x16x16_bf16 v[34:37], v[106:107], v[122:123], v[212:215]
	v_fmac_f32_e32 v59, v233, v229
	v_fmac_f32_e32 v63, v221, v225
	v_fmac_f32_e32 v67, v234, v230
	v_fmac_f32_e32 v71, v222, v226
	v_mfma_f32_16x16x16_bf16 v[38:41], v[106:107], v[124:125], v[212:215]
	v_fmac_f32_e32 v75, v235, v231
	v_fmac_f32_e32 v79, v223, v227
	v_fma_f32 v224, v216, v224, v51
	v_fma_f32 v228, v216, v228, v55
	v_mfma_f32_16x16x16_bf16 v[42:45], v[106:107], v[126:127], v[212:215]
	v_fma_f32 v225, v217, v225, v59
	v_fma_f32 v229, v217, v229, v63
	v_fma_f32 v226, v218, v226, v67
	v_fma_f32 v230, v218, v230, v71
	v_mfma_f32_16x16x16_bf16 v[46:49], v[106:107], v[128:129], v[212:215]
	v_fma_f32 v227, v219, v227, v75
	v_fma_f32 v231, v219, v231, v79
	v_fmac_f32_e32 v52, v232, v228
	v_fmac_f32_e32 v56, v220, v224
	v_fmac_f32_e32 v60, v233, v229
	v_fmac_f32_e32 v64, v221, v225
	v_fmac_f32_e32 v68, v234, v230
	v_fmac_f32_e32 v72, v222, v226
	v_fmac_f32_e32 v76, v235, v231
	v_fmac_f32_e32 v80, v223, v227
	v_fma_f32 v224, v216, v224, v52
	v_fma_f32 v228, v216, v228, v56
	v_fma_f32 v225, v217, v225, v60
	v_fma_f32 v229, v217, v229, v64
	v_fma_f32 v226, v218, v226, v68
	v_fma_f32 v230, v218, v230, v72
	v_fma_f32 v227, v219, v227, v76
	v_fma_f32 v231, v219, v231, v80
	v_fmac_f32_e32 v53, v232, v228
	v_fmac_f32_e32 v57, v220, v224
	v_fmac_f32_e32 v61, v233, v229
	v_fmac_f32_e32 v65, v221, v225
	v_fmac_f32_e32 v69, v234, v230
	v_fmac_f32_e32 v73, v222, v226
	v_fmac_f32_e32 v77, v235, v231
	v_fmac_f32_e32 v81, v223, v227
	v_fma_f32 v224, v216, v224, v53
	v_fma_f32 v228, v216, v228, v57
	v_fma_f32 v225, v217, v225, v61
	v_fma_f32 v229, v217, v229, v65
	v_fma_f32 v226, v218, v226, v69
	v_fma_f32 v230, v218, v230, v73
	v_fma_f32 v227, v219, v227, v77
	v_fma_f32 v231, v219, v231, v81
	global_load_dwordx2 v[98:99], v[130:131], off
	v_lshl_add_u64 v[130:131], v[130:131], 0, s[86:87]
	global_load_dwordx2 v[100:101], v[130:131], off
	v_lshl_add_u64 v[130:131], v[130:131], 0, s[86:87]
	global_load_dwordx2 v[102:103], v[130:131], off
	v_lshl_add_u64 v[130:131], v[130:131], 0, s[86:87]
	global_load_dwordx2 v[104:105], v[130:131], off
	v_lshl_add_u64 v[130:131], v[130:131], 0, s[86:87]
	v_fmac_f32_e32 v18, v232, v228
	v_fmac_f32_e32 v22, v220, v224
	v_mfma_f32_16x16x16_bf16 v[50:53], v[108:109], v[114:115], v[212:215]
	v_fmac_f32_e32 v26, v233, v229
	v_fmac_f32_e32 v30, v221, v225
	v_fmac_f32_e32 v34, v234, v230
	v_fmac_f32_e32 v38, v222, v226
	v_mfma_f32_16x16x16_bf16 v[54:57], v[108:109], v[116:117], v[212:215]
	v_fmac_f32_e32 v42, v235, v231
	v_fmac_f32_e32 v46, v223, v227
	v_fma_f32 v224, v216, v224, v18
	v_fma_f32 v228, v216, v228, v22
	v_mfma_f32_16x16x16_bf16 v[58:61], v[108:109], v[118:119], v[212:215]
	v_fma_f32 v225, v217, v225, v26
	v_fma_f32 v229, v217, v229, v30
	v_fma_f32 v226, v218, v226, v34
	v_fma_f32 v230, v218, v230, v38
	v_mfma_f32_16x16x16_bf16 v[62:65], v[108:109], v[120:121], v[212:215]
	v_fma_f32 v227, v219, v227, v42
	v_fma_f32 v231, v219, v231, v46
	v_fmac_f32_e32 v19, v232, v228
	v_fmac_f32_e32 v23, v220, v224
	v_mfma_f32_16x16x16_bf16 v[66:69], v[108:109], v[122:123], v[212:215]
	v_fmac_f32_e32 v27, v233, v229
	v_fmac_f32_e32 v31, v221, v225
	v_fmac_f32_e32 v35, v234, v230
	v_fmac_f32_e32 v39, v222, v226
	v_mfma_f32_16x16x16_bf16 v[70:73], v[108:109], v[124:125], v[212:215]
	v_fmac_f32_e32 v43, v235, v231
	v_fmac_f32_e32 v47, v223, v227
	v_fma_f32 v224, v216, v224, v19
	v_fma_f32 v228, v216, v228, v23
	v_mfma_f32_16x16x16_bf16 v[74:77], v[108:109], v[126:127], v[212:215]
	v_fma_f32 v225, v217, v225, v27
	v_fma_f32 v229, v217, v229, v31
	v_fma_f32 v226, v218, v226, v35
	v_fma_f32 v230, v218, v230, v39
	v_mfma_f32_16x16x16_bf16 v[78:81], v[108:109], v[128:129], v[212:215]
	v_fma_f32 v227, v219, v227, v43
	v_fma_f32 v231, v219, v231, v47
	v_fmac_f32_e32 v20, v232, v228
	v_fmac_f32_e32 v24, v220, v224
	v_fmac_f32_e32 v28, v233, v229
	v_fmac_f32_e32 v32, v221, v225
	v_fmac_f32_e32 v36, v234, v230
	v_fmac_f32_e32 v40, v222, v226
	v_fmac_f32_e32 v44, v235, v231
	v_fmac_f32_e32 v48, v223, v227
	v_fma_f32 v224, v216, v224, v20
	v_fma_f32 v228, v216, v228, v24
	v_fma_f32 v225, v217, v225, v28
	v_fma_f32 v229, v217, v229, v32
	v_fma_f32 v226, v218, v226, v36
	v_fma_f32 v230, v218, v230, v40
	v_fma_f32 v227, v219, v227, v44
	v_fma_f32 v231, v219, v231, v48
	v_fmac_f32_e32 v21, v232, v228
	v_fmac_f32_e32 v25, v220, v224
	v_fmac_f32_e32 v29, v233, v229
	v_fmac_f32_e32 v33, v221, v225
	v_fmac_f32_e32 v37, v234, v230
	v_fmac_f32_e32 v41, v222, v226
	v_fmac_f32_e32 v45, v235, v231
	v_fmac_f32_e32 v49, v223, v227
	v_fma_f32 v224, v216, v224, v21
	v_fma_f32 v228, v216, v228, v25
	v_fma_f32 v225, v217, v225, v29
	v_fma_f32 v229, v217, v229, v33
	v_fma_f32 v226, v218, v226, v37
	v_fma_f32 v230, v218, v230, v41
	v_fma_f32 v227, v219, v227, v45
	v_fma_f32 v231, v219, v231, v49
	v_fmac_f32_e32 v50, v232, v228
	v_fmac_f32_e32 v54, v220, v224
	v_mfma_f32_16x16x16_bf16 v[18:21], v[110:111], v[114:115], v[212:215]
	v_fmac_f32_e32 v58, v233, v229
	v_fmac_f32_e32 v62, v221, v225
	v_fmac_f32_e32 v66, v234, v230
	v_fmac_f32_e32 v70, v222, v226
	v_mfma_f32_16x16x16_bf16 v[22:25], v[110:111], v[116:117], v[212:215]
	v_fmac_f32_e32 v74, v235, v231
	v_fmac_f32_e32 v78, v223, v227
	v_fma_f32 v224, v216, v224, v50
	v_fma_f32 v228, v216, v228, v54
	v_mfma_f32_16x16x16_bf16 v[26:29], v[110:111], v[118:119], v[212:215]
	v_fma_f32 v225, v217, v225, v58
	v_fma_f32 v229, v217, v229, v62
	v_fma_f32 v226, v218, v226, v66
	v_fma_f32 v230, v218, v230, v70
	v_mfma_f32_16x16x16_bf16 v[30:33], v[110:111], v[120:121], v[212:215]
	v_fma_f32 v227, v219, v227, v74
	v_fma_f32 v231, v219, v231, v78
	v_fmac_f32_e32 v51, v232, v228
	v_fmac_f32_e32 v55, v220, v224
	v_mfma_f32_16x16x16_bf16 v[34:37], v[110:111], v[122:123], v[212:215]
	v_fmac_f32_e32 v59, v233, v229
	v_fmac_f32_e32 v63, v221, v225
	v_fmac_f32_e32 v67, v234, v230
	v_fmac_f32_e32 v71, v222, v226
	v_mfma_f32_16x16x16_bf16 v[38:41], v[110:111], v[124:125], v[212:215]
	v_fmac_f32_e32 v75, v235, v231
	v_fmac_f32_e32 v79, v223, v227
	v_fma_f32 v224, v216, v224, v51
	v_fma_f32 v228, v216, v228, v55
	v_mfma_f32_16x16x16_bf16 v[42:45], v[110:111], v[126:127], v[212:215]
	v_fma_f32 v225, v217, v225, v59
	v_fma_f32 v229, v217, v229, v63
	v_fma_f32 v226, v218, v226, v67
	v_fma_f32 v230, v218, v230, v71
	v_mfma_f32_16x16x16_bf16 v[46:49], v[110:111], v[128:129], v[212:215]
	v_fma_f32 v227, v219, v227, v75
	v_fma_f32 v231, v219, v231, v79
	v_fmac_f32_e32 v52, v232, v228
	v_fmac_f32_e32 v56, v220, v224
	v_fmac_f32_e32 v60, v233, v229
	v_fmac_f32_e32 v64, v221, v225
	v_fmac_f32_e32 v68, v234, v230
	v_fmac_f32_e32 v72, v222, v226
	v_fmac_f32_e32 v76, v235, v231
	v_fmac_f32_e32 v80, v223, v227
	v_fma_f32 v224, v216, v224, v52
	v_fma_f32 v228, v216, v228, v56
	v_fma_f32 v225, v217, v225, v60
	v_fma_f32 v229, v217, v229, v64
	v_fma_f32 v226, v218, v226, v68
	v_fma_f32 v230, v218, v230, v72
	v_fma_f32 v227, v219, v227, v76
	v_fma_f32 v231, v219, v231, v80
	v_fmac_f32_e32 v53, v232, v228
	v_fmac_f32_e32 v57, v220, v224
	v_fmac_f32_e32 v61, v233, v229
	v_fmac_f32_e32 v65, v221, v225
	v_fmac_f32_e32 v69, v234, v230
	v_fmac_f32_e32 v73, v222, v226
	v_fmac_f32_e32 v77, v235, v231
	v_fmac_f32_e32 v81, v223, v227
	v_fma_f32 v224, v216, v224, v53
	v_fma_f32 v228, v216, v228, v57
	v_fma_f32 v225, v217, v225, v61
	v_fma_f32 v229, v217, v229, v65
	v_fma_f32 v226, v218, v226, v69
	v_fma_f32 v230, v218, v230, v73
	v_fma_f32 v227, v219, v227, v77
	v_fma_f32 v231, v219, v231, v81
	v_fmac_f32_e32 v18, v232, v228
	v_fmac_f32_e32 v22, v220, v224
	v_mfma_f32_16x16x16_bf16 v[50:53], v[112:113], v[114:115], v[212:215]
	v_fmac_f32_e32 v26, v233, v229
	v_fmac_f32_e32 v30, v221, v225
	v_fmac_f32_e32 v34, v234, v230
	v_fmac_f32_e32 v38, v222, v226
	v_mfma_f32_16x16x16_bf16 v[54:57], v[112:113], v[116:117], v[212:215]
	v_fmac_f32_e32 v42, v235, v231
	v_fmac_f32_e32 v46, v223, v227
	v_fma_f32 v224, v216, v224, v18
	v_fma_f32 v228, v216, v228, v22
	v_mfma_f32_16x16x16_bf16 v[58:61], v[112:113], v[118:119], v[212:215]
	v_fma_f32 v225, v217, v225, v26
	v_fma_f32 v229, v217, v229, v30
	v_fma_f32 v226, v218, v226, v34
	v_fma_f32 v230, v218, v230, v38
	v_mfma_f32_16x16x16_bf16 v[62:65], v[112:113], v[120:121], v[212:215]
	v_fma_f32 v227, v219, v227, v42
	v_fma_f32 v231, v219, v231, v46
	v_fmac_f32_e32 v19, v232, v228
	v_fmac_f32_e32 v23, v220, v224
	v_mfma_f32_16x16x16_bf16 v[66:69], v[112:113], v[122:123], v[212:215]
	v_fmac_f32_e32 v27, v233, v229
	v_fmac_f32_e32 v31, v221, v225
	v_fmac_f32_e32 v35, v234, v230
	v_fmac_f32_e32 v39, v222, v226
	v_mfma_f32_16x16x16_bf16 v[70:73], v[112:113], v[124:125], v[212:215]
	v_fmac_f32_e32 v43, v235, v231
	v_fmac_f32_e32 v47, v223, v227
	v_fma_f32 v224, v216, v224, v19
	v_fma_f32 v228, v216, v228, v23
	v_mfma_f32_16x16x16_bf16 v[74:77], v[112:113], v[126:127], v[212:215]
	v_fma_f32 v225, v217, v225, v27
	v_fma_f32 v229, v217, v229, v31
	v_fma_f32 v226, v218, v226, v35
	v_fma_f32 v230, v218, v230, v39
	v_mfma_f32_16x16x16_bf16 v[78:81], v[112:113], v[128:129], v[212:215]
	v_fma_f32 v227, v219, v227, v43
	v_fma_f32 v231, v219, v231, v47
	v_fmac_f32_e32 v20, v232, v228
	v_fmac_f32_e32 v24, v220, v224
	v_fmac_f32_e32 v28, v233, v229
	v_fmac_f32_e32 v32, v221, v225
	v_fmac_f32_e32 v36, v234, v230
	v_fmac_f32_e32 v40, v222, v226
	v_fmac_f32_e32 v44, v235, v231
	v_fmac_f32_e32 v48, v223, v227
	v_fma_f32 v224, v216, v224, v20
	v_fma_f32 v228, v216, v228, v24
	v_fma_f32 v225, v217, v225, v28
	v_fma_f32 v229, v217, v229, v32
	v_fma_f32 v226, v218, v226, v36
	v_fma_f32 v230, v218, v230, v40
	v_fma_f32 v227, v219, v227, v44
	v_fma_f32 v231, v219, v231, v48
	v_fmac_f32_e32 v21, v232, v228
	v_fmac_f32_e32 v25, v220, v224
	v_fmac_f32_e32 v29, v233, v229
	v_fmac_f32_e32 v33, v221, v225
	v_fmac_f32_e32 v37, v234, v230
	v_fmac_f32_e32 v41, v222, v226
	v_fmac_f32_e32 v45, v235, v231
	v_fmac_f32_e32 v49, v223, v227
	v_fma_f32 v224, v216, v224, v21
	v_fma_f32 v228, v216, v228, v25
	v_fma_f32 v225, v217, v225, v29
	v_fma_f32 v229, v217, v229, v33
	v_fma_f32 v226, v218, v226, v37
	v_fma_f32 v230, v218, v230, v41
	v_fma_f32 v227, v219, v227, v45
	v_fma_f32 v231, v219, v231, v49
	s_waitcnt vmcnt(8)
	v_fmac_f32_e32 v50, v232, v228
	v_fmac_f32_e32 v54, v220, v224
	v_mfma_f32_16x16x16_bf16 v[18:21], v[82:83], v[114:115], v[212:215]
	v_fmac_f32_e32 v58, v233, v229
	v_fmac_f32_e32 v62, v221, v225
	v_fmac_f32_e32 v66, v234, v230
	v_fmac_f32_e32 v70, v222, v226
	v_mfma_f32_16x16x16_bf16 v[22:25], v[82:83], v[116:117], v[212:215]
	v_fmac_f32_e32 v74, v235, v231
	v_fmac_f32_e32 v78, v223, v227
	v_fma_f32 v224, v216, v224, v50
	v_fma_f32 v228, v216, v228, v54
	v_mfma_f32_16x16x16_bf16 v[26:29], v[82:83], v[118:119], v[212:215]
	v_fma_f32 v225, v217, v225, v58
	v_fma_f32 v229, v217, v229, v62
	v_fma_f32 v226, v218, v226, v66
	v_fma_f32 v230, v218, v230, v70
	v_mfma_f32_16x16x16_bf16 v[30:33], v[82:83], v[120:121], v[212:215]
	v_fma_f32 v227, v219, v227, v74
	v_fma_f32 v231, v219, v231, v78
	v_fmac_f32_e32 v51, v232, v228
	v_fmac_f32_e32 v55, v220, v224
	v_mfma_f32_16x16x16_bf16 v[34:37], v[82:83], v[122:123], v[212:215]
	v_fmac_f32_e32 v59, v233, v229
	v_fmac_f32_e32 v63, v221, v225
	v_fmac_f32_e32 v67, v234, v230
	v_fmac_f32_e32 v71, v222, v226
	v_mfma_f32_16x16x16_bf16 v[38:41], v[82:83], v[124:125], v[212:215]
	v_fmac_f32_e32 v75, v235, v231
	v_fmac_f32_e32 v79, v223, v227
	v_fma_f32 v224, v216, v224, v51
	v_fma_f32 v228, v216, v228, v55
	v_mfma_f32_16x16x16_bf16 v[42:45], v[82:83], v[126:127], v[212:215]
	v_fma_f32 v225, v217, v225, v59
	v_fma_f32 v229, v217, v229, v63
	v_fma_f32 v226, v218, v226, v67
	v_fma_f32 v230, v218, v230, v71
	v_mfma_f32_16x16x16_bf16 v[46:49], v[82:83], v[128:129], v[212:215]
	v_fma_f32 v227, v219, v227, v75
	v_fma_f32 v231, v219, v231, v79
	v_fmac_f32_e32 v52, v232, v228
	v_fmac_f32_e32 v56, v220, v224
	v_fmac_f32_e32 v60, v233, v229
	v_fmac_f32_e32 v64, v221, v225
	v_fmac_f32_e32 v68, v234, v230
	v_fmac_f32_e32 v72, v222, v226
	v_fmac_f32_e32 v76, v235, v231
	v_fmac_f32_e32 v80, v223, v227
	v_fma_f32 v224, v216, v224, v52
	v_fma_f32 v228, v216, v228, v56
	v_fma_f32 v225, v217, v225, v60
	v_fma_f32 v229, v217, v229, v64
	v_fma_f32 v226, v218, v226, v68
	v_fma_f32 v230, v218, v230, v72
	v_fma_f32 v227, v219, v227, v76
	v_fma_f32 v231, v219, v231, v80
	v_fmac_f32_e32 v53, v232, v228
	v_fmac_f32_e32 v57, v220, v224
	v_fmac_f32_e32 v61, v233, v229
	v_fmac_f32_e32 v65, v221, v225
	v_fmac_f32_e32 v69, v234, v230
	v_fmac_f32_e32 v73, v222, v226
	v_fmac_f32_e32 v77, v235, v231
	v_fmac_f32_e32 v81, v223, v227
	v_fma_f32 v224, v216, v224, v53
	v_fma_f32 v228, v216, v228, v57
	v_fma_f32 v225, v217, v225, v61
	v_fma_f32 v229, v217, v229, v65
	v_fma_f32 v226, v218, v226, v69
	v_fma_f32 v230, v218, v230, v73
	v_fma_f32 v227, v219, v227, v77
	v_fma_f32 v231, v219, v231, v81
	s_add_i32 s15, s15, 1
	s_cmp_lt_u32 s15, 4
	s_cbranch_scc1 .Lsc_local_loop
.Lsc_final:
	s_and_b64 s[82:83], s[84:85], exec
	s_cbranch_scc1 .Lsc_fin_lat
	s_load_dwordx2 s[82:83], s[58:59], 0xd0
	s_lshr_b32 s0, s18, 7
	s_lshl_b32 s0, s0, 16
	s_lshl_b32 s10, s39, 15
	s_add_i32 s0, s0, s10
	s_lshl_b32 s10, s1, 8
	s_add_i32 s0, s0, s10
	s_lshl_b32 s10, s3, 17
	s_add_i32 s0, s0, s10
	s_add_i32 s0, s0, 0x6000000
	v_lshlrev_b32_e32 v5, 17, v13
	v_lshl_add_u32 v5, v12, 2, v5
	v_add_u32_e32 v5, s0, v5
	v_add_u32_e32 v6, 0x4000, v5
	s_waitcnt lgkmcnt(0)
	global_store_dword v5, v224, s[82:83]
	global_store_dword v6, v228, s[82:83]
	global_store_dword v5, v225, s[82:83] offset:64
	global_store_dword v6, v229, s[82:83] offset:64
	global_store_dword v5, v226, s[82:83] offset:128
	global_store_dword v6, v230, s[82:83] offset:128
	global_store_dword v5, v227, s[82:83] offset:192
	global_store_dword v6, v231, s[82:83] offset:192
	s_branch .LBB0_235
.Lsc_fin_lat:
	s_and_b64 s[82:83], s[68:69], exec
	s_cbranch_scc0 .LBB0_235
	s_lshl_b32 s0, s39, 15
	s_lshl_b32 s10, s1, 9
	s_add_i32 s0, s0, s10
	s_mul_i32 s10, s3, 0x30000
	s_add_i32 s0, s0, s10
	s_lshl_b32 s10, s25, 16
	s_add_i32 s0, s0, s10
	v_mul_u32_u24_e32 v5, 0x30000, v13
	v_lshl_add_u32 v5, v12, 2, v5
	v_add_u32_e32 v5, s0, v5
	global_store_dword v5, v224, s[74:75]
	global_store_dword v5, v228, s[74:75] offset:256
	global_store_dword v5, v225, s[74:75] offset:64
	global_store_dword v5, v229, s[74:75] offset:320
	global_store_dword v5, v226, s[74:75] offset:128
	global_store_dword v5, v230, s[74:75] offset:384
	global_store_dword v5, v227, s[74:75] offset:192
	global_store_dword v5, v231, s[74:75] offset:448
	s_branch .LBB0_235

.LBB0_368:
	s_cmpk_gt_i32 s6, 0x2c83
	s_cselect_b64 s[0:1], -1, 0
	s_mov_b64 s[0:1], -1
	v_readlane_b32 s72, v247, 5
	v_readlane_b32 s68, v247, 7
	s_and_b64 vcc, exec, s[0:1]
	v_readlane_b32 s73, v247, 6
	v_readlane_b32 s69, v247, 8
	s_cbranch_vccnz .LBB0_387
	s_add_u32 s1, s56, 0x9c00000
	s_addc_u32 s3, s57, 0
	s_add_u32 s5, s56, 0x4400000
	s_addc_u32 s7, s57, 0
	s_add_u32 s9, s56, 0x3400000
	s_addc_u32 s15, s57, 0
	s_add_u32 s18, s56, 0x3000000
	v_lshrrev_b32_e32 v1, 5, v168
	v_and_b32_e32 v0, 31, v241
	s_addc_u32 s19, s57, 0
	v_lshlrev_b32_e32 v2, 2, v0
	v_mul_u32_u24_e32 v3, 0x84, v1
	s_add_u32 s25, s56, 0x1000000
	v_add3_u32 v3, s78, v2, v3
	v_lshlrev_b32_e32 v2, 3, v168
	s_addc_u32 s36, s57, 0
	v_lshrrev_b32_e32 v5, 3, v168
	v_and_b32_e32 v2, 56, v2
	s_lshl_b32 s0, s6, 5
	v_mul_u32_u24_e32 v6, 0x84, v2
	v_lshlrev_b32_e32 v7, 2, v5
	s_add_i32 s37, s0, 0x2af80
	s_lshl_b32 s0, s6, 1
	v_add3_u32 v10, s78, v6, v7
	v_or_b32_e32 v11, 8, v5
	v_or_b32_e32 v12, 16, v5
	v_or_b32_e32 v13, 24, v5
	s_lshl_b32 s38, s4, 5
	s_add_i32 s39, s6, 0x2f7c
	s_add_i32 s40, s0, 0x5ef8
	s_lshl_b32 s41, s4, 1
	s_branch .LBB0_371

.LBB0_422:
	s_branch .LBB0_441
	s_add_u32 s1, s56, 0x9c00000
	s_addc_u32 s3, s57, 0
	s_add_u32 s5, s56, 0x4400000
	s_addc_u32 s10, s57, 0
	s_add_u32 s11, s56, 0x3400000
	s_addc_u32 s12, s57, 0
	s_add_u32 s13, s56, 0x3000000
	v_lshrrev_b32_e32 v1, 5, v168
	v_and_b32_e32 v0, 31, v241
	s_addc_u32 s15, s57, 0
	v_lshlrev_b32_e32 v2, 2, v0
	v_mul_u32_u24_e32 v3, 0x84, v1
	s_add_u32 s18, s56, 0x1000000
	v_add3_u32 v3, s78, v2, v3
	v_lshlrev_b32_e32 v2, 3, v168
	s_addc_u32 s19, s57, 0
	v_lshrrev_b32_e32 v5, 3, v168
	v_and_b32_e32 v2, 56, v2
	s_lshl_b32 s0, s6, 5
	v_mul_u32_u24_e32 v6, 0x84, v2
	v_lshlrev_b32_e32 v7, 2, v5
	s_add_i32 s25, s0, 0x1f400
	s_lshl_b32 s0, s6, 1
	v_add3_u32 v10, s78, v6, v7
	v_or_b32_e32 v11, 8, v5
	v_or_b32_e32 v12, 16, v5
	v_or_b32_e32 v13, 24, v5
	s_lshl_b32 s36, s4, 5
	s_add_i32 s37, s6, 0x29a0
	s_add_i32 s38, s0, 0x5340
	s_lshl_b32 s39, s4, 1
	s_branch .LBB0_425
